# attention fast path: each softmax block split in two halves spread over the QK1 / PV0 / PV1 MFMA gaps (P low packed before PV starts, P high during its first half); no exposed pack block between MFMA
# speedup vs baseline: 1.0243x; 1.0243x over previous
.LBB0_847:
	s_cmp_gt_i32 s43, s84
	s_cbranch_scc1 .LBB0_858
	s_add_i32 s100, s43, 63
	s_cmp_le_i32 s100, s83
	s_cbranch_scc0 .Latt_slow_0
	s_lshl_b32 s98, s88, 14
	s_lshl_b32 s99, s88, 15
	s_add_i32 s99, s99, 0xc000
	v_add_u32_e32 v206, s98, v194
	ds_read_b128 v[206:209], v206
	v_add_u32_e32 v210, s98, v195
	ds_read_b128 v[210:213], v210
	v_add_u32_e32 v214, s98, v196
	ds_read_b128 v[214:217], v214
	v_add_u32_e32 v238, s98, v197
	ds_read_b128 v[238:241], v238
	v_add_u32_e32 v242, s98, v198
	ds_read_b128 v[242:245], v242
	v_add_u32_e32 v250, s98, v199
	ds_read_b128 v[250:253], v250
	v_add_u32_e32 v222, s98, v200
	ds_read_b128 v[222:225], v222
	v_add_u32_e32 v226, s98, v201
	ds_read_b128 v[226:229], v226
	v_bfe_u32 v246, v203, 2, 2
	v_bfe_u32 v247, v203, 5, 1
	v_lshl_or_b32 v247, v247, 2, v246
	v_and_b32_e32 v249, 3, v203
	v_and_b32_e32 v254, 16, v203
	v_lshl_or_b32 v249, v249, 2, v254
	v_lshlrev_b32_e32 v249, 1, v249
	v_lshl_add_u32 v247, v247, 9, v249
	v_add_u32_e32 v247, s99, v247
	v_lshlrev_b32_e32 v246, 6, v246
	v_add_u32_e32 v205, v247, v246
	v_xor_b32_e32 v249, 64, v246
	v_add_u32_e32 v218, v247, v249
	v_xor_b32_e32 v249, 0x80, v246
	v_add_u32_e32 v219, v247, v249
	v_xor_b32_e32 v249, 0xc0, v246
	v_add_u32_e32 v221, v247, v249
	s_waitcnt lgkmcnt(7)
	v_mfma_f32_32x32x16_bf16 v[128:143], v[206:209], v[144:147], 0
	v_add_u32_e32 v206, s98, v194
	ds_read_b128 v[206:209], v206 offset:8192
	s_waitcnt lgkmcnt(7)
	v_mfma_f32_32x32x16_bf16 v[128:143], v[210:213], v[148:151], v[128:143]
	v_add_u32_e32 v210, s98, v195
	ds_read_b128 v[210:213], v210 offset:8192
	s_waitcnt lgkmcnt(7)
	v_mfma_f32_32x32x16_bf16 v[128:143], v[214:217], v[152:155], v[128:143]
	v_add_u32_e32 v214, s98, v196
	ds_read_b128 v[214:217], v214 offset:8192
	s_waitcnt lgkmcnt(7)
	v_mfma_f32_32x32x16_bf16 v[128:143], v[238:241], v[156:159], v[128:143]
	v_add_u32_e32 v238, s98, v197
	ds_read_b128 v[238:241], v238 offset:8192
	s_waitcnt lgkmcnt(7)
	v_mfma_f32_32x32x16_bf16 v[128:143], v[242:245], v[160:163], v[128:143]
	s_waitcnt lgkmcnt(6)
	v_mfma_f32_32x32x16_bf16 v[128:143], v[250:253], v[164:167], v[128:143]
	s_waitcnt lgkmcnt(5)
	v_mfma_f32_32x32x16_bf16 v[128:143], v[222:225], v[168:171], v[128:143]
	s_waitcnt lgkmcnt(4)
	v_mfma_f32_32x32x16_bf16 v[128:143], v[226:229], v[172:175], v[128:143]
	s_waitcnt lgkmcnt(3)
	v_mfma_f32_32x32x16_bf16 v[222:237], v[206:209], v[144:147], 0
	v_add_u32_e32 v206, s98, v198
	ds_read_b128 v[206:209], v206 offset:8192
	s_nop 7
	v_max3_f32 v246, v128, v129, v130
	v_max3_f32 v247, v131, v132, v133
	v_max3_f32 v246, v246, v134, v135
	v_max3_f32 v247, v247, v136, v137
	v_max3_f32 v246, v246, v138, v139
	v_max3_f32 v247, v247, v140, v141
	v_max3_f32 v246, v246, v142, v143
	s_waitcnt lgkmcnt(3)
	v_mfma_f32_32x32x16_bf16 v[222:237], v[210:213], v[148:151], v[222:237]
	v_add_u32_e32 v210, s98, v199
	ds_read_b128 v[210:213], v210 offset:8192
	v_max_f32_e32 v246, v246, v247
	v_mov_b32_e32 v247, v246
	v_add_f32_e32 v249, 0x41000000, v190
	s_nop 1
	v_permlane32_swap_b32_e32 v246, v247
	v_max_f32_e32 v246, v246, v247
	v_cmp_gt_f32_e32 vcc, v246, v249
	s_cbranch_vccz .Latt_nr0_0
	v_max_f32_e32 v246, v190, v246
	v_sub_f32_e32 v190, v190, v246
	v_exp_f32_e32 v190, v190
	s_nop 0
	v_pk_mul_f32 v[126:127], v[126:127], v[190:191] op_sel_hi:[1,0]
	v_pk_mul_f32 v[124:125], v[124:125], v[190:191] op_sel_hi:[1,0]
	v_pk_mul_f32 v[122:123], v[122:123], v[190:191] op_sel_hi:[1,0]
	v_pk_mul_f32 v[120:121], v[120:121], v[190:191] op_sel_hi:[1,0]
	v_pk_mul_f32 v[118:119], v[118:119], v[190:191] op_sel_hi:[1,0]
	v_pk_mul_f32 v[116:117], v[116:117], v[190:191] op_sel_hi:[1,0]
	v_pk_mul_f32 v[114:115], v[114:115], v[190:191] op_sel_hi:[1,0]
	v_pk_mul_f32 v[112:113], v[112:113], v[190:191] op_sel_hi:[1,0]
	v_pk_mul_f32 v[110:111], v[110:111], v[190:191] op_sel_hi:[1,0]
	v_pk_mul_f32 v[108:109], v[108:109], v[190:191] op_sel_hi:[1,0]
	v_pk_mul_f32 v[106:107], v[106:107], v[190:191] op_sel_hi:[1,0]
	v_pk_mul_f32 v[104:105], v[104:105], v[190:191] op_sel_hi:[1,0]
	v_pk_mul_f32 v[102:103], v[102:103], v[190:191] op_sel_hi:[1,0]
	v_pk_mul_f32 v[100:101], v[100:101], v[190:191] op_sel_hi:[1,0]
	v_pk_mul_f32 v[98:99], v[98:99], v[190:191] op_sel_hi:[1,0]
	v_pk_mul_f32 v[96:97], v[96:97], v[190:191] op_sel_hi:[1,0]
	v_pk_mul_f32 v[94:95], v[94:95], v[190:191] op_sel_hi:[1,0]
	v_pk_mul_f32 v[92:93], v[92:93], v[190:191] op_sel_hi:[1,0]
	v_pk_mul_f32 v[90:91], v[90:91], v[190:191] op_sel_hi:[1,0]
	v_pk_mul_f32 v[88:89], v[88:89], v[190:191] op_sel_hi:[1,0]
	v_pk_mul_f32 v[86:87], v[86:87], v[190:191] op_sel_hi:[1,0]
	v_pk_mul_f32 v[84:85], v[84:85], v[190:191] op_sel_hi:[1,0]
	v_pk_mul_f32 v[82:83], v[82:83], v[190:191] op_sel_hi:[1,0]
	v_pk_mul_f32 v[80:81], v[80:81], v[190:191] op_sel_hi:[1,0]
	v_pk_mul_f32 v[78:79], v[78:79], v[190:191] op_sel_hi:[1,0]
	v_pk_mul_f32 v[76:77], v[76:77], v[190:191] op_sel_hi:[1,0]
	v_pk_mul_f32 v[74:75], v[74:75], v[190:191] op_sel_hi:[1,0]
	v_pk_mul_f32 v[72:73], v[72:73], v[190:191] op_sel_hi:[1,0]
	v_pk_mul_f32 v[70:71], v[70:71], v[190:191] op_sel_hi:[1,0]
	v_pk_mul_f32 v[68:69], v[68:69], v[190:191] op_sel_hi:[1,0]
	v_pk_mul_f32 v[66:67], v[66:67], v[190:191] op_sel_hi:[1,0]
	v_pk_mul_f32 v[64:65], v[64:65], v[190:191] op_sel_hi:[1,0]
	v_pk_mul_f32 v[62:63], v[62:63], v[190:191] op_sel_hi:[1,0]
	v_pk_mul_f32 v[60:61], v[60:61], v[190:191] op_sel_hi:[1,0]
	v_pk_mul_f32 v[58:59], v[58:59], v[190:191] op_sel_hi:[1,0]
	v_pk_mul_f32 v[56:57], v[56:57], v[190:191] op_sel_hi:[1,0]
	v_pk_mul_f32 v[54:55], v[54:55], v[190:191] op_sel_hi:[1,0]
	v_pk_mul_f32 v[52:53], v[52:53], v[190:191] op_sel_hi:[1,0]
	v_pk_mul_f32 v[50:51], v[50:51], v[190:191] op_sel_hi:[1,0]
	v_pk_mul_f32 v[48:49], v[48:49], v[190:191] op_sel_hi:[1,0]
	v_pk_mul_f32 v[46:47], v[46:47], v[190:191] op_sel_hi:[1,0]
	v_pk_mul_f32 v[44:45], v[44:45], v[190:191] op_sel_hi:[1,0]
	v_pk_mul_f32 v[42:43], v[42:43], v[190:191] op_sel_hi:[1,0]
	v_pk_mul_f32 v[40:41], v[40:41], v[190:191] op_sel_hi:[1,0]
	v_pk_mul_f32 v[38:39], v[38:39], v[190:191] op_sel_hi:[1,0]
	v_pk_mul_f32 v[36:37], v[36:37], v[190:191] op_sel_hi:[1,0]
	v_pk_mul_f32 v[34:35], v[34:35], v[190:191] op_sel_hi:[1,0]
	v_pk_mul_f32 v[32:33], v[32:33], v[190:191] op_sel_hi:[1,0]
	v_pk_mul_f32 v[30:31], v[30:31], v[190:191] op_sel_hi:[1,0]
	v_pk_mul_f32 v[28:29], v[28:29], v[190:191] op_sel_hi:[1,0]
	v_pk_mul_f32 v[26:27], v[26:27], v[190:191] op_sel_hi:[1,0]
	v_pk_mul_f32 v[24:25], v[24:25], v[190:191] op_sel_hi:[1,0]
	v_pk_mul_f32 v[22:23], v[22:23], v[190:191] op_sel_hi:[1,0]
	v_pk_mul_f32 v[20:21], v[20:21], v[190:191] op_sel_hi:[1,0]
	v_pk_mul_f32 v[18:19], v[18:19], v[190:191] op_sel_hi:[1,0]
	v_pk_mul_f32 v[16:17], v[16:17], v[190:191] op_sel_hi:[1,0]
	v_pk_mul_f32 v[14:15], v[14:15], v[190:191] op_sel_hi:[1,0]
	v_pk_mul_f32 v[12:13], v[12:13], v[190:191] op_sel_hi:[1,0]
	v_pk_mul_f32 v[10:11], v[10:11], v[190:191] op_sel_hi:[1,0]
	v_pk_mul_f32 v[8:9], v[8:9], v[190:191] op_sel_hi:[1,0]
	v_pk_mul_f32 v[6:7], v[6:7], v[190:191] op_sel_hi:[1,0]
	v_pk_mul_f32 v[4:5], v[4:5], v[190:191] op_sel_hi:[1,0]
	v_pk_mul_f32 v[2:3], v[2:3], v[190:191] op_sel_hi:[1,0]
	v_pk_mul_f32 v[0:1], v[0:1], v[190:191] op_sel_hi:[1,0]
	v_mul_f32_e32 v202, v202, v190
	v_mov_b32_e32 v190, v246
.Latt_nr0_0:
	s_waitcnt lgkmcnt(3)
	v_mfma_f32_32x32x16_bf16 v[222:237], v[214:217], v[152:155], v[222:237]
	v_add_u32_e32 v214, s98, v200
	ds_read_b128 v[214:217], v214 offset:8192
	v_sub_f32_e32 v128, v128, v190
	v_exp_f32_e32 v128, v128
	v_sub_f32_e32 v129, v129, v190
	v_exp_f32_e32 v129, v129
	v_sub_f32_e32 v130, v130, v190
	s_waitcnt lgkmcnt(3)
	v_mfma_f32_32x32x16_bf16 v[222:237], v[238:241], v[156:159], v[222:237]
	v_add_u32_e32 v238, s98, v201
	ds_read_b128 v[238:241], v238 offset:8192
	v_add_f32_e32 v254, 0, v128
	v_exp_f32_e32 v130, v130
	v_sub_f32_e32 v131, v131, v190
	v_add_f32_e32 v254, v129, v254
	v_exp_f32_e32 v131, v131
	s_waitcnt lgkmcnt(3)
	v_mfma_f32_32x32x16_bf16 v[222:237], v[206:209], v[160:163], v[222:237]
	ds_read_b64_tr_b16 v[206:207], v205
	ds_read_b64_tr_b16 v[208:209], v205 offset:4096
	v_sub_f32_e32 v132, v132, v190
	v_add_f32_e32 v254, v130, v254
	v_exp_f32_e32 v132, v132
	v_sub_f32_e32 v133, v133, v190
	v_add_f32_e32 v254, v131, v254
	s_waitcnt lgkmcnt(4)
	v_mfma_f32_32x32x16_bf16 v[222:237], v[210:213], v[164:167], v[222:237]
	ds_read_b64_tr_b16 v[210:211], v218
	ds_read_b64_tr_b16 v[212:213], v218 offset:4096
	v_exp_f32_e32 v133, v133
	v_sub_f32_e32 v134, v134, v190
	v_add_f32_e32 v254, v132, v254
	v_exp_f32_e32 v134, v134
	s_waitcnt lgkmcnt(5)
	v_mfma_f32_32x32x16_bf16 v[222:237], v[214:217], v[168:171], v[222:237]
	ds_read_b64_tr_b16 v[214:215], v219
	ds_read_b64_tr_b16 v[216:217], v219 offset:4096
	v_sub_f32_e32 v135, v135, v190
	v_add_f32_e32 v254, v133, v254
	v_exp_f32_e32 v135, v135
	s_nop 0
	s_waitcnt lgkmcnt(6)
	v_mfma_f32_32x32x16_bf16 v[222:237], v[238:241], v[172:175], v[222:237]
	ds_read_b64_tr_b16 v[238:239], v221
	ds_read_b64_tr_b16 v[240:241], v221 offset:4096
	v_cvt_pk_bf16_f32 v242, v128, v129
	v_cvt_pk_bf16_f32 v243, v130, v131
	v_cvt_pk_bf16_f32 v244, v132, v133
	v_cvt_pk_bf16_f32 v245, v134, v135
	s_nop 1
	s_waitcnt lgkmcnt(6)
	v_mfma_f32_32x32x16_bf16 v[112:127], v[206:209], v[242:245], v[112:127]
	ds_read_b64_tr_b16 v[206:207], v205 offset:256
	ds_read_b64_tr_b16 v[208:209], v205 offset:4352
	v_sub_f32_e32 v136, v136, v190
	v_add_f32_e32 v254, v134, v254
	v_exp_f32_e32 v136, v136
	v_sub_f32_e32 v137, v137, v190
	v_add_f32_e32 v254, v135, v254
	s_waitcnt lgkmcnt(6)
	v_mfma_f32_32x32x16_bf16 v[96:111], v[210:213], v[242:245], v[96:111]
	ds_read_b64_tr_b16 v[210:211], v218 offset:256
	ds_read_b64_tr_b16 v[212:213], v218 offset:4352
	v_exp_f32_e32 v137, v137
	v_sub_f32_e32 v138, v138, v190
	v_add_f32_e32 v254, v136, v254
	v_exp_f32_e32 v138, v138
	v_sub_f32_e32 v139, v139, v190
	s_waitcnt lgkmcnt(6)
	v_mfma_f32_32x32x16_bf16 v[80:95], v[214:217], v[242:245], v[80:95]
	ds_read_b64_tr_b16 v[214:215], v219 offset:256
	ds_read_b64_tr_b16 v[216:217], v219 offset:4352
	v_add_f32_e32 v254, v137, v254
	v_exp_f32_e32 v139, v139
	v_sub_f32_e32 v140, v140, v190
	v_add_f32_e32 v254, v138, v254
	s_waitcnt lgkmcnt(6)
	v_mfma_f32_32x32x16_bf16 v[64:79], v[238:241], v[242:245], v[64:79]
	ds_read_b64_tr_b16 v[238:239], v221 offset:256
	ds_read_b64_tr_b16 v[240:241], v221 offset:4352
	v_exp_f32_e32 v140, v140
	v_sub_f32_e32 v141, v141, v190
	v_add_f32_e32 v254, v139, v254
	v_exp_f32_e32 v141, v141
	s_waitcnt lgkmcnt(6)
	v_mfma_f32_32x32x16_bf16 v[48:63], v[206:209], v[242:245], v[48:63]
	ds_read_b64_tr_b16 v[206:207], v205 offset:8192
	ds_read_b64_tr_b16 v[208:209], v205 offset:12288
	v_sub_f32_e32 v142, v142, v190
	v_add_f32_e32 v254, v140, v254
	v_exp_f32_e32 v142, v142
	v_sub_f32_e32 v143, v143, v190
	s_waitcnt lgkmcnt(6)
	v_mfma_f32_32x32x16_bf16 v[32:47], v[210:213], v[242:245], v[32:47]
	ds_read_b64_tr_b16 v[210:211], v218 offset:8192
	ds_read_b64_tr_b16 v[212:213], v218 offset:12288
	v_add_f32_e32 v254, v141, v254
	v_exp_f32_e32 v143, v143
	v_add_f32_e32 v254, v142, v254
	v_add_f32_e32 v254, v143, v254
	s_waitcnt lgkmcnt(6)
	v_mfma_f32_32x32x16_bf16 v[16:31], v[214:217], v[242:245], v[16:31]
	ds_read_b64_tr_b16 v[214:215], v219 offset:8192
	ds_read_b64_tr_b16 v[216:217], v219 offset:12288
	v_cvt_pk_bf16_f32 v250, v136, v137
	v_cvt_pk_bf16_f32 v251, v138, v139
	v_cvt_pk_bf16_f32 v252, v140, v141
	v_cvt_pk_bf16_f32 v253, v142, v143
	v_add_f32_e32 v202, v202, v254
	s_waitcnt lgkmcnt(6)
	v_mfma_f32_32x32x16_bf16 v[0:15], v[238:241], v[242:245], v[0:15]
	ds_read_b64_tr_b16 v[238:239], v221 offset:8192
	ds_read_b64_tr_b16 v[240:241], v221 offset:12288
	ds_read_b64_tr_b16 v[128:129], v205 offset:8448
	ds_read_b64_tr_b16 v[130:131], v205 offset:12544
	s_waitcnt lgkmcnt(8)
	v_mfma_f32_32x32x16_bf16 v[112:127], v[206:209], v[250:253], v[112:127]
	ds_read_b64_tr_b16 v[206:207], v218 offset:8448
	ds_read_b64_tr_b16 v[208:209], v218 offset:12544
	v_max3_f32 v246, v222, v223, v224
	v_max3_f32 v247, v225, v226, v227
	v_max3_f32 v246, v246, v228, v229
	v_max3_f32 v247, v247, v230, v231
	v_max3_f32 v246, v246, v232, v233
	v_max3_f32 v247, v247, v234, v235
	s_waitcnt lgkmcnt(8)
	v_mfma_f32_32x32x16_bf16 v[96:111], v[210:213], v[250:253], v[96:111]
	ds_read_b64_tr_b16 v[210:211], v219 offset:8448
	ds_read_b64_tr_b16 v[212:213], v219 offset:12544
	v_max3_f32 v246, v246, v236, v237
	v_max_f32_e32 v246, v246, v247
	v_mov_b32_e32 v247, v246
	v_add_f32_e32 v249, 0x41000000, v190
	s_nop 1
	s_waitcnt lgkmcnt(8)
	v_mfma_f32_32x32x16_bf16 v[80:95], v[214:217], v[250:253], v[80:95]
	ds_read_b64_tr_b16 v[214:215], v221 offset:8448
	ds_read_b64_tr_b16 v[216:217], v221 offset:12544
	v_permlane32_swap_b32_e32 v246, v247
	v_max_f32_e32 v246, v246, v247
	v_cmp_gt_f32_e32 vcc, v246, v249
	s_cbranch_vccnz .Latt_rs1_0
	s_waitcnt lgkmcnt(8)
	v_mfma_f32_32x32x16_bf16 v[64:79], v[238:241], v[250:253], v[64:79]
	ds_read_b64_tr_b16 v[238:239], v205 offset:16384
	ds_read_b64_tr_b16 v[240:241], v205 offset:20480
	v_sub_f32_e32 v222, v222, v190
	v_exp_f32_e32 v222, v222
	v_sub_f32_e32 v223, v223, v190
	v_exp_f32_e32 v223, v223
	v_sub_f32_e32 v224, v224, v190
	v_add_f32_e32 v254, 0, v222
	s_waitcnt lgkmcnt(8)
	v_mfma_f32_32x32x16_bf16 v[48:63], v[128:131], v[250:253], v[48:63]
	ds_read_b64_tr_b16 v[128:129], v218 offset:16384
	ds_read_b64_tr_b16 v[130:131], v218 offset:20480
	v_exp_f32_e32 v224, v224
	v_sub_f32_e32 v225, v225, v190
	v_add_f32_e32 v254, v223, v254
	v_exp_f32_e32 v225, v225
	v_sub_f32_e32 v226, v226, v190
	v_add_f32_e32 v254, v224, v254
	s_waitcnt lgkmcnt(8)
	v_mfma_f32_32x32x16_bf16 v[32:47], v[206:209], v[250:253], v[32:47]
	ds_read_b64_tr_b16 v[206:207], v219 offset:16384
	ds_read_b64_tr_b16 v[208:209], v219 offset:20480
	v_exp_f32_e32 v226, v226
	v_sub_f32_e32 v227, v227, v190
	v_add_f32_e32 v254, v225, v254
	v_exp_f32_e32 v227, v227
	v_sub_f32_e32 v228, v228, v190
	s_waitcnt lgkmcnt(8)
	v_mfma_f32_32x32x16_bf16 v[16:31], v[210:213], v[250:253], v[16:31]
	ds_read_b64_tr_b16 v[210:211], v221 offset:16384
	ds_read_b64_tr_b16 v[212:213], v221 offset:20480
	v_add_f32_e32 v254, v226, v254
	v_exp_f32_e32 v228, v228
	v_sub_f32_e32 v229, v229, v190
	v_add_f32_e32 v254, v227, v254
	v_exp_f32_e32 v229, v229
	s_waitcnt lgkmcnt(8)
	v_mfma_f32_32x32x16_bf16 v[0:15], v[214:217], v[250:253], v[0:15]
	ds_read_b64_tr_b16 v[214:215], v205 offset:16640
	ds_read_b64_tr_b16 v[216:217], v205 offset:20736
	s_nop 0
	v_cvt_pk_bf16_f32 v242, v222, v223
	v_cvt_pk_bf16_f32 v243, v224, v225
	v_cvt_pk_bf16_f32 v244, v226, v227
	v_cvt_pk_bf16_f32 v245, v228, v229
	s_nop 1
	s_waitcnt lgkmcnt(8)
	v_mfma_f32_32x32x16_bf16 v[112:127], v[238:241], v[242:245], v[112:127]
	ds_read_b64_tr_b16 v[238:239], v218 offset:16640
	ds_read_b64_tr_b16 v[240:241], v218 offset:20736
	v_sub_f32_e32 v230, v230, v190
	v_add_f32_e32 v254, v228, v254
	v_exp_f32_e32 v230, v230
	v_sub_f32_e32 v231, v231, v190
	v_add_f32_e32 v254, v229, v254
	s_waitcnt lgkmcnt(8)
	v_mfma_f32_32x32x16_bf16 v[96:111], v[128:131], v[242:245], v[96:111]
	ds_read_b64_tr_b16 v[128:129], v219 offset:16640
	ds_read_b64_tr_b16 v[130:131], v219 offset:20736
	v_exp_f32_e32 v231, v231
	v_sub_f32_e32 v232, v232, v190
	v_add_f32_e32 v254, v230, v254
	v_exp_f32_e32 v232, v232
	v_sub_f32_e32 v233, v233, v190
	s_cmp_lg_u64 s[18:19], 0
	s_cbranch_scc1 .Latt_nd0_0
	s_sub_i32 s100, s88, 1
	s_cmp_eq_u32 s88, 0
	s_cselect_b32 s100, 2, s100
	s_lshl_b32 s101, s100, 14
	s_add_i32 m0, s85, s101
	s_nop 0
	global_load_lds_dwordx4 v178, s[14:15]
.Latt_nd0_0:
	s_waitcnt lgkmcnt(8)
	v_mfma_f32_32x32x16_bf16 v[80:95], v[206:209], v[242:245], v[80:95]
	ds_read_b64_tr_b16 v[206:207], v221 offset:16640
	ds_read_b64_tr_b16 v[208:209], v221 offset:20736
	v_add_f32_e32 v254, v231, v254
	v_exp_f32_e32 v233, v233
	v_sub_f32_e32 v234, v234, v190
	v_add_f32_e32 v254, v232, v254
	s_waitcnt lgkmcnt(8)
	v_mfma_f32_32x32x16_bf16 v[64:79], v[210:213], v[242:245], v[64:79]
	ds_read_b64_tr_b16 v[210:211], v205 offset:24576
	ds_read_b64_tr_b16 v[212:213], v205 offset:28672
	v_exp_f32_e32 v234, v234
	v_sub_f32_e32 v235, v235, v190
	v_add_f32_e32 v254, v233, v254
	v_exp_f32_e32 v235, v235
	s_cmp_lg_u64 s[18:19], 0
	s_cbranch_scc1 .Latt_nd1_0
	s_add_i32 m0, m0, 0x400
	s_nop 0
	global_load_lds_dwordx4 v180, s[14:15]
.Latt_nd1_0:
	s_waitcnt lgkmcnt(8)
	v_mfma_f32_32x32x16_bf16 v[48:63], v[214:217], v[242:245], v[48:63]
	ds_read_b64_tr_b16 v[214:215], v218 offset:24576
	ds_read_b64_tr_b16 v[216:217], v218 offset:28672
	v_sub_f32_e32 v236, v236, v190
	v_add_f32_e32 v254, v234, v254
	v_exp_f32_e32 v236, v236
	v_sub_f32_e32 v237, v237, v190
	s_waitcnt lgkmcnt(8)
	v_mfma_f32_32x32x16_bf16 v[32:47], v[238:241], v[242:245], v[32:47]
	ds_read_b64_tr_b16 v[238:239], v219 offset:24576
	ds_read_b64_tr_b16 v[240:241], v219 offset:28672
	v_add_f32_e32 v254, v235, v254
	v_exp_f32_e32 v237, v237
	v_add_f32_e32 v254, v236, v254
	v_add_f32_e32 v254, v237, v254
	s_cmp_lg_u64 s[18:19], 0
	s_cbranch_scc1 .Latt_nd2_0
	s_lshl_b32 s101, s100, 15
	s_add_i32 m0, s86, s101
	s_add_u32 s100, s14, 0x1000
	s_addc_u32 s101, s15, 0
	global_load_lds_dwordx4 v182, s[100:101]
.Latt_nd2_0:
	s_waitcnt lgkmcnt(8)
	v_mfma_f32_32x32x16_bf16 v[16:31], v[128:131], v[242:245], v[16:31]
	ds_read_b64_tr_b16 v[128:129], v221 offset:24576
	ds_read_b64_tr_b16 v[130:131], v221 offset:28672
	v_cvt_pk_bf16_f32 v250, v230, v231
	v_cvt_pk_bf16_f32 v251, v232, v233
	v_cvt_pk_bf16_f32 v252, v234, v235
	v_cvt_pk_bf16_f32 v253, v236, v237
	v_add_f32_e32 v202, v202, v254
	s_waitcnt lgkmcnt(8)
	v_mfma_f32_32x32x16_bf16 v[0:15], v[206:209], v[242:245], v[0:15]
	ds_read_b64_tr_b16 v[206:207], v205 offset:24832
	ds_read_b64_tr_b16 v[208:209], v205 offset:28928
	s_cmp_lg_u64 s[18:19], 0
	s_cbranch_scc1 .Latt_nd3_0
	s_add_i32 m0, m0, 0x400
	s_nop 0
	global_load_lds_dwordx4 v184, s[100:101]
.Latt_nd3_0:
	s_waitcnt lgkmcnt(8)
	v_mfma_f32_32x32x16_bf16 v[112:127], v[210:213], v[250:253], v[112:127]
	ds_read_b64_tr_b16 v[210:211], v218 offset:24832
	ds_read_b64_tr_b16 v[212:213], v218 offset:28928
	s_waitcnt lgkmcnt(8)
	v_mfma_f32_32x32x16_bf16 v[96:111], v[214:217], v[250:253], v[96:111]
	ds_read_b64_tr_b16 v[214:215], v219 offset:24832
	ds_read_b64_tr_b16 v[216:217], v219 offset:28928
	s_cmp_lg_u64 s[18:19], 0
	s_cbranch_scc1 .Latt_nd4_0
	s_add_i32 m0, m0, 0x400
	s_nop 0
	global_load_lds_dwordx4 v186, s[100:101]
.Latt_nd4_0:
	s_waitcnt lgkmcnt(8)
	v_mfma_f32_32x32x16_bf16 v[80:95], v[238:241], v[250:253], v[80:95]
	ds_read_b64_tr_b16 v[238:239], v221 offset:24832
	ds_read_b64_tr_b16 v[240:241], v221 offset:28928
	s_waitcnt lgkmcnt(8)
	v_mfma_f32_32x32x16_bf16 v[64:79], v[128:131], v[250:253], v[64:79]
	s_cmp_lg_u64 s[18:19], 0
	s_cbranch_scc1 .Latt_nd5_0
	s_add_i32 m0, m0, 0x400
	s_nop 0
	global_load_lds_dwordx4 v188, s[100:101]
.Latt_nd5_0:
	s_waitcnt lgkmcnt(6)
	v_mfma_f32_32x32x16_bf16 v[48:63], v[206:209], v[250:253], v[48:63]
	s_waitcnt lgkmcnt(4)
	v_mfma_f32_32x32x16_bf16 v[32:47], v[210:213], v[250:253], v[32:47]
	s_waitcnt lgkmcnt(2)
	v_mfma_f32_32x32x16_bf16 v[16:31], v[214:217], v[250:253], v[16:31]
	s_waitcnt lgkmcnt(0)
	v_mfma_f32_32x32x16_bf16 v[0:15], v[238:241], v[250:253], v[0:15]
	s_branch .LBB0_858
.Latt_rs1_0:
	s_waitcnt lgkmcnt(8)
	v_mfma_f32_32x32x16_bf16 v[64:79], v[238:241], v[250:253], v[64:79]
	ds_read_b64_tr_b16 v[238:239], v205 offset:16384
	ds_read_b64_tr_b16 v[240:241], v205 offset:20480
	s_waitcnt lgkmcnt(8)
	v_mfma_f32_32x32x16_bf16 v[48:63], v[128:131], v[250:253], v[48:63]
	ds_read_b64_tr_b16 v[128:129], v218 offset:16384
	ds_read_b64_tr_b16 v[130:131], v218 offset:20480
	s_waitcnt lgkmcnt(8)
	v_mfma_f32_32x32x16_bf16 v[32:47], v[206:209], v[250:253], v[32:47]
	ds_read_b64_tr_b16 v[206:207], v219 offset:16384
	ds_read_b64_tr_b16 v[208:209], v219 offset:20480
	s_waitcnt lgkmcnt(8)
	v_mfma_f32_32x32x16_bf16 v[16:31], v[210:213], v[250:253], v[16:31]
	ds_read_b64_tr_b16 v[210:211], v221 offset:16384
	ds_read_b64_tr_b16 v[212:213], v221 offset:20480
	s_waitcnt lgkmcnt(8)
	v_mfma_f32_32x32x16_bf16 v[0:15], v[214:217], v[250:253], v[0:15]
	ds_read_b64_tr_b16 v[214:215], v205 offset:16640
	ds_read_b64_tr_b16 v[216:217], v205 offset:20736
	s_nop 11
	v_max_f32_e32 v246, v190, v246
	v_sub_f32_e32 v190, v190, v246
	v_exp_f32_e32 v190, v190
	s_nop 0
	v_pk_mul_f32 v[126:127], v[126:127], v[190:191] op_sel_hi:[1,0]
	v_pk_mul_f32 v[124:125], v[124:125], v[190:191] op_sel_hi:[1,0]
	v_pk_mul_f32 v[122:123], v[122:123], v[190:191] op_sel_hi:[1,0]
	v_pk_mul_f32 v[120:121], v[120:121], v[190:191] op_sel_hi:[1,0]
	v_pk_mul_f32 v[118:119], v[118:119], v[190:191] op_sel_hi:[1,0]
	v_pk_mul_f32 v[116:117], v[116:117], v[190:191] op_sel_hi:[1,0]
	v_pk_mul_f32 v[114:115], v[114:115], v[190:191] op_sel_hi:[1,0]
	v_pk_mul_f32 v[112:113], v[112:113], v[190:191] op_sel_hi:[1,0]
	v_pk_mul_f32 v[110:111], v[110:111], v[190:191] op_sel_hi:[1,0]
	v_pk_mul_f32 v[108:109], v[108:109], v[190:191] op_sel_hi:[1,0]
	v_pk_mul_f32 v[106:107], v[106:107], v[190:191] op_sel_hi:[1,0]
	v_pk_mul_f32 v[104:105], v[104:105], v[190:191] op_sel_hi:[1,0]
	v_pk_mul_f32 v[102:103], v[102:103], v[190:191] op_sel_hi:[1,0]
	v_pk_mul_f32 v[100:101], v[100:101], v[190:191] op_sel_hi:[1,0]
	v_pk_mul_f32 v[98:99], v[98:99], v[190:191] op_sel_hi:[1,0]
	v_pk_mul_f32 v[96:97], v[96:97], v[190:191] op_sel_hi:[1,0]
	v_pk_mul_f32 v[94:95], v[94:95], v[190:191] op_sel_hi:[1,0]
	v_pk_mul_f32 v[92:93], v[92:93], v[190:191] op_sel_hi:[1,0]
	v_pk_mul_f32 v[90:91], v[90:91], v[190:191] op_sel_hi:[1,0]
	v_pk_mul_f32 v[88:89], v[88:89], v[190:191] op_sel_hi:[1,0]
	v_pk_mul_f32 v[86:87], v[86:87], v[190:191] op_sel_hi:[1,0]
	v_pk_mul_f32 v[84:85], v[84:85], v[190:191] op_sel_hi:[1,0]
	v_pk_mul_f32 v[82:83], v[82:83], v[190:191] op_sel_hi:[1,0]
	v_pk_mul_f32 v[80:81], v[80:81], v[190:191] op_sel_hi:[1,0]
	v_pk_mul_f32 v[78:79], v[78:79], v[190:191] op_sel_hi:[1,0]
	v_pk_mul_f32 v[76:77], v[76:77], v[190:191] op_sel_hi:[1,0]
	v_pk_mul_f32 v[74:75], v[74:75], v[190:191] op_sel_hi:[1,0]
	v_pk_mul_f32 v[72:73], v[72:73], v[190:191] op_sel_hi:[1,0]
	v_pk_mul_f32 v[70:71], v[70:71], v[190:191] op_sel_hi:[1,0]
	v_pk_mul_f32 v[68:69], v[68:69], v[190:191] op_sel_hi:[1,0]
	v_pk_mul_f32 v[66:67], v[66:67], v[190:191] op_sel_hi:[1,0]
	v_pk_mul_f32 v[64:65], v[64:65], v[190:191] op_sel_hi:[1,0]
	v_pk_mul_f32 v[62:63], v[62:63], v[190:191] op_sel_hi:[1,0]
	v_pk_mul_f32 v[60:61], v[60:61], v[190:191] op_sel_hi:[1,0]
	v_pk_mul_f32 v[58:59], v[58:59], v[190:191] op_sel_hi:[1,0]
	v_pk_mul_f32 v[56:57], v[56:57], v[190:191] op_sel_hi:[1,0]
	v_pk_mul_f32 v[54:55], v[54:55], v[190:191] op_sel_hi:[1,0]
	v_pk_mul_f32 v[52:53], v[52:53], v[190:191] op_sel_hi:[1,0]
	v_pk_mul_f32 v[50:51], v[50:51], v[190:191] op_sel_hi:[1,0]
	v_pk_mul_f32 v[48:49], v[48:49], v[190:191] op_sel_hi:[1,0]
	v_pk_mul_f32 v[46:47], v[46:47], v[190:191] op_sel_hi:[1,0]
	v_pk_mul_f32 v[44:45], v[44:45], v[190:191] op_sel_hi:[1,0]
	v_pk_mul_f32 v[42:43], v[42:43], v[190:191] op_sel_hi:[1,0]
	v_pk_mul_f32 v[40:41], v[40:41], v[190:191] op_sel_hi:[1,0]
	v_pk_mul_f32 v[38:39], v[38:39], v[190:191] op_sel_hi:[1,0]
	v_pk_mul_f32 v[36:37], v[36:37], v[190:191] op_sel_hi:[1,0]
	v_pk_mul_f32 v[34:35], v[34:35], v[190:191] op_sel_hi:[1,0]
	v_pk_mul_f32 v[32:33], v[32:33], v[190:191] op_sel_hi:[1,0]
	v_pk_mul_f32 v[30:31], v[30:31], v[190:191] op_sel_hi:[1,0]
	v_pk_mul_f32 v[28:29], v[28:29], v[190:191] op_sel_hi:[1,0]
	v_pk_mul_f32 v[26:27], v[26:27], v[190:191] op_sel_hi:[1,0]
	v_pk_mul_f32 v[24:25], v[24:25], v[190:191] op_sel_hi:[1,0]
	v_pk_mul_f32 v[22:23], v[22:23], v[190:191] op_sel_hi:[1,0]
	v_pk_mul_f32 v[20:21], v[20:21], v[190:191] op_sel_hi:[1,0]
	v_pk_mul_f32 v[18:19], v[18:19], v[190:191] op_sel_hi:[1,0]
	v_pk_mul_f32 v[16:17], v[16:17], v[190:191] op_sel_hi:[1,0]
	v_pk_mul_f32 v[14:15], v[14:15], v[190:191] op_sel_hi:[1,0]
	v_pk_mul_f32 v[12:13], v[12:13], v[190:191] op_sel_hi:[1,0]
	v_pk_mul_f32 v[10:11], v[10:11], v[190:191] op_sel_hi:[1,0]
	v_pk_mul_f32 v[8:9], v[8:9], v[190:191] op_sel_hi:[1,0]
	v_pk_mul_f32 v[6:7], v[6:7], v[190:191] op_sel_hi:[1,0]
	v_pk_mul_f32 v[4:5], v[4:5], v[190:191] op_sel_hi:[1,0]
	v_pk_mul_f32 v[2:3], v[2:3], v[190:191] op_sel_hi:[1,0]
	v_pk_mul_f32 v[0:1], v[0:1], v[190:191] op_sel_hi:[1,0]
	v_mul_f32_e32 v202, v202, v190
	v_mov_b32_e32 v190, v246
	v_sub_f32_e32 v222, v222, v190
	v_exp_f32_e32 v222, v222
	v_sub_f32_e32 v223, v223, v190
	v_exp_f32_e32 v223, v223
	v_sub_f32_e32 v224, v224, v190
	v_add_f32_e32 v254, 0, v222
	v_exp_f32_e32 v224, v224
	v_sub_f32_e32 v225, v225, v190
	v_add_f32_e32 v254, v223, v254
	v_exp_f32_e32 v225, v225
	v_sub_f32_e32 v226, v226, v190
	v_add_f32_e32 v254, v224, v254
	v_exp_f32_e32 v226, v226
	v_sub_f32_e32 v227, v227, v190
	v_add_f32_e32 v254, v225, v254
	v_exp_f32_e32 v227, v227
	v_sub_f32_e32 v228, v228, v190
	v_add_f32_e32 v254, v226, v254
	v_exp_f32_e32 v228, v228
	v_sub_f32_e32 v229, v229, v190
	v_add_f32_e32 v254, v227, v254
	v_exp_f32_e32 v229, v229
	v_sub_f32_e32 v230, v230, v190
	v_add_f32_e32 v254, v228, v254
	v_exp_f32_e32 v230, v230
	v_sub_f32_e32 v231, v231, v190
	v_add_f32_e32 v254, v229, v254
	v_exp_f32_e32 v231, v231
	v_sub_f32_e32 v232, v232, v190
	v_add_f32_e32 v254, v230, v254
	v_exp_f32_e32 v232, v232
	v_sub_f32_e32 v233, v233, v190
	v_add_f32_e32 v254, v231, v254
	v_exp_f32_e32 v233, v233
	v_sub_f32_e32 v234, v234, v190
	v_add_f32_e32 v254, v232, v254
	v_exp_f32_e32 v234, v234
	v_sub_f32_e32 v235, v235, v190
	v_add_f32_e32 v254, v233, v254
	v_exp_f32_e32 v235, v235
	v_sub_f32_e32 v236, v236, v190
	v_add_f32_e32 v254, v234, v254
	v_exp_f32_e32 v236, v236
	v_sub_f32_e32 v237, v237, v190
	v_add_f32_e32 v254, v235, v254
	v_exp_f32_e32 v237, v237
	v_add_f32_e32 v254, v236, v254
	v_add_f32_e32 v254, v237, v254
	v_cvt_pk_bf16_f32 v242, v222, v223
	v_cvt_pk_bf16_f32 v243, v224, v225
	v_cvt_pk_bf16_f32 v244, v226, v227
	v_cvt_pk_bf16_f32 v245, v228, v229
	v_cvt_pk_bf16_f32 v250, v230, v231
	v_cvt_pk_bf16_f32 v251, v232, v233
	v_cvt_pk_bf16_f32 v252, v234, v235
	v_cvt_pk_bf16_f32 v253, v236, v237
	v_add_f32_e32 v202, v202, v254
	s_nop 1
	s_waitcnt lgkmcnt(8)
	v_mfma_f32_32x32x16_bf16 v[112:127], v[238:241], v[242:245], v[112:127]
	ds_read_b64_tr_b16 v[238:239], v218 offset:16640
	ds_read_b64_tr_b16 v[240:241], v218 offset:20736
	s_waitcnt lgkmcnt(8)
	v_mfma_f32_32x32x16_bf16 v[96:111], v[128:131], v[242:245], v[96:111]
	ds_read_b64_tr_b16 v[222:223], v219 offset:16640
	ds_read_b64_tr_b16 v[224:225], v219 offset:20736
	s_cmp_lg_u64 s[18:19], 0
	s_cbranch_scc1 .Latt_ndr0_0
	s_sub_i32 s100, s88, 1
	s_cmp_eq_u32 s88, 0
	s_cselect_b32 s100, 2, s100
	s_lshl_b32 s101, s100, 14
	s_add_i32 m0, s85, s101
	s_nop 0
	global_load_lds_dwordx4 v178, s[14:15]
.Latt_ndr0_0:
	s_waitcnt lgkmcnt(8)
	v_mfma_f32_32x32x16_bf16 v[80:95], v[206:209], v[242:245], v[80:95]
	ds_read_b64_tr_b16 v[206:207], v221 offset:16640
	ds_read_b64_tr_b16 v[208:209], v221 offset:20736
	s_waitcnt lgkmcnt(8)
	v_mfma_f32_32x32x16_bf16 v[64:79], v[210:213], v[242:245], v[64:79]
	ds_read_b64_tr_b16 v[210:211], v205 offset:24576
	ds_read_b64_tr_b16 v[212:213], v205 offset:28672
	s_cmp_lg_u64 s[18:19], 0
	s_cbranch_scc1 .Latt_ndr1_0
	s_add_i32 m0, m0, 0x400
	s_nop 0
	global_load_lds_dwordx4 v180, s[14:15]

.Latt_ndr2_0:
	s_waitcnt lgkmcnt(8)
	v_mfma_f32_32x32x16_bf16 v[16:31], v[222:225], v[242:245], v[16:31]
	ds_read_b64_tr_b16 v[222:223], v221 offset:24576
	ds_read_b64_tr_b16 v[224:225], v221 offset:28672
	s_waitcnt lgkmcnt(8)
	v_mfma_f32_32x32x16_bf16 v[0:15], v[206:209], v[242:245], v[0:15]
	ds_read_b64_tr_b16 v[206:207], v205 offset:24832
	ds_read_b64_tr_b16 v[208:209], v205 offset:28928
	s_cmp_lg_u64 s[18:19], 0
	s_cbranch_scc1 .Latt_ndr3_0
	s_add_i32 m0, m0, 0x400
	s_nop 0
	global_load_lds_dwordx4 v184, s[100:101]

.Latt_ndr4_0:
	s_waitcnt lgkmcnt(8)
	v_mfma_f32_32x32x16_bf16 v[80:95], v[238:241], v[250:253], v[80:95]
	ds_read_b64_tr_b16 v[238:239], v221 offset:24832
	ds_read_b64_tr_b16 v[240:241], v221 offset:28928
	s_waitcnt lgkmcnt(8)
	v_mfma_f32_32x32x16_bf16 v[64:79], v[222:225], v[250:253], v[64:79]
	s_cmp_lg_u64 s[18:19], 0
	s_cbranch_scc1 .Latt_ndr5_0
	s_add_i32 m0, m0, 0x400
	s_nop 0
	global_load_lds_dwordx4 v188, s[100:101]

.LBB0_866:
	s_cmp_gt_i32 s4, s84
	s_cbranch_scc1 .LBB0_877
	s_add_i32 s100, s4, 63
	s_cmp_le_i32 s100, s83
	s_cbranch_scc0 .Latt_slow_1
	s_lshl_b32 s98, s33, 14
	s_lshl_b32 s99, s33, 15
	s_add_i32 s99, s99, 0xc000
	v_add_u32_e32 v206, s98, v196
	ds_read_b128 v[206:209], v206
	v_add_u32_e32 v210, s98, v197
	ds_read_b128 v[210:213], v210
	v_add_u32_e32 v214, s98, v198
	ds_read_b128 v[214:217], v214
	v_add_u32_e32 v238, s98, v199
	ds_read_b128 v[238:241], v238
	v_add_u32_e32 v242, s98, v200
	ds_read_b128 v[242:245], v242
	v_add_u32_e32 v250, s98, v201
	ds_read_b128 v[250:253], v250
	v_add_u32_e32 v222, s98, v202
	ds_read_b128 v[222:225], v222
	v_add_u32_e32 v226, s98, v203
	ds_read_b128 v[226:229], v226
	v_bfe_u32 v246, v204, 2, 2
	v_bfe_u32 v247, v204, 5, 1
	v_lshl_or_b32 v247, v247, 2, v246
	v_and_b32_e32 v249, 3, v204
	v_and_b32_e32 v254, 16, v204
	v_lshl_or_b32 v249, v249, 2, v254
	v_lshlrev_b32_e32 v249, 1, v249
	v_lshl_add_u32 v247, v247, 9, v249
	v_add_u32_e32 v247, s99, v247
	v_lshlrev_b32_e32 v246, 6, v246
	v_add_u32_e32 v205, v247, v246
	v_xor_b32_e32 v249, 64, v246
	v_add_u32_e32 v218, v247, v249
	v_xor_b32_e32 v249, 0x80, v246
	v_add_u32_e32 v219, v247, v249
	v_xor_b32_e32 v249, 0xc0, v246
	v_add_u32_e32 v221, v247, v249
	s_waitcnt lgkmcnt(7)
	v_mfma_f32_32x32x16_bf16 v[128:143], v[206:209], v[144:147], 0
	v_add_u32_e32 v206, s98, v196
	ds_read_b128 v[206:209], v206 offset:8192
	s_waitcnt lgkmcnt(7)
	v_mfma_f32_32x32x16_bf16 v[128:143], v[210:213], v[148:151], v[128:143]
	v_add_u32_e32 v210, s98, v197
	ds_read_b128 v[210:213], v210 offset:8192
	s_waitcnt lgkmcnt(7)
	v_mfma_f32_32x32x16_bf16 v[128:143], v[214:217], v[152:155], v[128:143]
	v_add_u32_e32 v214, s98, v198
	ds_read_b128 v[214:217], v214 offset:8192
	s_waitcnt lgkmcnt(7)
	v_mfma_f32_32x32x16_bf16 v[128:143], v[238:241], v[156:159], v[128:143]
	v_add_u32_e32 v238, s98, v199
	ds_read_b128 v[238:241], v238 offset:8192
	s_waitcnt lgkmcnt(7)
	v_mfma_f32_32x32x16_bf16 v[128:143], v[242:245], v[160:163], v[128:143]
	s_waitcnt lgkmcnt(6)
	v_mfma_f32_32x32x16_bf16 v[128:143], v[250:253], v[164:167], v[128:143]
	s_waitcnt lgkmcnt(5)
	v_mfma_f32_32x32x16_bf16 v[128:143], v[222:225], v[168:171], v[128:143]
	s_waitcnt lgkmcnt(4)
	v_mfma_f32_32x32x16_bf16 v[128:143], v[226:229], v[172:175], v[128:143]
	s_waitcnt lgkmcnt(3)
	v_mfma_f32_32x32x16_bf16 v[222:237], v[206:209], v[144:147], 0
	v_add_u32_e32 v206, s98, v200
	ds_read_b128 v[206:209], v206 offset:8192
	s_nop 7
	v_max3_f32 v246, v128, v129, v130
	v_max3_f32 v247, v131, v132, v133
	v_max3_f32 v246, v246, v134, v135
	v_max3_f32 v247, v247, v136, v137
	v_max3_f32 v246, v246, v138, v139
	v_max3_f32 v247, v247, v140, v141
	v_max3_f32 v246, v246, v142, v143
	s_waitcnt lgkmcnt(3)
	v_mfma_f32_32x32x16_bf16 v[222:237], v[210:213], v[148:151], v[222:237]
	v_add_u32_e32 v210, s98, v201
	ds_read_b128 v[210:213], v210 offset:8192
	v_max_f32_e32 v246, v246, v247
	v_mov_b32_e32 v247, v246
	v_add_f32_e32 v249, 0x41000000, v190
	s_nop 1
	v_permlane32_swap_b32_e32 v246, v247
	v_max_f32_e32 v246, v246, v247
	v_cmp_gt_f32_e32 vcc, v246, v249
	s_cbranch_vccz .Latt_nr0_1
	v_max_f32_e32 v246, v190, v246
	v_sub_f32_e32 v190, v190, v246
	v_exp_f32_e32 v190, v190
	s_nop 0
	v_pk_mul_f32 v[126:127], v[126:127], v[190:191] op_sel_hi:[1,0]
	v_pk_mul_f32 v[124:125], v[124:125], v[190:191] op_sel_hi:[1,0]
	v_pk_mul_f32 v[122:123], v[122:123], v[190:191] op_sel_hi:[1,0]
	v_pk_mul_f32 v[120:121], v[120:121], v[190:191] op_sel_hi:[1,0]
	v_pk_mul_f32 v[118:119], v[118:119], v[190:191] op_sel_hi:[1,0]
	v_pk_mul_f32 v[116:117], v[116:117], v[190:191] op_sel_hi:[1,0]
	v_pk_mul_f32 v[114:115], v[114:115], v[190:191] op_sel_hi:[1,0]
	v_pk_mul_f32 v[112:113], v[112:113], v[190:191] op_sel_hi:[1,0]
	v_pk_mul_f32 v[110:111], v[110:111], v[190:191] op_sel_hi:[1,0]
	v_pk_mul_f32 v[108:109], v[108:109], v[190:191] op_sel_hi:[1,0]
	v_pk_mul_f32 v[106:107], v[106:107], v[190:191] op_sel_hi:[1,0]
	v_pk_mul_f32 v[104:105], v[104:105], v[190:191] op_sel_hi:[1,0]
	v_pk_mul_f32 v[102:103], v[102:103], v[190:191] op_sel_hi:[1,0]
	v_pk_mul_f32 v[100:101], v[100:101], v[190:191] op_sel_hi:[1,0]
	v_pk_mul_f32 v[98:99], v[98:99], v[190:191] op_sel_hi:[1,0]
	v_pk_mul_f32 v[96:97], v[96:97], v[190:191] op_sel_hi:[1,0]
	v_pk_mul_f32 v[94:95], v[94:95], v[190:191] op_sel_hi:[1,0]
	v_pk_mul_f32 v[92:93], v[92:93], v[190:191] op_sel_hi:[1,0]
	v_pk_mul_f32 v[90:91], v[90:91], v[190:191] op_sel_hi:[1,0]
	v_pk_mul_f32 v[88:89], v[88:89], v[190:191] op_sel_hi:[1,0]
	v_pk_mul_f32 v[86:87], v[86:87], v[190:191] op_sel_hi:[1,0]
	v_pk_mul_f32 v[84:85], v[84:85], v[190:191] op_sel_hi:[1,0]
	v_pk_mul_f32 v[82:83], v[82:83], v[190:191] op_sel_hi:[1,0]
	v_pk_mul_f32 v[80:81], v[80:81], v[190:191] op_sel_hi:[1,0]
	v_pk_mul_f32 v[78:79], v[78:79], v[190:191] op_sel_hi:[1,0]
	v_pk_mul_f32 v[76:77], v[76:77], v[190:191] op_sel_hi:[1,0]
	v_pk_mul_f32 v[74:75], v[74:75], v[190:191] op_sel_hi:[1,0]
	v_pk_mul_f32 v[72:73], v[72:73], v[190:191] op_sel_hi:[1,0]
	v_pk_mul_f32 v[70:71], v[70:71], v[190:191] op_sel_hi:[1,0]
	v_pk_mul_f32 v[68:69], v[68:69], v[190:191] op_sel_hi:[1,0]
	v_pk_mul_f32 v[66:67], v[66:67], v[190:191] op_sel_hi:[1,0]
	v_pk_mul_f32 v[64:65], v[64:65], v[190:191] op_sel_hi:[1,0]
	v_pk_mul_f32 v[62:63], v[62:63], v[190:191] op_sel_hi:[1,0]
	v_pk_mul_f32 v[60:61], v[60:61], v[190:191] op_sel_hi:[1,0]
	v_pk_mul_f32 v[58:59], v[58:59], v[190:191] op_sel_hi:[1,0]
	v_pk_mul_f32 v[56:57], v[56:57], v[190:191] op_sel_hi:[1,0]
	v_pk_mul_f32 v[54:55], v[54:55], v[190:191] op_sel_hi:[1,0]
	v_pk_mul_f32 v[52:53], v[52:53], v[190:191] op_sel_hi:[1,0]
	v_pk_mul_f32 v[50:51], v[50:51], v[190:191] op_sel_hi:[1,0]
	v_pk_mul_f32 v[48:49], v[48:49], v[190:191] op_sel_hi:[1,0]
	v_pk_mul_f32 v[46:47], v[46:47], v[190:191] op_sel_hi:[1,0]
	v_pk_mul_f32 v[44:45], v[44:45], v[190:191] op_sel_hi:[1,0]
	v_pk_mul_f32 v[42:43], v[42:43], v[190:191] op_sel_hi:[1,0]
	v_pk_mul_f32 v[40:41], v[40:41], v[190:191] op_sel_hi:[1,0]
	v_pk_mul_f32 v[38:39], v[38:39], v[190:191] op_sel_hi:[1,0]
	v_pk_mul_f32 v[36:37], v[36:37], v[190:191] op_sel_hi:[1,0]
	v_pk_mul_f32 v[34:35], v[34:35], v[190:191] op_sel_hi:[1,0]
	v_pk_mul_f32 v[32:33], v[32:33], v[190:191] op_sel_hi:[1,0]
	v_pk_mul_f32 v[30:31], v[30:31], v[190:191] op_sel_hi:[1,0]
	v_pk_mul_f32 v[28:29], v[28:29], v[190:191] op_sel_hi:[1,0]
	v_pk_mul_f32 v[26:27], v[26:27], v[190:191] op_sel_hi:[1,0]
	v_pk_mul_f32 v[24:25], v[24:25], v[190:191] op_sel_hi:[1,0]
	v_pk_mul_f32 v[22:23], v[22:23], v[190:191] op_sel_hi:[1,0]
	v_pk_mul_f32 v[20:21], v[20:21], v[190:191] op_sel_hi:[1,0]
	v_pk_mul_f32 v[18:19], v[18:19], v[190:191] op_sel_hi:[1,0]
	v_pk_mul_f32 v[16:17], v[16:17], v[190:191] op_sel_hi:[1,0]
	v_pk_mul_f32 v[14:15], v[14:15], v[190:191] op_sel_hi:[1,0]
	v_pk_mul_f32 v[12:13], v[12:13], v[190:191] op_sel_hi:[1,0]
	v_pk_mul_f32 v[10:11], v[10:11], v[190:191] op_sel_hi:[1,0]
	v_pk_mul_f32 v[8:9], v[8:9], v[190:191] op_sel_hi:[1,0]
	v_pk_mul_f32 v[6:7], v[6:7], v[190:191] op_sel_hi:[1,0]
	v_pk_mul_f32 v[4:5], v[4:5], v[190:191] op_sel_hi:[1,0]
	v_pk_mul_f32 v[2:3], v[2:3], v[190:191] op_sel_hi:[1,0]
	v_pk_mul_f32 v[0:1], v[0:1], v[190:191] op_sel_hi:[1,0]
	v_mul_f32_e32 v195, v195, v190
	v_mov_b32_e32 v190, v246
.Latt_nr0_1:
	s_waitcnt lgkmcnt(3)
	v_mfma_f32_32x32x16_bf16 v[222:237], v[214:217], v[152:155], v[222:237]
	v_add_u32_e32 v214, s98, v202
	ds_read_b128 v[214:217], v214 offset:8192
	v_sub_f32_e32 v128, v128, v190
	v_exp_f32_e32 v128, v128
	v_sub_f32_e32 v129, v129, v190
	v_exp_f32_e32 v129, v129
	v_sub_f32_e32 v130, v130, v190
	s_waitcnt lgkmcnt(3)
	v_mfma_f32_32x32x16_bf16 v[222:237], v[238:241], v[156:159], v[222:237]
	v_add_u32_e32 v238, s98, v203
	ds_read_b128 v[238:241], v238 offset:8192
	v_add_f32_e32 v254, 0, v128
	v_exp_f32_e32 v130, v130
	v_sub_f32_e32 v131, v131, v190
	v_add_f32_e32 v254, v129, v254
	v_exp_f32_e32 v131, v131
	s_waitcnt lgkmcnt(3)
	v_mfma_f32_32x32x16_bf16 v[222:237], v[206:209], v[160:163], v[222:237]
	ds_read_b64_tr_b16 v[206:207], v205
	ds_read_b64_tr_b16 v[208:209], v205 offset:4096
	v_sub_f32_e32 v132, v132, v190
	v_add_f32_e32 v254, v130, v254
	v_exp_f32_e32 v132, v132
	v_sub_f32_e32 v133, v133, v190
	v_add_f32_e32 v254, v131, v254
	s_waitcnt lgkmcnt(4)
	v_mfma_f32_32x32x16_bf16 v[222:237], v[210:213], v[164:167], v[222:237]
	ds_read_b64_tr_b16 v[210:211], v218
	ds_read_b64_tr_b16 v[212:213], v218 offset:4096
	v_exp_f32_e32 v133, v133
	v_sub_f32_e32 v134, v134, v190
	v_add_f32_e32 v254, v132, v254
	v_exp_f32_e32 v134, v134
	s_waitcnt lgkmcnt(5)
	v_mfma_f32_32x32x16_bf16 v[222:237], v[214:217], v[168:171], v[222:237]
	ds_read_b64_tr_b16 v[214:215], v219
	ds_read_b64_tr_b16 v[216:217], v219 offset:4096
	v_sub_f32_e32 v135, v135, v190
	v_add_f32_e32 v254, v133, v254
	v_exp_f32_e32 v135, v135
	s_nop 0
	s_waitcnt lgkmcnt(6)
	v_mfma_f32_32x32x16_bf16 v[222:237], v[238:241], v[172:175], v[222:237]
	ds_read_b64_tr_b16 v[238:239], v221
	ds_read_b64_tr_b16 v[240:241], v221 offset:4096
	v_cvt_pk_bf16_f32 v242, v128, v129
	v_cvt_pk_bf16_f32 v243, v130, v131
	v_cvt_pk_bf16_f32 v244, v132, v133
	v_cvt_pk_bf16_f32 v245, v134, v135
	s_nop 1
	s_waitcnt lgkmcnt(6)
	v_mfma_f32_32x32x16_bf16 v[112:127], v[206:209], v[242:245], v[112:127]
	ds_read_b64_tr_b16 v[206:207], v205 offset:256
	ds_read_b64_tr_b16 v[208:209], v205 offset:4352
	v_sub_f32_e32 v136, v136, v190
	v_add_f32_e32 v254, v134, v254
	v_exp_f32_e32 v136, v136
	v_sub_f32_e32 v137, v137, v190
	v_add_f32_e32 v254, v135, v254
	s_waitcnt lgkmcnt(6)
	v_mfma_f32_32x32x16_bf16 v[96:111], v[210:213], v[242:245], v[96:111]
	ds_read_b64_tr_b16 v[210:211], v218 offset:256
	ds_read_b64_tr_b16 v[212:213], v218 offset:4352
	v_exp_f32_e32 v137, v137
	v_sub_f32_e32 v138, v138, v190
	v_add_f32_e32 v254, v136, v254
	v_exp_f32_e32 v138, v138
	v_sub_f32_e32 v139, v139, v190
	s_waitcnt lgkmcnt(6)
	v_mfma_f32_32x32x16_bf16 v[80:95], v[214:217], v[242:245], v[80:95]
	ds_read_b64_tr_b16 v[214:215], v219 offset:256
	ds_read_b64_tr_b16 v[216:217], v219 offset:4352
	v_add_f32_e32 v254, v137, v254
	v_exp_f32_e32 v139, v139
	v_sub_f32_e32 v140, v140, v190
	v_add_f32_e32 v254, v138, v254
	s_waitcnt lgkmcnt(6)
	v_mfma_f32_32x32x16_bf16 v[64:79], v[238:241], v[242:245], v[64:79]
	ds_read_b64_tr_b16 v[238:239], v221 offset:256
	ds_read_b64_tr_b16 v[240:241], v221 offset:4352
	v_exp_f32_e32 v140, v140
	v_sub_f32_e32 v141, v141, v190
	v_add_f32_e32 v254, v139, v254
	v_exp_f32_e32 v141, v141
	s_waitcnt lgkmcnt(6)
	v_mfma_f32_32x32x16_bf16 v[48:63], v[206:209], v[242:245], v[48:63]
	ds_read_b64_tr_b16 v[206:207], v205 offset:8192
	ds_read_b64_tr_b16 v[208:209], v205 offset:12288
	v_sub_f32_e32 v142, v142, v190
	v_add_f32_e32 v254, v140, v254
	v_exp_f32_e32 v142, v142
	v_sub_f32_e32 v143, v143, v190
	s_waitcnt lgkmcnt(6)
	v_mfma_f32_32x32x16_bf16 v[32:47], v[210:213], v[242:245], v[32:47]
	ds_read_b64_tr_b16 v[210:211], v218 offset:8192
	ds_read_b64_tr_b16 v[212:213], v218 offset:12288
	v_add_f32_e32 v254, v141, v254
	v_exp_f32_e32 v143, v143
	v_add_f32_e32 v254, v142, v254
	v_add_f32_e32 v254, v143, v254
	s_waitcnt lgkmcnt(6)
	v_mfma_f32_32x32x16_bf16 v[16:31], v[214:217], v[242:245], v[16:31]
	ds_read_b64_tr_b16 v[214:215], v219 offset:8192
	ds_read_b64_tr_b16 v[216:217], v219 offset:12288
	v_cvt_pk_bf16_f32 v250, v136, v137
	v_cvt_pk_bf16_f32 v251, v138, v139
	v_cvt_pk_bf16_f32 v252, v140, v141
	v_cvt_pk_bf16_f32 v253, v142, v143
	v_add_f32_e32 v195, v195, v254
	s_waitcnt lgkmcnt(6)
	v_mfma_f32_32x32x16_bf16 v[0:15], v[238:241], v[242:245], v[0:15]
	ds_read_b64_tr_b16 v[238:239], v221 offset:8192
	ds_read_b64_tr_b16 v[240:241], v221 offset:12288
	ds_read_b64_tr_b16 v[128:129], v205 offset:8448
	ds_read_b64_tr_b16 v[130:131], v205 offset:12544
	s_waitcnt lgkmcnt(8)
	v_mfma_f32_32x32x16_bf16 v[112:127], v[206:209], v[250:253], v[112:127]
	ds_read_b64_tr_b16 v[206:207], v218 offset:8448
	ds_read_b64_tr_b16 v[208:209], v218 offset:12544
	v_max3_f32 v246, v222, v223, v224
	v_max3_f32 v247, v225, v226, v227
	v_max3_f32 v246, v246, v228, v229
	v_max3_f32 v247, v247, v230, v231
	v_max3_f32 v246, v246, v232, v233
	v_max3_f32 v247, v247, v234, v235
	s_waitcnt lgkmcnt(8)
	v_mfma_f32_32x32x16_bf16 v[96:111], v[210:213], v[250:253], v[96:111]
	ds_read_b64_tr_b16 v[210:211], v219 offset:8448
	ds_read_b64_tr_b16 v[212:213], v219 offset:12544
	v_max3_f32 v246, v246, v236, v237
	v_max_f32_e32 v246, v246, v247
	v_mov_b32_e32 v247, v246
	v_add_f32_e32 v249, 0x41000000, v190
	s_nop 1
	s_waitcnt lgkmcnt(8)
	v_mfma_f32_32x32x16_bf16 v[80:95], v[214:217], v[250:253], v[80:95]
	ds_read_b64_tr_b16 v[214:215], v221 offset:8448
	ds_read_b64_tr_b16 v[216:217], v221 offset:12544
	v_permlane32_swap_b32_e32 v246, v247
	v_max_f32_e32 v246, v246, v247
	v_cmp_gt_f32_e32 vcc, v246, v249
	s_cbranch_vccnz .Latt_rs1_1
	s_waitcnt lgkmcnt(8)
	v_mfma_f32_32x32x16_bf16 v[64:79], v[238:241], v[250:253], v[64:79]
	ds_read_b64_tr_b16 v[238:239], v205 offset:16384
	ds_read_b64_tr_b16 v[240:241], v205 offset:20480
	v_sub_f32_e32 v222, v222, v190
	v_exp_f32_e32 v222, v222
	v_sub_f32_e32 v223, v223, v190
	v_exp_f32_e32 v223, v223
	v_sub_f32_e32 v224, v224, v190
	v_add_f32_e32 v254, 0, v222
	s_waitcnt lgkmcnt(8)
	v_mfma_f32_32x32x16_bf16 v[48:63], v[128:131], v[250:253], v[48:63]
	ds_read_b64_tr_b16 v[128:129], v218 offset:16384
	ds_read_b64_tr_b16 v[130:131], v218 offset:20480
	v_exp_f32_e32 v224, v224
	v_sub_f32_e32 v225, v225, v190
	v_add_f32_e32 v254, v223, v254
	v_exp_f32_e32 v225, v225
	v_sub_f32_e32 v226, v226, v190
	v_add_f32_e32 v254, v224, v254
	s_waitcnt lgkmcnt(8)
	v_mfma_f32_32x32x16_bf16 v[32:47], v[206:209], v[250:253], v[32:47]
	ds_read_b64_tr_b16 v[206:207], v219 offset:16384
	ds_read_b64_tr_b16 v[208:209], v219 offset:20480
	v_exp_f32_e32 v226, v226
	v_sub_f32_e32 v227, v227, v190
	v_add_f32_e32 v254, v225, v254
	v_exp_f32_e32 v227, v227
	v_sub_f32_e32 v228, v228, v190
	s_waitcnt lgkmcnt(8)
	v_mfma_f32_32x32x16_bf16 v[16:31], v[210:213], v[250:253], v[16:31]
	ds_read_b64_tr_b16 v[210:211], v221 offset:16384
	ds_read_b64_tr_b16 v[212:213], v221 offset:20480
	v_add_f32_e32 v254, v226, v254
	v_exp_f32_e32 v228, v228
	v_sub_f32_e32 v229, v229, v190
	v_add_f32_e32 v254, v227, v254
	v_exp_f32_e32 v229, v229
	s_waitcnt lgkmcnt(8)
	v_mfma_f32_32x32x16_bf16 v[0:15], v[214:217], v[250:253], v[0:15]
	ds_read_b64_tr_b16 v[214:215], v205 offset:16640
	ds_read_b64_tr_b16 v[216:217], v205 offset:20736
	s_nop 0
	v_cvt_pk_bf16_f32 v242, v222, v223
	v_cvt_pk_bf16_f32 v243, v224, v225
	v_cvt_pk_bf16_f32 v244, v226, v227
	v_cvt_pk_bf16_f32 v245, v228, v229
	s_nop 1
	s_waitcnt lgkmcnt(8)
	v_mfma_f32_32x32x16_bf16 v[112:127], v[238:241], v[242:245], v[112:127]
	ds_read_b64_tr_b16 v[238:239], v218 offset:16640
	ds_read_b64_tr_b16 v[240:241], v218 offset:20736
	v_sub_f32_e32 v230, v230, v190
	v_add_f32_e32 v254, v228, v254
	v_exp_f32_e32 v230, v230
	v_sub_f32_e32 v231, v231, v190
	v_add_f32_e32 v254, v229, v254
	s_waitcnt lgkmcnt(8)
	v_mfma_f32_32x32x16_bf16 v[96:111], v[128:131], v[242:245], v[96:111]
	ds_read_b64_tr_b16 v[128:129], v219 offset:16640
	ds_read_b64_tr_b16 v[130:131], v219 offset:20736
	v_exp_f32_e32 v231, v231
	v_sub_f32_e32 v232, v232, v190
	v_add_f32_e32 v254, v230, v254
	v_exp_f32_e32 v232, v232
	v_sub_f32_e32 v233, v233, v190
	s_cmp_lg_u64 s[18:19], 0
	s_cbranch_scc1 .Latt_nd0_1
	s_sub_i32 s100, s33, 1
	s_cmp_eq_u32 s33, 0
	s_cselect_b32 s100, 2, s100
	s_lshl_b32 s101, s100, 14
	s_add_i32 m0, s85, s101
	s_nop 0
	global_load_lds_dwordx4 v178, s[12:13]
.Latt_nd0_1:
	s_waitcnt lgkmcnt(8)
	v_mfma_f32_32x32x16_bf16 v[80:95], v[206:209], v[242:245], v[80:95]
	ds_read_b64_tr_b16 v[206:207], v221 offset:16640
	ds_read_b64_tr_b16 v[208:209], v221 offset:20736
	v_add_f32_e32 v254, v231, v254
	v_exp_f32_e32 v233, v233
	v_sub_f32_e32 v234, v234, v190
	v_add_f32_e32 v254, v232, v254
	s_waitcnt lgkmcnt(8)
	v_mfma_f32_32x32x16_bf16 v[64:79], v[210:213], v[242:245], v[64:79]
	ds_read_b64_tr_b16 v[210:211], v205 offset:24576
	ds_read_b64_tr_b16 v[212:213], v205 offset:28672
	v_exp_f32_e32 v234, v234
	v_sub_f32_e32 v235, v235, v190
	v_add_f32_e32 v254, v233, v254
	v_exp_f32_e32 v235, v235
	s_cmp_lg_u64 s[18:19], 0
	s_cbranch_scc1 .Latt_nd1_1
	s_add_i32 m0, m0, 0x400
	s_nop 0
	global_load_lds_dwordx4 v180, s[12:13]
.Latt_nd1_1:
	s_waitcnt lgkmcnt(8)
	v_mfma_f32_32x32x16_bf16 v[48:63], v[214:217], v[242:245], v[48:63]
	ds_read_b64_tr_b16 v[214:215], v218 offset:24576
	ds_read_b64_tr_b16 v[216:217], v218 offset:28672
	v_sub_f32_e32 v236, v236, v190
	v_add_f32_e32 v254, v234, v254
	v_exp_f32_e32 v236, v236
	v_sub_f32_e32 v237, v237, v190
	s_waitcnt lgkmcnt(8)
	v_mfma_f32_32x32x16_bf16 v[32:47], v[238:241], v[242:245], v[32:47]
	ds_read_b64_tr_b16 v[238:239], v219 offset:24576
	ds_read_b64_tr_b16 v[240:241], v219 offset:28672
	v_add_f32_e32 v254, v235, v254
	v_exp_f32_e32 v237, v237
	v_add_f32_e32 v254, v236, v254
	v_add_f32_e32 v254, v237, v254
	s_cmp_lg_u64 s[18:19], 0
	s_cbranch_scc1 .Latt_nd2_1
	s_lshl_b32 s101, s100, 15
	s_add_i32 m0, s86, s101
	s_add_u32 s100, s12, 0xf00
	s_addc_u32 s101, s13, 0
	global_load_lds_dwordx4 v182, s[100:101]
.Latt_nd2_1:
	s_waitcnt lgkmcnt(8)
	v_mfma_f32_32x32x16_bf16 v[16:31], v[128:131], v[242:245], v[16:31]
	ds_read_b64_tr_b16 v[128:129], v221 offset:24576
	ds_read_b64_tr_b16 v[130:131], v221 offset:28672
	v_cvt_pk_bf16_f32 v250, v230, v231
	v_cvt_pk_bf16_f32 v251, v232, v233
	v_cvt_pk_bf16_f32 v252, v234, v235
	v_cvt_pk_bf16_f32 v253, v236, v237
	v_add_f32_e32 v195, v195, v254
	s_waitcnt lgkmcnt(8)
	v_mfma_f32_32x32x16_bf16 v[0:15], v[206:209], v[242:245], v[0:15]
	ds_read_b64_tr_b16 v[206:207], v205 offset:24832
	ds_read_b64_tr_b16 v[208:209], v205 offset:28928
	s_cmp_lg_u64 s[18:19], 0
	s_cbranch_scc1 .Latt_nd3_1
	s_add_i32 m0, m0, 0x400
	s_nop 0
	global_load_lds_dwordx4 v184, s[100:101]

.Latt_rs1_1:
	s_waitcnt lgkmcnt(8)
	v_mfma_f32_32x32x16_bf16 v[64:79], v[238:241], v[250:253], v[64:79]
	ds_read_b64_tr_b16 v[238:239], v205 offset:16384
	ds_read_b64_tr_b16 v[240:241], v205 offset:20480
	s_waitcnt lgkmcnt(8)
	v_mfma_f32_32x32x16_bf16 v[48:63], v[128:131], v[250:253], v[48:63]
	ds_read_b64_tr_b16 v[128:129], v218 offset:16384
	ds_read_b64_tr_b16 v[130:131], v218 offset:20480
	s_waitcnt lgkmcnt(8)
	v_mfma_f32_32x32x16_bf16 v[32:47], v[206:209], v[250:253], v[32:47]
	ds_read_b64_tr_b16 v[206:207], v219 offset:16384
	ds_read_b64_tr_b16 v[208:209], v219 offset:20480
	s_waitcnt lgkmcnt(8)
	v_mfma_f32_32x32x16_bf16 v[16:31], v[210:213], v[250:253], v[16:31]
	ds_read_b64_tr_b16 v[210:211], v221 offset:16384
	ds_read_b64_tr_b16 v[212:213], v221 offset:20480
	s_waitcnt lgkmcnt(8)
	v_mfma_f32_32x32x16_bf16 v[0:15], v[214:217], v[250:253], v[0:15]
	ds_read_b64_tr_b16 v[214:215], v205 offset:16640
	ds_read_b64_tr_b16 v[216:217], v205 offset:20736
	s_nop 11
	v_max_f32_e32 v246, v190, v246
	v_sub_f32_e32 v190, v190, v246
	v_exp_f32_e32 v190, v190
	s_nop 0
	v_pk_mul_f32 v[126:127], v[126:127], v[190:191] op_sel_hi:[1,0]
	v_pk_mul_f32 v[124:125], v[124:125], v[190:191] op_sel_hi:[1,0]
	v_pk_mul_f32 v[122:123], v[122:123], v[190:191] op_sel_hi:[1,0]
	v_pk_mul_f32 v[120:121], v[120:121], v[190:191] op_sel_hi:[1,0]
	v_pk_mul_f32 v[118:119], v[118:119], v[190:191] op_sel_hi:[1,0]
	v_pk_mul_f32 v[116:117], v[116:117], v[190:191] op_sel_hi:[1,0]
	v_pk_mul_f32 v[114:115], v[114:115], v[190:191] op_sel_hi:[1,0]
	v_pk_mul_f32 v[112:113], v[112:113], v[190:191] op_sel_hi:[1,0]
	v_pk_mul_f32 v[110:111], v[110:111], v[190:191] op_sel_hi:[1,0]
	v_pk_mul_f32 v[108:109], v[108:109], v[190:191] op_sel_hi:[1,0]
	v_pk_mul_f32 v[106:107], v[106:107], v[190:191] op_sel_hi:[1,0]
	v_pk_mul_f32 v[104:105], v[104:105], v[190:191] op_sel_hi:[1,0]
	v_pk_mul_f32 v[102:103], v[102:103], v[190:191] op_sel_hi:[1,0]
	v_pk_mul_f32 v[100:101], v[100:101], v[190:191] op_sel_hi:[1,0]
	v_pk_mul_f32 v[98:99], v[98:99], v[190:191] op_sel_hi:[1,0]
	v_pk_mul_f32 v[96:97], v[96:97], v[190:191] op_sel_hi:[1,0]
	v_pk_mul_f32 v[94:95], v[94:95], v[190:191] op_sel_hi:[1,0]
	v_pk_mul_f32 v[92:93], v[92:93], v[190:191] op_sel_hi:[1,0]
	v_pk_mul_f32 v[90:91], v[90:91], v[190:191] op_sel_hi:[1,0]
	v_pk_mul_f32 v[88:89], v[88:89], v[190:191] op_sel_hi:[1,0]
	v_pk_mul_f32 v[86:87], v[86:87], v[190:191] op_sel_hi:[1,0]
	v_pk_mul_f32 v[84:85], v[84:85], v[190:191] op_sel_hi:[1,0]
	v_pk_mul_f32 v[82:83], v[82:83], v[190:191] op_sel_hi:[1,0]
	v_pk_mul_f32 v[80:81], v[80:81], v[190:191] op_sel_hi:[1,0]
	v_pk_mul_f32 v[78:79], v[78:79], v[190:191] op_sel_hi:[1,0]
	v_pk_mul_f32 v[76:77], v[76:77], v[190:191] op_sel_hi:[1,0]
	v_pk_mul_f32 v[74:75], v[74:75], v[190:191] op_sel_hi:[1,0]
	v_pk_mul_f32 v[72:73], v[72:73], v[190:191] op_sel_hi:[1,0]
	v_pk_mul_f32 v[70:71], v[70:71], v[190:191] op_sel_hi:[1,0]
	v_pk_mul_f32 v[68:69], v[68:69], v[190:191] op_sel_hi:[1,0]
	v_pk_mul_f32 v[66:67], v[66:67], v[190:191] op_sel_hi:[1,0]
	v_pk_mul_f32 v[64:65], v[64:65], v[190:191] op_sel_hi:[1,0]
	v_pk_mul_f32 v[62:63], v[62:63], v[190:191] op_sel_hi:[1,0]
	v_pk_mul_f32 v[60:61], v[60:61], v[190:191] op_sel_hi:[1,0]
	v_pk_mul_f32 v[58:59], v[58:59], v[190:191] op_sel_hi:[1,0]
	v_pk_mul_f32 v[56:57], v[56:57], v[190:191] op_sel_hi:[1,0]
	v_pk_mul_f32 v[54:55], v[54:55], v[190:191] op_sel_hi:[1,0]
	v_pk_mul_f32 v[52:53], v[52:53], v[190:191] op_sel_hi:[1,0]
	v_pk_mul_f32 v[50:51], v[50:51], v[190:191] op_sel_hi:[1,0]
	v_pk_mul_f32 v[48:49], v[48:49], v[190:191] op_sel_hi:[1,0]
	v_pk_mul_f32 v[46:47], v[46:47], v[190:191] op_sel_hi:[1,0]
	v_pk_mul_f32 v[44:45], v[44:45], v[190:191] op_sel_hi:[1,0]
	v_pk_mul_f32 v[42:43], v[42:43], v[190:191] op_sel_hi:[1,0]
	v_pk_mul_f32 v[40:41], v[40:41], v[190:191] op_sel_hi:[1,0]
	v_pk_mul_f32 v[38:39], v[38:39], v[190:191] op_sel_hi:[1,0]
	v_pk_mul_f32 v[36:37], v[36:37], v[190:191] op_sel_hi:[1,0]
	v_pk_mul_f32 v[34:35], v[34:35], v[190:191] op_sel_hi:[1,0]
	v_pk_mul_f32 v[32:33], v[32:33], v[190:191] op_sel_hi:[1,0]
	v_pk_mul_f32 v[30:31], v[30:31], v[190:191] op_sel_hi:[1,0]
	v_pk_mul_f32 v[28:29], v[28:29], v[190:191] op_sel_hi:[1,0]
	v_pk_mul_f32 v[26:27], v[26:27], v[190:191] op_sel_hi:[1,0]
	v_pk_mul_f32 v[24:25], v[24:25], v[190:191] op_sel_hi:[1,0]
	v_pk_mul_f32 v[22:23], v[22:23], v[190:191] op_sel_hi:[1,0]
	v_pk_mul_f32 v[20:21], v[20:21], v[190:191] op_sel_hi:[1,0]
	v_pk_mul_f32 v[18:19], v[18:19], v[190:191] op_sel_hi:[1,0]
	v_pk_mul_f32 v[16:17], v[16:17], v[190:191] op_sel_hi:[1,0]
	v_pk_mul_f32 v[14:15], v[14:15], v[190:191] op_sel_hi:[1,0]
	v_pk_mul_f32 v[12:13], v[12:13], v[190:191] op_sel_hi:[1,0]
	v_pk_mul_f32 v[10:11], v[10:11], v[190:191] op_sel_hi:[1,0]
	v_pk_mul_f32 v[8:9], v[8:9], v[190:191] op_sel_hi:[1,0]
	v_pk_mul_f32 v[6:7], v[6:7], v[190:191] op_sel_hi:[1,0]
	v_pk_mul_f32 v[4:5], v[4:5], v[190:191] op_sel_hi:[1,0]
	v_pk_mul_f32 v[2:3], v[2:3], v[190:191] op_sel_hi:[1,0]
	v_pk_mul_f32 v[0:1], v[0:1], v[190:191] op_sel_hi:[1,0]
	v_mul_f32_e32 v195, v195, v190
	v_mov_b32_e32 v190, v246
	v_sub_f32_e32 v222, v222, v190
	v_exp_f32_e32 v222, v222
	v_sub_f32_e32 v223, v223, v190
	v_exp_f32_e32 v223, v223
	v_sub_f32_e32 v224, v224, v190
	v_add_f32_e32 v254, 0, v222
	v_exp_f32_e32 v224, v224
	v_sub_f32_e32 v225, v225, v190
	v_add_f32_e32 v254, v223, v254
	v_exp_f32_e32 v225, v225
	v_sub_f32_e32 v226, v226, v190
	v_add_f32_e32 v254, v224, v254
	v_exp_f32_e32 v226, v226
	v_sub_f32_e32 v227, v227, v190
	v_add_f32_e32 v254, v225, v254
	v_exp_f32_e32 v227, v227
	v_sub_f32_e32 v228, v228, v190
	v_add_f32_e32 v254, v226, v254
	v_exp_f32_e32 v228, v228
	v_sub_f32_e32 v229, v229, v190
	v_add_f32_e32 v254, v227, v254
	v_exp_f32_e32 v229, v229
	v_sub_f32_e32 v230, v230, v190
	v_add_f32_e32 v254, v228, v254
	v_exp_f32_e32 v230, v230
	v_sub_f32_e32 v231, v231, v190
	v_add_f32_e32 v254, v229, v254
	v_exp_f32_e32 v231, v231
	v_sub_f32_e32 v232, v232, v190
	v_add_f32_e32 v254, v230, v254
	v_exp_f32_e32 v232, v232
	v_sub_f32_e32 v233, v233, v190
	v_add_f32_e32 v254, v231, v254
	v_exp_f32_e32 v233, v233
	v_sub_f32_e32 v234, v234, v190
	v_add_f32_e32 v254, v232, v254
	v_exp_f32_e32 v234, v234
	v_sub_f32_e32 v235, v235, v190
	v_add_f32_e32 v254, v233, v254
	v_exp_f32_e32 v235, v235
	v_sub_f32_e32 v236, v236, v190
	v_add_f32_e32 v254, v234, v254
	v_exp_f32_e32 v236, v236
	v_sub_f32_e32 v237, v237, v190
	v_add_f32_e32 v254, v235, v254
	v_exp_f32_e32 v237, v237
	v_add_f32_e32 v254, v236, v254
	v_add_f32_e32 v254, v237, v254
	v_cvt_pk_bf16_f32 v242, v222, v223
	v_cvt_pk_bf16_f32 v243, v224, v225
	v_cvt_pk_bf16_f32 v244, v226, v227
	v_cvt_pk_bf16_f32 v245, v228, v229
	v_cvt_pk_bf16_f32 v250, v230, v231
	v_cvt_pk_bf16_f32 v251, v232, v233
	v_cvt_pk_bf16_f32 v252, v234, v235
	v_cvt_pk_bf16_f32 v253, v236, v237
	v_add_f32_e32 v195, v195, v254
	s_nop 1
	s_waitcnt lgkmcnt(8)
	v_mfma_f32_32x32x16_bf16 v[112:127], v[238:241], v[242:245], v[112:127]
	ds_read_b64_tr_b16 v[238:239], v218 offset:16640
	ds_read_b64_tr_b16 v[240:241], v218 offset:20736
	s_waitcnt lgkmcnt(8)
	v_mfma_f32_32x32x16_bf16 v[96:111], v[128:131], v[242:245], v[96:111]
	ds_read_b64_tr_b16 v[222:223], v219 offset:16640
	ds_read_b64_tr_b16 v[224:225], v219 offset:20736
	s_cmp_lg_u64 s[18:19], 0
	s_cbranch_scc1 .Latt_ndr0_1
	s_sub_i32 s100, s33, 1
	s_cmp_eq_u32 s33, 0
	s_cselect_b32 s100, 2, s100
	s_lshl_b32 s101, s100, 14
	s_add_i32 m0, s85, s101
	s_nop 0
	global_load_lds_dwordx4 v178, s[12:13]
.Latt_ndr0_1:
	s_waitcnt lgkmcnt(8)
	v_mfma_f32_32x32x16_bf16 v[80:95], v[206:209], v[242:245], v[80:95]
	ds_read_b64_tr_b16 v[206:207], v221 offset:16640
	ds_read_b64_tr_b16 v[208:209], v221 offset:20736
	s_waitcnt lgkmcnt(8)
	v_mfma_f32_32x32x16_bf16 v[64:79], v[210:213], v[242:245], v[64:79]
	ds_read_b64_tr_b16 v[210:211], v205 offset:24576
	ds_read_b64_tr_b16 v[212:213], v205 offset:28672
	s_cmp_lg_u64 s[18:19], 0
	s_cbranch_scc1 .Latt_ndr1_1
	s_add_i32 m0, m0, 0x400
	s_nop 0
	global_load_lds_dwordx4 v180, s[12:13]

.LBB0_885:
	s_cmp_gt_i32 s84, s81
	s_cbranch_scc1 .LBB0_896
	s_add_i32 s100, s84, 63
	s_cmp_le_i32 s100, s80
	s_cbranch_scc0 .Latt_slow_2
	s_lshl_b32 s98, s38, 14
	s_lshl_b32 s99, s38, 15
	s_add_i32 s99, s99, 0xc000
	v_add_u32_e32 v206, s98, v195
	ds_read_b128 v[206:209], v206
	v_add_u32_e32 v210, s98, v196
	ds_read_b128 v[210:213], v210
	v_add_u32_e32 v214, s98, v197
	ds_read_b128 v[214:217], v214
	v_add_u32_e32 v238, s98, v198
	ds_read_b128 v[238:241], v238
	v_add_u32_e32 v242, s98, v199
	ds_read_b128 v[242:245], v242
	v_add_u32_e32 v250, s98, v200
	ds_read_b128 v[250:253], v250
	v_add_u32_e32 v222, s98, v201
	ds_read_b128 v[222:225], v222
	v_add_u32_e32 v226, s98, v202
	ds_read_b128 v[226:229], v226
	v_bfe_u32 v246, v204, 2, 2
	v_bfe_u32 v247, v204, 5, 1
	v_lshl_or_b32 v247, v247, 2, v246
	v_and_b32_e32 v249, 3, v204
	v_and_b32_e32 v254, 16, v204
	v_lshl_or_b32 v249, v249, 2, v254
	v_lshlrev_b32_e32 v249, 1, v249
	v_lshl_add_u32 v247, v247, 9, v249
	v_add_u32_e32 v247, s99, v247
	v_lshlrev_b32_e32 v246, 6, v246
	v_add_u32_e32 v205, v247, v246
	v_xor_b32_e32 v249, 64, v246
	v_add_u32_e32 v218, v247, v249
	v_xor_b32_e32 v249, 0x80, v246
	v_add_u32_e32 v219, v247, v249
	v_xor_b32_e32 v249, 0xc0, v246
	v_add_u32_e32 v221, v247, v249
	s_waitcnt lgkmcnt(7)
	v_mfma_f32_32x32x16_bf16 v[128:143], v[206:209], v[144:147], 0
	v_add_u32_e32 v206, s98, v195
	ds_read_b128 v[206:209], v206 offset:8192
	s_waitcnt lgkmcnt(7)
	v_mfma_f32_32x32x16_bf16 v[128:143], v[210:213], v[148:151], v[128:143]
	v_add_u32_e32 v210, s98, v196
	ds_read_b128 v[210:213], v210 offset:8192
	s_waitcnt lgkmcnt(7)
	v_mfma_f32_32x32x16_bf16 v[128:143], v[214:217], v[152:155], v[128:143]
	v_add_u32_e32 v214, s98, v197
	ds_read_b128 v[214:217], v214 offset:8192
	s_waitcnt lgkmcnt(7)
	v_mfma_f32_32x32x16_bf16 v[128:143], v[238:241], v[156:159], v[128:143]
	v_add_u32_e32 v238, s98, v198
	ds_read_b128 v[238:241], v238 offset:8192
	s_waitcnt lgkmcnt(7)
	v_mfma_f32_32x32x16_bf16 v[128:143], v[242:245], v[160:163], v[128:143]
	s_waitcnt lgkmcnt(6)
	v_mfma_f32_32x32x16_bf16 v[128:143], v[250:253], v[164:167], v[128:143]
	s_waitcnt lgkmcnt(5)
	v_mfma_f32_32x32x16_bf16 v[128:143], v[222:225], v[168:171], v[128:143]
	s_waitcnt lgkmcnt(4)
	v_mfma_f32_32x32x16_bf16 v[128:143], v[226:229], v[172:175], v[128:143]
	s_waitcnt lgkmcnt(3)
	v_mfma_f32_32x32x16_bf16 v[222:237], v[206:209], v[144:147], 0
	v_add_u32_e32 v206, s98, v199
	ds_read_b128 v[206:209], v206 offset:8192
	s_nop 7
	v_max3_f32 v246, v128, v129, v130
	v_max3_f32 v247, v131, v132, v133
	v_max3_f32 v246, v246, v134, v135
	v_max3_f32 v247, v247, v136, v137
	v_max3_f32 v246, v246, v138, v139
	v_max3_f32 v247, v247, v140, v141
	v_max3_f32 v246, v246, v142, v143
	s_waitcnt lgkmcnt(3)
	v_mfma_f32_32x32x16_bf16 v[222:237], v[210:213], v[148:151], v[222:237]
	v_add_u32_e32 v210, s98, v200
	ds_read_b128 v[210:213], v210 offset:8192
	v_max_f32_e32 v246, v246, v247
	v_mov_b32_e32 v247, v246
	v_add_f32_e32 v249, 0x41000000, v190
	s_nop 1
	v_permlane32_swap_b32_e32 v246, v247
	v_max_f32_e32 v246, v246, v247
	v_cmp_gt_f32_e32 vcc, v246, v249
	s_cbranch_vccz .Latt_nr0_2
	v_max_f32_e32 v246, v190, v246
	v_sub_f32_e32 v190, v190, v246
	v_exp_f32_e32 v190, v190
	s_nop 0
	v_pk_mul_f32 v[126:127], v[126:127], v[190:191] op_sel_hi:[1,0]
	v_pk_mul_f32 v[124:125], v[124:125], v[190:191] op_sel_hi:[1,0]
	v_pk_mul_f32 v[122:123], v[122:123], v[190:191] op_sel_hi:[1,0]
	v_pk_mul_f32 v[120:121], v[120:121], v[190:191] op_sel_hi:[1,0]
	v_pk_mul_f32 v[118:119], v[118:119], v[190:191] op_sel_hi:[1,0]
	v_pk_mul_f32 v[116:117], v[116:117], v[190:191] op_sel_hi:[1,0]
	v_pk_mul_f32 v[114:115], v[114:115], v[190:191] op_sel_hi:[1,0]
	v_pk_mul_f32 v[112:113], v[112:113], v[190:191] op_sel_hi:[1,0]
	v_pk_mul_f32 v[110:111], v[110:111], v[190:191] op_sel_hi:[1,0]
	v_pk_mul_f32 v[108:109], v[108:109], v[190:191] op_sel_hi:[1,0]
	v_pk_mul_f32 v[106:107], v[106:107], v[190:191] op_sel_hi:[1,0]
	v_pk_mul_f32 v[104:105], v[104:105], v[190:191] op_sel_hi:[1,0]
	v_pk_mul_f32 v[102:103], v[102:103], v[190:191] op_sel_hi:[1,0]
	v_pk_mul_f32 v[100:101], v[100:101], v[190:191] op_sel_hi:[1,0]
	v_pk_mul_f32 v[98:99], v[98:99], v[190:191] op_sel_hi:[1,0]
	v_pk_mul_f32 v[96:97], v[96:97], v[190:191] op_sel_hi:[1,0]
	v_pk_mul_f32 v[94:95], v[94:95], v[190:191] op_sel_hi:[1,0]
	v_pk_mul_f32 v[92:93], v[92:93], v[190:191] op_sel_hi:[1,0]
	v_pk_mul_f32 v[90:91], v[90:91], v[190:191] op_sel_hi:[1,0]
	v_pk_mul_f32 v[88:89], v[88:89], v[190:191] op_sel_hi:[1,0]
	v_pk_mul_f32 v[86:87], v[86:87], v[190:191] op_sel_hi:[1,0]
	v_pk_mul_f32 v[84:85], v[84:85], v[190:191] op_sel_hi:[1,0]
	v_pk_mul_f32 v[82:83], v[82:83], v[190:191] op_sel_hi:[1,0]
	v_pk_mul_f32 v[80:81], v[80:81], v[190:191] op_sel_hi:[1,0]
	v_pk_mul_f32 v[78:79], v[78:79], v[190:191] op_sel_hi:[1,0]
	v_pk_mul_f32 v[76:77], v[76:77], v[190:191] op_sel_hi:[1,0]
	v_pk_mul_f32 v[74:75], v[74:75], v[190:191] op_sel_hi:[1,0]
	v_pk_mul_f32 v[72:73], v[72:73], v[190:191] op_sel_hi:[1,0]
	v_pk_mul_f32 v[70:71], v[70:71], v[190:191] op_sel_hi:[1,0]
	v_pk_mul_f32 v[68:69], v[68:69], v[190:191] op_sel_hi:[1,0]
	v_pk_mul_f32 v[66:67], v[66:67], v[190:191] op_sel_hi:[1,0]
	v_pk_mul_f32 v[64:65], v[64:65], v[190:191] op_sel_hi:[1,0]
	v_pk_mul_f32 v[62:63], v[62:63], v[190:191] op_sel_hi:[1,0]
	v_pk_mul_f32 v[60:61], v[60:61], v[190:191] op_sel_hi:[1,0]
	v_pk_mul_f32 v[58:59], v[58:59], v[190:191] op_sel_hi:[1,0]
	v_pk_mul_f32 v[56:57], v[56:57], v[190:191] op_sel_hi:[1,0]
	v_pk_mul_f32 v[54:55], v[54:55], v[190:191] op_sel_hi:[1,0]
	v_pk_mul_f32 v[52:53], v[52:53], v[190:191] op_sel_hi:[1,0]
	v_pk_mul_f32 v[50:51], v[50:51], v[190:191] op_sel_hi:[1,0]
	v_pk_mul_f32 v[48:49], v[48:49], v[190:191] op_sel_hi:[1,0]
	v_pk_mul_f32 v[46:47], v[46:47], v[190:191] op_sel_hi:[1,0]
	v_pk_mul_f32 v[44:45], v[44:45], v[190:191] op_sel_hi:[1,0]
	v_pk_mul_f32 v[42:43], v[42:43], v[190:191] op_sel_hi:[1,0]
	v_pk_mul_f32 v[40:41], v[40:41], v[190:191] op_sel_hi:[1,0]
	v_pk_mul_f32 v[38:39], v[38:39], v[190:191] op_sel_hi:[1,0]
	v_pk_mul_f32 v[36:37], v[36:37], v[190:191] op_sel_hi:[1,0]
	v_pk_mul_f32 v[34:35], v[34:35], v[190:191] op_sel_hi:[1,0]
	v_pk_mul_f32 v[32:33], v[32:33], v[190:191] op_sel_hi:[1,0]
	v_pk_mul_f32 v[30:31], v[30:31], v[190:191] op_sel_hi:[1,0]
	v_pk_mul_f32 v[28:29], v[28:29], v[190:191] op_sel_hi:[1,0]
	v_pk_mul_f32 v[26:27], v[26:27], v[190:191] op_sel_hi:[1,0]
	v_pk_mul_f32 v[24:25], v[24:25], v[190:191] op_sel_hi:[1,0]
	v_pk_mul_f32 v[22:23], v[22:23], v[190:191] op_sel_hi:[1,0]
	v_pk_mul_f32 v[20:21], v[20:21], v[190:191] op_sel_hi:[1,0]
	v_pk_mul_f32 v[18:19], v[18:19], v[190:191] op_sel_hi:[1,0]
	v_pk_mul_f32 v[16:17], v[16:17], v[190:191] op_sel_hi:[1,0]
	v_pk_mul_f32 v[14:15], v[14:15], v[190:191] op_sel_hi:[1,0]
	v_pk_mul_f32 v[12:13], v[12:13], v[190:191] op_sel_hi:[1,0]
	v_pk_mul_f32 v[10:11], v[10:11], v[190:191] op_sel_hi:[1,0]
	v_pk_mul_f32 v[8:9], v[8:9], v[190:191] op_sel_hi:[1,0]
	v_pk_mul_f32 v[6:7], v[6:7], v[190:191] op_sel_hi:[1,0]
	v_pk_mul_f32 v[4:5], v[4:5], v[190:191] op_sel_hi:[1,0]
	v_pk_mul_f32 v[2:3], v[2:3], v[190:191] op_sel_hi:[1,0]
	v_pk_mul_f32 v[0:1], v[0:1], v[190:191] op_sel_hi:[1,0]
	v_mul_f32_e32 v203, v203, v190
	v_mov_b32_e32 v190, v246
.Latt_nr0_2:
	s_waitcnt lgkmcnt(3)
	v_mfma_f32_32x32x16_bf16 v[222:237], v[214:217], v[152:155], v[222:237]
	v_add_u32_e32 v214, s98, v201
	ds_read_b128 v[214:217], v214 offset:8192
	v_sub_f32_e32 v128, v128, v190
	v_exp_f32_e32 v128, v128
	v_sub_f32_e32 v129, v129, v190
	v_exp_f32_e32 v129, v129
	v_sub_f32_e32 v130, v130, v190
	s_waitcnt lgkmcnt(3)
	v_mfma_f32_32x32x16_bf16 v[222:237], v[238:241], v[156:159], v[222:237]
	v_add_u32_e32 v238, s98, v202
	ds_read_b128 v[238:241], v238 offset:8192
	v_add_f32_e32 v254, 0, v128
	v_exp_f32_e32 v130, v130
	v_sub_f32_e32 v131, v131, v190
	v_add_f32_e32 v254, v129, v254
	v_exp_f32_e32 v131, v131
	s_waitcnt lgkmcnt(3)
	v_mfma_f32_32x32x16_bf16 v[222:237], v[206:209], v[160:163], v[222:237]
	ds_read_b64_tr_b16 v[206:207], v205
	ds_read_b64_tr_b16 v[208:209], v205 offset:4096
	v_sub_f32_e32 v132, v132, v190
	v_add_f32_e32 v254, v130, v254
	v_exp_f32_e32 v132, v132
	v_sub_f32_e32 v133, v133, v190
	v_add_f32_e32 v254, v131, v254
	s_waitcnt lgkmcnt(4)
	v_mfma_f32_32x32x16_bf16 v[222:237], v[210:213], v[164:167], v[222:237]
	ds_read_b64_tr_b16 v[210:211], v218
	ds_read_b64_tr_b16 v[212:213], v218 offset:4096
	v_exp_f32_e32 v133, v133
	v_sub_f32_e32 v134, v134, v190
	v_add_f32_e32 v254, v132, v254
	v_exp_f32_e32 v134, v134
	s_waitcnt lgkmcnt(5)
	v_mfma_f32_32x32x16_bf16 v[222:237], v[214:217], v[168:171], v[222:237]
	ds_read_b64_tr_b16 v[214:215], v219
	ds_read_b64_tr_b16 v[216:217], v219 offset:4096
	v_sub_f32_e32 v135, v135, v190
	v_add_f32_e32 v254, v133, v254
	v_exp_f32_e32 v135, v135
	s_nop 0
	s_waitcnt lgkmcnt(6)
	v_mfma_f32_32x32x16_bf16 v[222:237], v[238:241], v[172:175], v[222:237]
	ds_read_b64_tr_b16 v[238:239], v221
	ds_read_b64_tr_b16 v[240:241], v221 offset:4096
	v_cvt_pk_bf16_f32 v242, v128, v129
	v_cvt_pk_bf16_f32 v243, v130, v131
	v_cvt_pk_bf16_f32 v244, v132, v133
	v_cvt_pk_bf16_f32 v245, v134, v135
	s_nop 1
	s_waitcnt lgkmcnt(6)
	v_mfma_f32_32x32x16_bf16 v[112:127], v[206:209], v[242:245], v[112:127]
	ds_read_b64_tr_b16 v[206:207], v205 offset:256
	ds_read_b64_tr_b16 v[208:209], v205 offset:4352
	v_sub_f32_e32 v136, v136, v190
	v_add_f32_e32 v254, v134, v254
	v_exp_f32_e32 v136, v136
	v_sub_f32_e32 v137, v137, v190
	v_add_f32_e32 v254, v135, v254
	s_waitcnt lgkmcnt(6)
	v_mfma_f32_32x32x16_bf16 v[96:111], v[210:213], v[242:245], v[96:111]
	ds_read_b64_tr_b16 v[210:211], v218 offset:256
	ds_read_b64_tr_b16 v[212:213], v218 offset:4352
	v_exp_f32_e32 v137, v137
	v_sub_f32_e32 v138, v138, v190
	v_add_f32_e32 v254, v136, v254
	v_exp_f32_e32 v138, v138
	v_sub_f32_e32 v139, v139, v190
	s_waitcnt lgkmcnt(6)
	v_mfma_f32_32x32x16_bf16 v[80:95], v[214:217], v[242:245], v[80:95]
	ds_read_b64_tr_b16 v[214:215], v219 offset:256
	ds_read_b64_tr_b16 v[216:217], v219 offset:4352
	v_add_f32_e32 v254, v137, v254
	v_exp_f32_e32 v139, v139
	v_sub_f32_e32 v140, v140, v190
	v_add_f32_e32 v254, v138, v254
	s_waitcnt lgkmcnt(6)
	v_mfma_f32_32x32x16_bf16 v[64:79], v[238:241], v[242:245], v[64:79]
	ds_read_b64_tr_b16 v[238:239], v221 offset:256
	ds_read_b64_tr_b16 v[240:241], v221 offset:4352
	v_exp_f32_e32 v140, v140
	v_sub_f32_e32 v141, v141, v190
	v_add_f32_e32 v254, v139, v254
	v_exp_f32_e32 v141, v141
	s_waitcnt lgkmcnt(6)
	v_mfma_f32_32x32x16_bf16 v[48:63], v[206:209], v[242:245], v[48:63]
	ds_read_b64_tr_b16 v[206:207], v205 offset:8192
	ds_read_b64_tr_b16 v[208:209], v205 offset:12288
	v_sub_f32_e32 v142, v142, v190
	v_add_f32_e32 v254, v140, v254
	v_exp_f32_e32 v142, v142
	v_sub_f32_e32 v143, v143, v190
	s_waitcnt lgkmcnt(6)
	v_mfma_f32_32x32x16_bf16 v[32:47], v[210:213], v[242:245], v[32:47]
	ds_read_b64_tr_b16 v[210:211], v218 offset:8192
	ds_read_b64_tr_b16 v[212:213], v218 offset:12288
	v_add_f32_e32 v254, v141, v254
	v_exp_f32_e32 v143, v143
	v_add_f32_e32 v254, v142, v254
	v_add_f32_e32 v254, v143, v254
	s_waitcnt lgkmcnt(6)
	v_mfma_f32_32x32x16_bf16 v[16:31], v[214:217], v[242:245], v[16:31]
	ds_read_b64_tr_b16 v[214:215], v219 offset:8192
	ds_read_b64_tr_b16 v[216:217], v219 offset:12288
	v_cvt_pk_bf16_f32 v250, v136, v137
	v_cvt_pk_bf16_f32 v251, v138, v139
	v_cvt_pk_bf16_f32 v252, v140, v141
	v_cvt_pk_bf16_f32 v253, v142, v143
	v_add_f32_e32 v203, v203, v254
	s_waitcnt lgkmcnt(6)
	v_mfma_f32_32x32x16_bf16 v[0:15], v[238:241], v[242:245], v[0:15]
	ds_read_b64_tr_b16 v[238:239], v221 offset:8192
	ds_read_b64_tr_b16 v[240:241], v221 offset:12288
	ds_read_b64_tr_b16 v[128:129], v205 offset:8448
	ds_read_b64_tr_b16 v[130:131], v205 offset:12544
	s_waitcnt lgkmcnt(8)
	v_mfma_f32_32x32x16_bf16 v[112:127], v[206:209], v[250:253], v[112:127]
	ds_read_b64_tr_b16 v[206:207], v218 offset:8448
	ds_read_b64_tr_b16 v[208:209], v218 offset:12544
	v_max3_f32 v246, v222, v223, v224
	v_max3_f32 v247, v225, v226, v227
	v_max3_f32 v246, v246, v228, v229
	v_max3_f32 v247, v247, v230, v231
	v_max3_f32 v246, v246, v232, v233
	v_max3_f32 v247, v247, v234, v235
	s_waitcnt lgkmcnt(8)
	v_mfma_f32_32x32x16_bf16 v[96:111], v[210:213], v[250:253], v[96:111]
	ds_read_b64_tr_b16 v[210:211], v219 offset:8448
	ds_read_b64_tr_b16 v[212:213], v219 offset:12544
	v_max3_f32 v246, v246, v236, v237
	v_max_f32_e32 v246, v246, v247
	v_mov_b32_e32 v247, v246
	v_add_f32_e32 v249, 0x41000000, v190
	s_nop 1
	s_waitcnt lgkmcnt(8)
	v_mfma_f32_32x32x16_bf16 v[80:95], v[214:217], v[250:253], v[80:95]
	ds_read_b64_tr_b16 v[214:215], v221 offset:8448
	ds_read_b64_tr_b16 v[216:217], v221 offset:12544
	v_permlane32_swap_b32_e32 v246, v247
	v_max_f32_e32 v246, v246, v247
	v_cmp_gt_f32_e32 vcc, v246, v249
	s_cbranch_vccnz .Latt_rs1_2
	s_waitcnt lgkmcnt(8)
	v_mfma_f32_32x32x16_bf16 v[64:79], v[238:241], v[250:253], v[64:79]
	ds_read_b64_tr_b16 v[238:239], v205 offset:16384
	ds_read_b64_tr_b16 v[240:241], v205 offset:20480
	v_sub_f32_e32 v222, v222, v190
	v_exp_f32_e32 v222, v222
	v_sub_f32_e32 v223, v223, v190
	v_exp_f32_e32 v223, v223
	v_sub_f32_e32 v224, v224, v190
	v_add_f32_e32 v254, 0, v222
	s_waitcnt lgkmcnt(8)
	v_mfma_f32_32x32x16_bf16 v[48:63], v[128:131], v[250:253], v[48:63]
	ds_read_b64_tr_b16 v[128:129], v218 offset:16384
	ds_read_b64_tr_b16 v[130:131], v218 offset:20480
	v_exp_f32_e32 v224, v224
	v_sub_f32_e32 v225, v225, v190
	v_add_f32_e32 v254, v223, v254
	v_exp_f32_e32 v225, v225
	v_sub_f32_e32 v226, v226, v190
	v_add_f32_e32 v254, v224, v254
	s_waitcnt lgkmcnt(8)
	v_mfma_f32_32x32x16_bf16 v[32:47], v[206:209], v[250:253], v[32:47]
	ds_read_b64_tr_b16 v[206:207], v219 offset:16384
	ds_read_b64_tr_b16 v[208:209], v219 offset:20480
	v_exp_f32_e32 v226, v226
	v_sub_f32_e32 v227, v227, v190
	v_add_f32_e32 v254, v225, v254
	v_exp_f32_e32 v227, v227
	v_sub_f32_e32 v228, v228, v190
	s_waitcnt lgkmcnt(8)
	v_mfma_f32_32x32x16_bf16 v[16:31], v[210:213], v[250:253], v[16:31]
	ds_read_b64_tr_b16 v[210:211], v221 offset:16384
	ds_read_b64_tr_b16 v[212:213], v221 offset:20480
	v_add_f32_e32 v254, v226, v254
	v_exp_f32_e32 v228, v228
	v_sub_f32_e32 v229, v229, v190
	v_add_f32_e32 v254, v227, v254
	v_exp_f32_e32 v229, v229
	s_waitcnt lgkmcnt(8)
	v_mfma_f32_32x32x16_bf16 v[0:15], v[214:217], v[250:253], v[0:15]
	ds_read_b64_tr_b16 v[214:215], v205 offset:16640
	ds_read_b64_tr_b16 v[216:217], v205 offset:20736
	s_nop 0
	v_cvt_pk_bf16_f32 v242, v222, v223
	v_cvt_pk_bf16_f32 v243, v224, v225
	v_cvt_pk_bf16_f32 v244, v226, v227
	v_cvt_pk_bf16_f32 v245, v228, v229
	s_nop 1
	s_waitcnt lgkmcnt(8)
	v_mfma_f32_32x32x16_bf16 v[112:127], v[238:241], v[242:245], v[112:127]
	ds_read_b64_tr_b16 v[238:239], v218 offset:16640
	ds_read_b64_tr_b16 v[240:241], v218 offset:20736
	v_sub_f32_e32 v230, v230, v190
	v_add_f32_e32 v254, v228, v254
	v_exp_f32_e32 v230, v230
	v_sub_f32_e32 v231, v231, v190
	v_add_f32_e32 v254, v229, v254
	s_waitcnt lgkmcnt(8)
	v_mfma_f32_32x32x16_bf16 v[96:111], v[128:131], v[242:245], v[96:111]
	ds_read_b64_tr_b16 v[128:129], v219 offset:16640
	ds_read_b64_tr_b16 v[130:131], v219 offset:20736
	v_exp_f32_e32 v231, v231
	v_sub_f32_e32 v232, v232, v190
	v_add_f32_e32 v254, v230, v254
	v_exp_f32_e32 v232, v232
	v_sub_f32_e32 v233, v233, v190
	s_cmp_lg_u64 s[12:13], 0
	s_cbranch_scc1 .Latt_nd0_2
	s_sub_i32 s100, s38, 1
	s_cmp_eq_u32 s38, 0
	s_cselect_b32 s100, 2, s100
	s_lshl_b32 s101, s100, 14
	s_add_i32 m0, s40, s101
	s_nop 0
	global_load_lds_dwordx4 v178, s[22:23]
.Latt_nd0_2:
	s_waitcnt lgkmcnt(8)
	v_mfma_f32_32x32x16_bf16 v[80:95], v[206:209], v[242:245], v[80:95]
	ds_read_b64_tr_b16 v[206:207], v221 offset:16640
	ds_read_b64_tr_b16 v[208:209], v221 offset:20736
	v_add_f32_e32 v254, v231, v254
	v_exp_f32_e32 v233, v233
	v_sub_f32_e32 v234, v234, v190
	v_add_f32_e32 v254, v232, v254
	s_waitcnt lgkmcnt(8)
	v_mfma_f32_32x32x16_bf16 v[64:79], v[210:213], v[242:245], v[64:79]
	ds_read_b64_tr_b16 v[210:211], v205 offset:24576
	ds_read_b64_tr_b16 v[212:213], v205 offset:28672
	v_exp_f32_e32 v234, v234
	v_sub_f32_e32 v235, v235, v190
	v_add_f32_e32 v254, v233, v254
	v_exp_f32_e32 v235, v235
	s_cmp_lg_u64 s[12:13], 0
	s_cbranch_scc1 .Latt_nd1_2
	s_add_i32 m0, m0, 0x400
	s_nop 0
	global_load_lds_dwordx4 v180, s[22:23]
.Latt_nd1_2:
	s_waitcnt lgkmcnt(8)
	v_mfma_f32_32x32x16_bf16 v[48:63], v[214:217], v[242:245], v[48:63]
	ds_read_b64_tr_b16 v[214:215], v218 offset:24576
	ds_read_b64_tr_b16 v[216:217], v218 offset:28672
	v_sub_f32_e32 v236, v236, v190
	v_add_f32_e32 v254, v234, v254
	v_exp_f32_e32 v236, v236
	v_sub_f32_e32 v237, v237, v190
	s_waitcnt lgkmcnt(8)
	v_mfma_f32_32x32x16_bf16 v[32:47], v[238:241], v[242:245], v[32:47]
	ds_read_b64_tr_b16 v[238:239], v219 offset:24576
	ds_read_b64_tr_b16 v[240:241], v219 offset:28672
	v_add_f32_e32 v254, v235, v254
	v_exp_f32_e32 v237, v237
	v_add_f32_e32 v254, v236, v254
	v_add_f32_e32 v254, v237, v254
	s_cmp_lg_u64 s[12:13], 0
	s_cbranch_scc1 .Latt_nd2_2
	s_lshl_b32 s101, s100, 15
	s_add_i32 m0, s41, s101
	s_add_u32 s100, s22, 0x1000
	s_addc_u32 s101, s23, 0
	global_load_lds_dwordx4 v182, s[100:101]
.Latt_nd2_2:
	s_waitcnt lgkmcnt(8)
	v_mfma_f32_32x32x16_bf16 v[16:31], v[128:131], v[242:245], v[16:31]
	ds_read_b64_tr_b16 v[128:129], v221 offset:24576
	ds_read_b64_tr_b16 v[130:131], v221 offset:28672
	v_cvt_pk_bf16_f32 v250, v230, v231
	v_cvt_pk_bf16_f32 v251, v232, v233
	v_cvt_pk_bf16_f32 v252, v234, v235
	v_cvt_pk_bf16_f32 v253, v236, v237
	v_add_f32_e32 v203, v203, v254
	s_waitcnt lgkmcnt(8)
	v_mfma_f32_32x32x16_bf16 v[0:15], v[206:209], v[242:245], v[0:15]
	ds_read_b64_tr_b16 v[206:207], v205 offset:24832
	ds_read_b64_tr_b16 v[208:209], v205 offset:28928
	s_cmp_lg_u64 s[12:13], 0
	s_cbranch_scc1 .Latt_nd3_2
	s_add_i32 m0, m0, 0x400
	s_nop 0
	global_load_lds_dwordx4 v184, s[100:101]
.Latt_nd3_2:
	s_waitcnt lgkmcnt(8)
	v_mfma_f32_32x32x16_bf16 v[112:127], v[210:213], v[250:253], v[112:127]
	ds_read_b64_tr_b16 v[210:211], v218 offset:24832
	ds_read_b64_tr_b16 v[212:213], v218 offset:28928
	s_waitcnt lgkmcnt(8)
	v_mfma_f32_32x32x16_bf16 v[96:111], v[214:217], v[250:253], v[96:111]
	ds_read_b64_tr_b16 v[214:215], v219 offset:24832
	ds_read_b64_tr_b16 v[216:217], v219 offset:28928
	s_cmp_lg_u64 s[12:13], 0
	s_cbranch_scc1 .Latt_nd4_2
	s_add_i32 m0, m0, 0x400
	s_nop 0
	global_load_lds_dwordx4 v186, s[100:101]
.Latt_nd4_2:
	s_waitcnt lgkmcnt(8)
	v_mfma_f32_32x32x16_bf16 v[80:95], v[238:241], v[250:253], v[80:95]
	ds_read_b64_tr_b16 v[238:239], v221 offset:24832
	ds_read_b64_tr_b16 v[240:241], v221 offset:28928
	s_waitcnt lgkmcnt(8)
	v_mfma_f32_32x32x16_bf16 v[64:79], v[128:131], v[250:253], v[64:79]
	s_cmp_lg_u64 s[12:13], 0
	s_cbranch_scc1 .Latt_nd5_2
	s_add_i32 m0, m0, 0x400
	s_nop 0
	global_load_lds_dwordx4 v188, s[100:101]

.Latt_rs1_2:
	s_waitcnt lgkmcnt(8)
	v_mfma_f32_32x32x16_bf16 v[64:79], v[238:241], v[250:253], v[64:79]
	ds_read_b64_tr_b16 v[238:239], v205 offset:16384
	ds_read_b64_tr_b16 v[240:241], v205 offset:20480
	s_waitcnt lgkmcnt(8)
	v_mfma_f32_32x32x16_bf16 v[48:63], v[128:131], v[250:253], v[48:63]
	ds_read_b64_tr_b16 v[128:129], v218 offset:16384
	ds_read_b64_tr_b16 v[130:131], v218 offset:20480
	s_waitcnt lgkmcnt(8)
	v_mfma_f32_32x32x16_bf16 v[32:47], v[206:209], v[250:253], v[32:47]
	ds_read_b64_tr_b16 v[206:207], v219 offset:16384
	ds_read_b64_tr_b16 v[208:209], v219 offset:20480
	s_waitcnt lgkmcnt(8)
	v_mfma_f32_32x32x16_bf16 v[16:31], v[210:213], v[250:253], v[16:31]
	ds_read_b64_tr_b16 v[210:211], v221 offset:16384
	ds_read_b64_tr_b16 v[212:213], v221 offset:20480
	s_waitcnt lgkmcnt(8)
	v_mfma_f32_32x32x16_bf16 v[0:15], v[214:217], v[250:253], v[0:15]
	ds_read_b64_tr_b16 v[214:215], v205 offset:16640
	ds_read_b64_tr_b16 v[216:217], v205 offset:20736
	s_nop 11
	v_max_f32_e32 v246, v190, v246
	v_sub_f32_e32 v190, v190, v246
	v_exp_f32_e32 v190, v190
	s_nop 0
	v_pk_mul_f32 v[126:127], v[126:127], v[190:191] op_sel_hi:[1,0]
	v_pk_mul_f32 v[124:125], v[124:125], v[190:191] op_sel_hi:[1,0]
	v_pk_mul_f32 v[122:123], v[122:123], v[190:191] op_sel_hi:[1,0]
	v_pk_mul_f32 v[120:121], v[120:121], v[190:191] op_sel_hi:[1,0]
	v_pk_mul_f32 v[118:119], v[118:119], v[190:191] op_sel_hi:[1,0]
	v_pk_mul_f32 v[116:117], v[116:117], v[190:191] op_sel_hi:[1,0]
	v_pk_mul_f32 v[114:115], v[114:115], v[190:191] op_sel_hi:[1,0]
	v_pk_mul_f32 v[112:113], v[112:113], v[190:191] op_sel_hi:[1,0]
	v_pk_mul_f32 v[110:111], v[110:111], v[190:191] op_sel_hi:[1,0]
	v_pk_mul_f32 v[108:109], v[108:109], v[190:191] op_sel_hi:[1,0]
	v_pk_mul_f32 v[106:107], v[106:107], v[190:191] op_sel_hi:[1,0]
	v_pk_mul_f32 v[104:105], v[104:105], v[190:191] op_sel_hi:[1,0]
	v_pk_mul_f32 v[102:103], v[102:103], v[190:191] op_sel_hi:[1,0]
	v_pk_mul_f32 v[100:101], v[100:101], v[190:191] op_sel_hi:[1,0]
	v_pk_mul_f32 v[98:99], v[98:99], v[190:191] op_sel_hi:[1,0]
	v_pk_mul_f32 v[96:97], v[96:97], v[190:191] op_sel_hi:[1,0]
	v_pk_mul_f32 v[94:95], v[94:95], v[190:191] op_sel_hi:[1,0]
	v_pk_mul_f32 v[92:93], v[92:93], v[190:191] op_sel_hi:[1,0]
	v_pk_mul_f32 v[90:91], v[90:91], v[190:191] op_sel_hi:[1,0]
	v_pk_mul_f32 v[88:89], v[88:89], v[190:191] op_sel_hi:[1,0]
	v_pk_mul_f32 v[86:87], v[86:87], v[190:191] op_sel_hi:[1,0]
	v_pk_mul_f32 v[84:85], v[84:85], v[190:191] op_sel_hi:[1,0]
	v_pk_mul_f32 v[82:83], v[82:83], v[190:191] op_sel_hi:[1,0]
	v_pk_mul_f32 v[80:81], v[80:81], v[190:191] op_sel_hi:[1,0]
	v_pk_mul_f32 v[78:79], v[78:79], v[190:191] op_sel_hi:[1,0]
	v_pk_mul_f32 v[76:77], v[76:77], v[190:191] op_sel_hi:[1,0]
	v_pk_mul_f32 v[74:75], v[74:75], v[190:191] op_sel_hi:[1,0]
	v_pk_mul_f32 v[72:73], v[72:73], v[190:191] op_sel_hi:[1,0]
	v_pk_mul_f32 v[70:71], v[70:71], v[190:191] op_sel_hi:[1,0]
	v_pk_mul_f32 v[68:69], v[68:69], v[190:191] op_sel_hi:[1,0]
	v_pk_mul_f32 v[66:67], v[66:67], v[190:191] op_sel_hi:[1,0]
	v_pk_mul_f32 v[64:65], v[64:65], v[190:191] op_sel_hi:[1,0]
	v_pk_mul_f32 v[62:63], v[62:63], v[190:191] op_sel_hi:[1,0]
	v_pk_mul_f32 v[60:61], v[60:61], v[190:191] op_sel_hi:[1,0]
	v_pk_mul_f32 v[58:59], v[58:59], v[190:191] op_sel_hi:[1,0]
	v_pk_mul_f32 v[56:57], v[56:57], v[190:191] op_sel_hi:[1,0]
	v_pk_mul_f32 v[54:55], v[54:55], v[190:191] op_sel_hi:[1,0]
	v_pk_mul_f32 v[52:53], v[52:53], v[190:191] op_sel_hi:[1,0]
	v_pk_mul_f32 v[50:51], v[50:51], v[190:191] op_sel_hi:[1,0]
	v_pk_mul_f32 v[48:49], v[48:49], v[190:191] op_sel_hi:[1,0]
	v_pk_mul_f32 v[46:47], v[46:47], v[190:191] op_sel_hi:[1,0]
	v_pk_mul_f32 v[44:45], v[44:45], v[190:191] op_sel_hi:[1,0]
	v_pk_mul_f32 v[42:43], v[42:43], v[190:191] op_sel_hi:[1,0]
	v_pk_mul_f32 v[40:41], v[40:41], v[190:191] op_sel_hi:[1,0]
	v_pk_mul_f32 v[38:39], v[38:39], v[190:191] op_sel_hi:[1,0]
	v_pk_mul_f32 v[36:37], v[36:37], v[190:191] op_sel_hi:[1,0]
	v_pk_mul_f32 v[34:35], v[34:35], v[190:191] op_sel_hi:[1,0]
	v_pk_mul_f32 v[32:33], v[32:33], v[190:191] op_sel_hi:[1,0]
	v_pk_mul_f32 v[30:31], v[30:31], v[190:191] op_sel_hi:[1,0]
	v_pk_mul_f32 v[28:29], v[28:29], v[190:191] op_sel_hi:[1,0]
	v_pk_mul_f32 v[26:27], v[26:27], v[190:191] op_sel_hi:[1,0]
	v_pk_mul_f32 v[24:25], v[24:25], v[190:191] op_sel_hi:[1,0]
	v_pk_mul_f32 v[22:23], v[22:23], v[190:191] op_sel_hi:[1,0]
	v_pk_mul_f32 v[20:21], v[20:21], v[190:191] op_sel_hi:[1,0]
	v_pk_mul_f32 v[18:19], v[18:19], v[190:191] op_sel_hi:[1,0]
	v_pk_mul_f32 v[16:17], v[16:17], v[190:191] op_sel_hi:[1,0]
	v_pk_mul_f32 v[14:15], v[14:15], v[190:191] op_sel_hi:[1,0]
	v_pk_mul_f32 v[12:13], v[12:13], v[190:191] op_sel_hi:[1,0]
	v_pk_mul_f32 v[10:11], v[10:11], v[190:191] op_sel_hi:[1,0]
	v_pk_mul_f32 v[8:9], v[8:9], v[190:191] op_sel_hi:[1,0]
	v_pk_mul_f32 v[6:7], v[6:7], v[190:191] op_sel_hi:[1,0]
	v_pk_mul_f32 v[4:5], v[4:5], v[190:191] op_sel_hi:[1,0]
	v_pk_mul_f32 v[2:3], v[2:3], v[190:191] op_sel_hi:[1,0]
	v_pk_mul_f32 v[0:1], v[0:1], v[190:191] op_sel_hi:[1,0]
	v_mul_f32_e32 v203, v203, v190
	v_mov_b32_e32 v190, v246
	v_sub_f32_e32 v222, v222, v190
	v_exp_f32_e32 v222, v222
	v_sub_f32_e32 v223, v223, v190
	v_exp_f32_e32 v223, v223
	v_sub_f32_e32 v224, v224, v190
	v_add_f32_e32 v254, 0, v222
	v_exp_f32_e32 v224, v224
	v_sub_f32_e32 v225, v225, v190
	v_add_f32_e32 v254, v223, v254
	v_exp_f32_e32 v225, v225
	v_sub_f32_e32 v226, v226, v190
	v_add_f32_e32 v254, v224, v254
	v_exp_f32_e32 v226, v226
	v_sub_f32_e32 v227, v227, v190
	v_add_f32_e32 v254, v225, v254
	v_exp_f32_e32 v227, v227
	v_sub_f32_e32 v228, v228, v190
	v_add_f32_e32 v254, v226, v254
	v_exp_f32_e32 v228, v228
	v_sub_f32_e32 v229, v229, v190
	v_add_f32_e32 v254, v227, v254
	v_exp_f32_e32 v229, v229
	v_sub_f32_e32 v230, v230, v190
	v_add_f32_e32 v254, v228, v254
	v_exp_f32_e32 v230, v230
	v_sub_f32_e32 v231, v231, v190
	v_add_f32_e32 v254, v229, v254
	v_exp_f32_e32 v231, v231
	v_sub_f32_e32 v232, v232, v190
	v_add_f32_e32 v254, v230, v254
	v_exp_f32_e32 v232, v232
	v_sub_f32_e32 v233, v233, v190
	v_add_f32_e32 v254, v231, v254
	v_exp_f32_e32 v233, v233
	v_sub_f32_e32 v234, v234, v190
	v_add_f32_e32 v254, v232, v254
	v_exp_f32_e32 v234, v234
	v_sub_f32_e32 v235, v235, v190
	v_add_f32_e32 v254, v233, v254
	v_exp_f32_e32 v235, v235
	v_sub_f32_e32 v236, v236, v190
	v_add_f32_e32 v254, v234, v254
	v_exp_f32_e32 v236, v236
	v_sub_f32_e32 v237, v237, v190
	v_add_f32_e32 v254, v235, v254
	v_exp_f32_e32 v237, v237
	v_add_f32_e32 v254, v236, v254
	v_add_f32_e32 v254, v237, v254
	v_cvt_pk_bf16_f32 v242, v222, v223
	v_cvt_pk_bf16_f32 v243, v224, v225
	v_cvt_pk_bf16_f32 v244, v226, v227
	v_cvt_pk_bf16_f32 v245, v228, v229
	v_cvt_pk_bf16_f32 v250, v230, v231
	v_cvt_pk_bf16_f32 v251, v232, v233
	v_cvt_pk_bf16_f32 v252, v234, v235
	v_cvt_pk_bf16_f32 v253, v236, v237
	v_add_f32_e32 v203, v203, v254
	s_nop 1
	s_waitcnt lgkmcnt(8)
	v_mfma_f32_32x32x16_bf16 v[112:127], v[238:241], v[242:245], v[112:127]
	ds_read_b64_tr_b16 v[238:239], v218 offset:16640
	ds_read_b64_tr_b16 v[240:241], v218 offset:20736
	s_waitcnt lgkmcnt(8)
	v_mfma_f32_32x32x16_bf16 v[96:111], v[128:131], v[242:245], v[96:111]
	ds_read_b64_tr_b16 v[222:223], v219 offset:16640
	ds_read_b64_tr_b16 v[224:225], v219 offset:20736
	s_cmp_lg_u64 s[12:13], 0
	s_cbranch_scc1 .Latt_ndr0_2
	s_sub_i32 s100, s38, 1
	s_cmp_eq_u32 s38, 0
	s_cselect_b32 s100, 2, s100
	s_lshl_b32 s101, s100, 14
	s_add_i32 m0, s40, s101
	s_nop 0
	global_load_lds_dwordx4 v178, s[22:23]
.Latt_ndr0_2:
	s_waitcnt lgkmcnt(8)
	v_mfma_f32_32x32x16_bf16 v[80:95], v[206:209], v[242:245], v[80:95]
	ds_read_b64_tr_b16 v[206:207], v221 offset:16640
	ds_read_b64_tr_b16 v[208:209], v221 offset:20736
	s_waitcnt lgkmcnt(8)
	v_mfma_f32_32x32x16_bf16 v[64:79], v[210:213], v[242:245], v[64:79]
	ds_read_b64_tr_b16 v[210:211], v205 offset:24576
	ds_read_b64_tr_b16 v[212:213], v205 offset:28672
	s_cmp_lg_u64 s[12:13], 0
	s_cbranch_scc1 .Latt_ndr1_2
	s_add_i32 m0, m0, 0x400
	s_nop 0
	global_load_lds_dwordx4 v180, s[22:23]

.Latt_ndr2_2:
	s_waitcnt lgkmcnt(8)
	v_mfma_f32_32x32x16_bf16 v[16:31], v[222:225], v[242:245], v[16:31]
	ds_read_b64_tr_b16 v[222:223], v221 offset:24576
	ds_read_b64_tr_b16 v[224:225], v221 offset:28672
	s_waitcnt lgkmcnt(8)
	v_mfma_f32_32x32x16_bf16 v[0:15], v[206:209], v[242:245], v[0:15]
	ds_read_b64_tr_b16 v[206:207], v205 offset:24832
	ds_read_b64_tr_b16 v[208:209], v205 offset:28928
	s_cmp_lg_u64 s[12:13], 0
	s_cbranch_scc1 .Latt_ndr3_2
	s_add_i32 m0, m0, 0x400
	s_nop 0
	global_load_lds_dwordx4 v184, s[100:101]

.Latt_ndr4_2:
	s_waitcnt lgkmcnt(8)
	v_mfma_f32_32x32x16_bf16 v[80:95], v[238:241], v[250:253], v[80:95]
	ds_read_b64_tr_b16 v[238:239], v221 offset:24832
	ds_read_b64_tr_b16 v[240:241], v221 offset:28928
	s_waitcnt lgkmcnt(8)
	v_mfma_f32_32x32x16_bf16 v[64:79], v[222:225], v[250:253], v[64:79]
	s_cmp_lg_u64 s[12:13], 0
	s_cbranch_scc1 .Latt_ndr5_2
	s_add_i32 m0, m0, 0x400
	s_nop 0
	global_load_lds_dwordx4 v188, s[100:101]

.LBB0_904:
	s_cmp_gt_i32 s14, s81
	s_cbranch_scc1 .LBB0_915
	s_add_i32 s100, s14, 63
	s_cmp_le_i32 s100, s80
	s_cbranch_scc0 .Latt_slow_3
	s_lshl_b32 s98, s11, 14
	s_lshl_b32 s99, s11, 15
	s_add_i32 s99, s99, 0xc000
	v_add_u32_e32 v206, s98, v196
	ds_read_b128 v[206:209], v206
	v_add_u32_e32 v210, s98, v197
	ds_read_b128 v[210:213], v210
	v_add_u32_e32 v214, s98, v198
	ds_read_b128 v[214:217], v214
	v_add_u32_e32 v238, s98, v199
	ds_read_b128 v[238:241], v238
	v_add_u32_e32 v242, s98, v200
	ds_read_b128 v[242:245], v242
	v_add_u32_e32 v250, s98, v201
	ds_read_b128 v[250:253], v250
	v_add_u32_e32 v222, s98, v202
	ds_read_b128 v[222:225], v222
	v_add_u32_e32 v226, s98, v203
	ds_read_b128 v[226:229], v226
	v_bfe_u32 v246, v204, 2, 2
	v_bfe_u32 v247, v204, 5, 1
	v_lshl_or_b32 v247, v247, 2, v246
	v_and_b32_e32 v249, 3, v204
	v_and_b32_e32 v254, 16, v204
	v_lshl_or_b32 v249, v249, 2, v254
	v_lshlrev_b32_e32 v249, 1, v249
	v_lshl_add_u32 v247, v247, 9, v249
	v_add_u32_e32 v247, s99, v247
	v_lshlrev_b32_e32 v246, 6, v246
	v_add_u32_e32 v205, v247, v246
	v_xor_b32_e32 v249, 64, v246
	v_add_u32_e32 v218, v247, v249
	v_xor_b32_e32 v249, 0x80, v246
	v_add_u32_e32 v219, v247, v249
	v_xor_b32_e32 v249, 0xc0, v246
	v_add_u32_e32 v221, v247, v249
	s_waitcnt lgkmcnt(7)
	v_mfma_f32_32x32x16_bf16 v[128:143], v[206:209], v[144:147], 0
	v_add_u32_e32 v206, s98, v196
	ds_read_b128 v[206:209], v206 offset:8192
	s_waitcnt lgkmcnt(7)
	v_mfma_f32_32x32x16_bf16 v[128:143], v[210:213], v[148:151], v[128:143]
	v_add_u32_e32 v210, s98, v197
	ds_read_b128 v[210:213], v210 offset:8192
	s_waitcnt lgkmcnt(7)
	v_mfma_f32_32x32x16_bf16 v[128:143], v[214:217], v[152:155], v[128:143]
	v_add_u32_e32 v214, s98, v198
	ds_read_b128 v[214:217], v214 offset:8192
	s_waitcnt lgkmcnt(7)
	v_mfma_f32_32x32x16_bf16 v[128:143], v[238:241], v[156:159], v[128:143]
	v_add_u32_e32 v238, s98, v199
	ds_read_b128 v[238:241], v238 offset:8192
	s_waitcnt lgkmcnt(7)
	v_mfma_f32_32x32x16_bf16 v[128:143], v[242:245], v[160:163], v[128:143]
	s_waitcnt lgkmcnt(6)
	v_mfma_f32_32x32x16_bf16 v[128:143], v[250:253], v[164:167], v[128:143]
	s_waitcnt lgkmcnt(5)
	v_mfma_f32_32x32x16_bf16 v[128:143], v[222:225], v[168:171], v[128:143]
	s_waitcnt lgkmcnt(4)
	v_mfma_f32_32x32x16_bf16 v[128:143], v[226:229], v[172:175], v[128:143]
	s_waitcnt lgkmcnt(3)
	v_mfma_f32_32x32x16_bf16 v[222:237], v[206:209], v[144:147], 0
	v_add_u32_e32 v206, s98, v200
	ds_read_b128 v[206:209], v206 offset:8192
	s_nop 7
	v_max3_f32 v246, v128, v129, v130
	v_max3_f32 v247, v131, v132, v133
	v_max3_f32 v246, v246, v134, v135
	v_max3_f32 v247, v247, v136, v137
	v_max3_f32 v246, v246, v138, v139
	v_max3_f32 v247, v247, v140, v141
	v_max3_f32 v246, v246, v142, v143
	s_waitcnt lgkmcnt(3)
	v_mfma_f32_32x32x16_bf16 v[222:237], v[210:213], v[148:151], v[222:237]
	v_add_u32_e32 v210, s98, v201
	ds_read_b128 v[210:213], v210 offset:8192
	v_max_f32_e32 v246, v246, v247
	v_mov_b32_e32 v247, v246
	v_add_f32_e32 v249, 0x41000000, v190
	s_nop 1
	v_permlane32_swap_b32_e32 v246, v247
	v_max_f32_e32 v246, v246, v247
	v_cmp_gt_f32_e32 vcc, v246, v249
	s_cbranch_vccz .Latt_nr0_3
	v_max_f32_e32 v246, v190, v246
	v_sub_f32_e32 v190, v190, v246
	v_exp_f32_e32 v190, v190
	s_nop 0
	v_pk_mul_f32 v[126:127], v[126:127], v[190:191] op_sel_hi:[1,0]
	v_pk_mul_f32 v[124:125], v[124:125], v[190:191] op_sel_hi:[1,0]
	v_pk_mul_f32 v[122:123], v[122:123], v[190:191] op_sel_hi:[1,0]
	v_pk_mul_f32 v[120:121], v[120:121], v[190:191] op_sel_hi:[1,0]
	v_pk_mul_f32 v[118:119], v[118:119], v[190:191] op_sel_hi:[1,0]
	v_pk_mul_f32 v[116:117], v[116:117], v[190:191] op_sel_hi:[1,0]
	v_pk_mul_f32 v[114:115], v[114:115], v[190:191] op_sel_hi:[1,0]
	v_pk_mul_f32 v[112:113], v[112:113], v[190:191] op_sel_hi:[1,0]
	v_pk_mul_f32 v[110:111], v[110:111], v[190:191] op_sel_hi:[1,0]
	v_pk_mul_f32 v[108:109], v[108:109], v[190:191] op_sel_hi:[1,0]
	v_pk_mul_f32 v[106:107], v[106:107], v[190:191] op_sel_hi:[1,0]
	v_pk_mul_f32 v[104:105], v[104:105], v[190:191] op_sel_hi:[1,0]
	v_pk_mul_f32 v[102:103], v[102:103], v[190:191] op_sel_hi:[1,0]
	v_pk_mul_f32 v[100:101], v[100:101], v[190:191] op_sel_hi:[1,0]
	v_pk_mul_f32 v[98:99], v[98:99], v[190:191] op_sel_hi:[1,0]
	v_pk_mul_f32 v[96:97], v[96:97], v[190:191] op_sel_hi:[1,0]
	v_pk_mul_f32 v[94:95], v[94:95], v[190:191] op_sel_hi:[1,0]
	v_pk_mul_f32 v[92:93], v[92:93], v[190:191] op_sel_hi:[1,0]
	v_pk_mul_f32 v[90:91], v[90:91], v[190:191] op_sel_hi:[1,0]
	v_pk_mul_f32 v[88:89], v[88:89], v[190:191] op_sel_hi:[1,0]
	v_pk_mul_f32 v[86:87], v[86:87], v[190:191] op_sel_hi:[1,0]
	v_pk_mul_f32 v[84:85], v[84:85], v[190:191] op_sel_hi:[1,0]
	v_pk_mul_f32 v[82:83], v[82:83], v[190:191] op_sel_hi:[1,0]
	v_pk_mul_f32 v[80:81], v[80:81], v[190:191] op_sel_hi:[1,0]
	v_pk_mul_f32 v[78:79], v[78:79], v[190:191] op_sel_hi:[1,0]
	v_pk_mul_f32 v[76:77], v[76:77], v[190:191] op_sel_hi:[1,0]
	v_pk_mul_f32 v[74:75], v[74:75], v[190:191] op_sel_hi:[1,0]
	v_pk_mul_f32 v[72:73], v[72:73], v[190:191] op_sel_hi:[1,0]
	v_pk_mul_f32 v[70:71], v[70:71], v[190:191] op_sel_hi:[1,0]
	v_pk_mul_f32 v[68:69], v[68:69], v[190:191] op_sel_hi:[1,0]
	v_pk_mul_f32 v[66:67], v[66:67], v[190:191] op_sel_hi:[1,0]
	v_pk_mul_f32 v[64:65], v[64:65], v[190:191] op_sel_hi:[1,0]
	v_pk_mul_f32 v[62:63], v[62:63], v[190:191] op_sel_hi:[1,0]
	v_pk_mul_f32 v[60:61], v[60:61], v[190:191] op_sel_hi:[1,0]
	v_pk_mul_f32 v[58:59], v[58:59], v[190:191] op_sel_hi:[1,0]
	v_pk_mul_f32 v[56:57], v[56:57], v[190:191] op_sel_hi:[1,0]
	v_pk_mul_f32 v[54:55], v[54:55], v[190:191] op_sel_hi:[1,0]
	v_pk_mul_f32 v[52:53], v[52:53], v[190:191] op_sel_hi:[1,0]
	v_pk_mul_f32 v[50:51], v[50:51], v[190:191] op_sel_hi:[1,0]
	v_pk_mul_f32 v[48:49], v[48:49], v[190:191] op_sel_hi:[1,0]
	v_pk_mul_f32 v[46:47], v[46:47], v[190:191] op_sel_hi:[1,0]
	v_pk_mul_f32 v[44:45], v[44:45], v[190:191] op_sel_hi:[1,0]
	v_pk_mul_f32 v[42:43], v[42:43], v[190:191] op_sel_hi:[1,0]
	v_pk_mul_f32 v[40:41], v[40:41], v[190:191] op_sel_hi:[1,0]
	v_pk_mul_f32 v[38:39], v[38:39], v[190:191] op_sel_hi:[1,0]
	v_pk_mul_f32 v[36:37], v[36:37], v[190:191] op_sel_hi:[1,0]
	v_pk_mul_f32 v[34:35], v[34:35], v[190:191] op_sel_hi:[1,0]
	v_pk_mul_f32 v[32:33], v[32:33], v[190:191] op_sel_hi:[1,0]
	v_pk_mul_f32 v[30:31], v[30:31], v[190:191] op_sel_hi:[1,0]
	v_pk_mul_f32 v[28:29], v[28:29], v[190:191] op_sel_hi:[1,0]
	v_pk_mul_f32 v[26:27], v[26:27], v[190:191] op_sel_hi:[1,0]
	v_pk_mul_f32 v[24:25], v[24:25], v[190:191] op_sel_hi:[1,0]
	v_pk_mul_f32 v[22:23], v[22:23], v[190:191] op_sel_hi:[1,0]
	v_pk_mul_f32 v[20:21], v[20:21], v[190:191] op_sel_hi:[1,0]
	v_pk_mul_f32 v[18:19], v[18:19], v[190:191] op_sel_hi:[1,0]
	v_pk_mul_f32 v[16:17], v[16:17], v[190:191] op_sel_hi:[1,0]
	v_pk_mul_f32 v[14:15], v[14:15], v[190:191] op_sel_hi:[1,0]
	v_pk_mul_f32 v[12:13], v[12:13], v[190:191] op_sel_hi:[1,0]
	v_pk_mul_f32 v[10:11], v[10:11], v[190:191] op_sel_hi:[1,0]
	v_pk_mul_f32 v[8:9], v[8:9], v[190:191] op_sel_hi:[1,0]
	v_pk_mul_f32 v[6:7], v[6:7], v[190:191] op_sel_hi:[1,0]
	v_pk_mul_f32 v[4:5], v[4:5], v[190:191] op_sel_hi:[1,0]
	v_pk_mul_f32 v[2:3], v[2:3], v[190:191] op_sel_hi:[1,0]
	v_pk_mul_f32 v[0:1], v[0:1], v[190:191] op_sel_hi:[1,0]
	v_mul_f32_e32 v195, v195, v190
	v_mov_b32_e32 v190, v246
.Latt_nr0_3:
	s_waitcnt lgkmcnt(3)
	v_mfma_f32_32x32x16_bf16 v[222:237], v[214:217], v[152:155], v[222:237]
	v_add_u32_e32 v214, s98, v202
	ds_read_b128 v[214:217], v214 offset:8192
	v_sub_f32_e32 v128, v128, v190
	v_exp_f32_e32 v128, v128
	v_sub_f32_e32 v129, v129, v190
	v_exp_f32_e32 v129, v129
	v_sub_f32_e32 v130, v130, v190
	s_waitcnt lgkmcnt(3)
	v_mfma_f32_32x32x16_bf16 v[222:237], v[238:241], v[156:159], v[222:237]
	v_add_u32_e32 v238, s98, v203
	ds_read_b128 v[238:241], v238 offset:8192
	v_add_f32_e32 v254, 0, v128
	v_exp_f32_e32 v130, v130
	v_sub_f32_e32 v131, v131, v190
	v_add_f32_e32 v254, v129, v254
	v_exp_f32_e32 v131, v131
	s_waitcnt lgkmcnt(3)
	v_mfma_f32_32x32x16_bf16 v[222:237], v[206:209], v[160:163], v[222:237]
	ds_read_b64_tr_b16 v[206:207], v205
	ds_read_b64_tr_b16 v[208:209], v205 offset:4096
	v_sub_f32_e32 v132, v132, v190
	v_add_f32_e32 v254, v130, v254
	v_exp_f32_e32 v132, v132
	v_sub_f32_e32 v133, v133, v190
	v_add_f32_e32 v254, v131, v254
	s_waitcnt lgkmcnt(4)
	v_mfma_f32_32x32x16_bf16 v[222:237], v[210:213], v[164:167], v[222:237]
	ds_read_b64_tr_b16 v[210:211], v218
	ds_read_b64_tr_b16 v[212:213], v218 offset:4096
	v_exp_f32_e32 v133, v133
	v_sub_f32_e32 v134, v134, v190
	v_add_f32_e32 v254, v132, v254
	v_exp_f32_e32 v134, v134
	s_waitcnt lgkmcnt(5)
	v_mfma_f32_32x32x16_bf16 v[222:237], v[214:217], v[168:171], v[222:237]
	ds_read_b64_tr_b16 v[214:215], v219
	ds_read_b64_tr_b16 v[216:217], v219 offset:4096
	v_sub_f32_e32 v135, v135, v190
	v_add_f32_e32 v254, v133, v254
	v_exp_f32_e32 v135, v135
	s_nop 0
	s_waitcnt lgkmcnt(6)
	v_mfma_f32_32x32x16_bf16 v[222:237], v[238:241], v[172:175], v[222:237]
	ds_read_b64_tr_b16 v[238:239], v221
	ds_read_b64_tr_b16 v[240:241], v221 offset:4096
	v_cvt_pk_bf16_f32 v242, v128, v129
	v_cvt_pk_bf16_f32 v243, v130, v131
	v_cvt_pk_bf16_f32 v244, v132, v133
	v_cvt_pk_bf16_f32 v245, v134, v135
	s_nop 1
	s_waitcnt lgkmcnt(6)
	v_mfma_f32_32x32x16_bf16 v[112:127], v[206:209], v[242:245], v[112:127]
	ds_read_b64_tr_b16 v[206:207], v205 offset:256
	ds_read_b64_tr_b16 v[208:209], v205 offset:4352
	v_sub_f32_e32 v136, v136, v190
	v_add_f32_e32 v254, v134, v254
	v_exp_f32_e32 v136, v136
	v_sub_f32_e32 v137, v137, v190
	v_add_f32_e32 v254, v135, v254
	s_waitcnt lgkmcnt(6)
	v_mfma_f32_32x32x16_bf16 v[96:111], v[210:213], v[242:245], v[96:111]
	ds_read_b64_tr_b16 v[210:211], v218 offset:256
	ds_read_b64_tr_b16 v[212:213], v218 offset:4352
	v_exp_f32_e32 v137, v137
	v_sub_f32_e32 v138, v138, v190
	v_add_f32_e32 v254, v136, v254
	v_exp_f32_e32 v138, v138
	v_sub_f32_e32 v139, v139, v190
	s_waitcnt lgkmcnt(6)
	v_mfma_f32_32x32x16_bf16 v[80:95], v[214:217], v[242:245], v[80:95]
	ds_read_b64_tr_b16 v[214:215], v219 offset:256
	ds_read_b64_tr_b16 v[216:217], v219 offset:4352
	v_add_f32_e32 v254, v137, v254
	v_exp_f32_e32 v139, v139
	v_sub_f32_e32 v140, v140, v190
	v_add_f32_e32 v254, v138, v254
	s_waitcnt lgkmcnt(6)
	v_mfma_f32_32x32x16_bf16 v[64:79], v[238:241], v[242:245], v[64:79]
	ds_read_b64_tr_b16 v[238:239], v221 offset:256
	ds_read_b64_tr_b16 v[240:241], v221 offset:4352
	v_exp_f32_e32 v140, v140
	v_sub_f32_e32 v141, v141, v190
	v_add_f32_e32 v254, v139, v254
	v_exp_f32_e32 v141, v141
	s_waitcnt lgkmcnt(6)
	v_mfma_f32_32x32x16_bf16 v[48:63], v[206:209], v[242:245], v[48:63]
	ds_read_b64_tr_b16 v[206:207], v205 offset:8192
	ds_read_b64_tr_b16 v[208:209], v205 offset:12288
	v_sub_f32_e32 v142, v142, v190
	v_add_f32_e32 v254, v140, v254
	v_exp_f32_e32 v142, v142
	v_sub_f32_e32 v143, v143, v190
	s_waitcnt lgkmcnt(6)
	v_mfma_f32_32x32x16_bf16 v[32:47], v[210:213], v[242:245], v[32:47]
	ds_read_b64_tr_b16 v[210:211], v218 offset:8192
	ds_read_b64_tr_b16 v[212:213], v218 offset:12288
	v_add_f32_e32 v254, v141, v254
	v_exp_f32_e32 v143, v143
	v_add_f32_e32 v254, v142, v254
	v_add_f32_e32 v254, v143, v254
	s_waitcnt lgkmcnt(6)
	v_mfma_f32_32x32x16_bf16 v[16:31], v[214:217], v[242:245], v[16:31]
	ds_read_b64_tr_b16 v[214:215], v219 offset:8192
	ds_read_b64_tr_b16 v[216:217], v219 offset:12288
	v_cvt_pk_bf16_f32 v250, v136, v137
	v_cvt_pk_bf16_f32 v251, v138, v139
	v_cvt_pk_bf16_f32 v252, v140, v141
	v_cvt_pk_bf16_f32 v253, v142, v143
	v_add_f32_e32 v195, v195, v254
	s_waitcnt lgkmcnt(6)
	v_mfma_f32_32x32x16_bf16 v[0:15], v[238:241], v[242:245], v[0:15]
	ds_read_b64_tr_b16 v[238:239], v221 offset:8192
	ds_read_b64_tr_b16 v[240:241], v221 offset:12288
	ds_read_b64_tr_b16 v[128:129], v205 offset:8448
	ds_read_b64_tr_b16 v[130:131], v205 offset:12544
	s_waitcnt lgkmcnt(8)
	v_mfma_f32_32x32x16_bf16 v[112:127], v[206:209], v[250:253], v[112:127]
	ds_read_b64_tr_b16 v[206:207], v218 offset:8448
	ds_read_b64_tr_b16 v[208:209], v218 offset:12544
	v_max3_f32 v246, v222, v223, v224
	v_max3_f32 v247, v225, v226, v227
	v_max3_f32 v246, v246, v228, v229
	v_max3_f32 v247, v247, v230, v231
	v_max3_f32 v246, v246, v232, v233
	v_max3_f32 v247, v247, v234, v235
	s_waitcnt lgkmcnt(8)
	v_mfma_f32_32x32x16_bf16 v[96:111], v[210:213], v[250:253], v[96:111]
	ds_read_b64_tr_b16 v[210:211], v219 offset:8448
	ds_read_b64_tr_b16 v[212:213], v219 offset:12544
	v_max3_f32 v246, v246, v236, v237
	v_max_f32_e32 v246, v246, v247
	v_mov_b32_e32 v247, v246
	v_add_f32_e32 v249, 0x41000000, v190
	s_nop 1
	s_waitcnt lgkmcnt(8)
	v_mfma_f32_32x32x16_bf16 v[80:95], v[214:217], v[250:253], v[80:95]
	ds_read_b64_tr_b16 v[214:215], v221 offset:8448
	ds_read_b64_tr_b16 v[216:217], v221 offset:12544
	v_permlane32_swap_b32_e32 v246, v247
	v_max_f32_e32 v246, v246, v247
	v_cmp_gt_f32_e32 vcc, v246, v249
	s_cbranch_vccnz .Latt_rs1_3
	s_waitcnt lgkmcnt(8)
	v_mfma_f32_32x32x16_bf16 v[64:79], v[238:241], v[250:253], v[64:79]
	ds_read_b64_tr_b16 v[238:239], v205 offset:16384
	ds_read_b64_tr_b16 v[240:241], v205 offset:20480
	v_sub_f32_e32 v222, v222, v190
	v_exp_f32_e32 v222, v222
	v_sub_f32_e32 v223, v223, v190
	v_exp_f32_e32 v223, v223
	v_sub_f32_e32 v224, v224, v190
	v_add_f32_e32 v254, 0, v222
	s_waitcnt lgkmcnt(8)
	v_mfma_f32_32x32x16_bf16 v[48:63], v[128:131], v[250:253], v[48:63]
	ds_read_b64_tr_b16 v[128:129], v218 offset:16384
	ds_read_b64_tr_b16 v[130:131], v218 offset:20480
	v_exp_f32_e32 v224, v224
	v_sub_f32_e32 v225, v225, v190
	v_add_f32_e32 v254, v223, v254
	v_exp_f32_e32 v225, v225
	v_sub_f32_e32 v226, v226, v190
	v_add_f32_e32 v254, v224, v254
	s_waitcnt lgkmcnt(8)
	v_mfma_f32_32x32x16_bf16 v[32:47], v[206:209], v[250:253], v[32:47]
	ds_read_b64_tr_b16 v[206:207], v219 offset:16384
	ds_read_b64_tr_b16 v[208:209], v219 offset:20480
	v_exp_f32_e32 v226, v226
	v_sub_f32_e32 v227, v227, v190
	v_add_f32_e32 v254, v225, v254
	v_exp_f32_e32 v227, v227
	v_sub_f32_e32 v228, v228, v190
	s_waitcnt lgkmcnt(8)
	v_mfma_f32_32x32x16_bf16 v[16:31], v[210:213], v[250:253], v[16:31]
	ds_read_b64_tr_b16 v[210:211], v221 offset:16384
	ds_read_b64_tr_b16 v[212:213], v221 offset:20480
	v_add_f32_e32 v254, v226, v254
	v_exp_f32_e32 v228, v228
	v_sub_f32_e32 v229, v229, v190
	v_add_f32_e32 v254, v227, v254
	v_exp_f32_e32 v229, v229
	s_waitcnt lgkmcnt(8)
	v_mfma_f32_32x32x16_bf16 v[0:15], v[214:217], v[250:253], v[0:15]
	ds_read_b64_tr_b16 v[214:215], v205 offset:16640
	ds_read_b64_tr_b16 v[216:217], v205 offset:20736
	s_nop 0
	v_cvt_pk_bf16_f32 v242, v222, v223
	v_cvt_pk_bf16_f32 v243, v224, v225
	v_cvt_pk_bf16_f32 v244, v226, v227
	v_cvt_pk_bf16_f32 v245, v228, v229
	s_nop 1
	s_waitcnt lgkmcnt(8)
	v_mfma_f32_32x32x16_bf16 v[112:127], v[238:241], v[242:245], v[112:127]
	ds_read_b64_tr_b16 v[238:239], v218 offset:16640
	ds_read_b64_tr_b16 v[240:241], v218 offset:20736
	v_sub_f32_e32 v230, v230, v190
	v_add_f32_e32 v254, v228, v254
	v_exp_f32_e32 v230, v230
	v_sub_f32_e32 v231, v231, v190
	v_add_f32_e32 v254, v229, v254
	s_waitcnt lgkmcnt(8)
	v_mfma_f32_32x32x16_bf16 v[96:111], v[128:131], v[242:245], v[96:111]
	ds_read_b64_tr_b16 v[128:129], v219 offset:16640
	ds_read_b64_tr_b16 v[130:131], v219 offset:20736
	v_exp_f32_e32 v231, v231
	v_sub_f32_e32 v232, v232, v190
	v_add_f32_e32 v254, v230, v254
	v_exp_f32_e32 v232, v232
	v_sub_f32_e32 v233, v233, v190
	s_cmp_lg_u64 s[8:9], 0
	s_cbranch_scc1 .Latt_nd0_3
	s_sub_i32 s100, s11, 1
	s_cmp_eq_u32 s11, 0
	s_cselect_b32 s100, 2, s100
	s_lshl_b32 s101, s100, 14
	s_add_i32 m0, s40, s101
	s_nop 0
	global_load_lds_dwordx4 v178, s[34:35]
.Latt_nd0_3:
	s_waitcnt lgkmcnt(8)
	v_mfma_f32_32x32x16_bf16 v[80:95], v[206:209], v[242:245], v[80:95]
	ds_read_b64_tr_b16 v[206:207], v221 offset:16640
	ds_read_b64_tr_b16 v[208:209], v221 offset:20736
	v_add_f32_e32 v254, v231, v254
	v_exp_f32_e32 v233, v233
	v_sub_f32_e32 v234, v234, v190
	v_add_f32_e32 v254, v232, v254
	s_waitcnt lgkmcnt(8)
	v_mfma_f32_32x32x16_bf16 v[64:79], v[210:213], v[242:245], v[64:79]
	ds_read_b64_tr_b16 v[210:211], v205 offset:24576
	ds_read_b64_tr_b16 v[212:213], v205 offset:28672
	v_exp_f32_e32 v234, v234
	v_sub_f32_e32 v235, v235, v190
	v_add_f32_e32 v254, v233, v254
	v_exp_f32_e32 v235, v235
	s_cmp_lg_u64 s[8:9], 0
	s_cbranch_scc1 .Latt_nd1_3
	s_add_i32 m0, m0, 0x400
	s_nop 0
	global_load_lds_dwordx4 v180, s[34:35]
.Latt_nd1_3:
	s_waitcnt lgkmcnt(8)
	v_mfma_f32_32x32x16_bf16 v[48:63], v[214:217], v[242:245], v[48:63]
	ds_read_b64_tr_b16 v[214:215], v218 offset:24576
	ds_read_b64_tr_b16 v[216:217], v218 offset:28672
	v_sub_f32_e32 v236, v236, v190
	v_add_f32_e32 v254, v234, v254
	v_exp_f32_e32 v236, v236
	v_sub_f32_e32 v237, v237, v190
	s_waitcnt lgkmcnt(8)
	v_mfma_f32_32x32x16_bf16 v[32:47], v[238:241], v[242:245], v[32:47]
	ds_read_b64_tr_b16 v[238:239], v219 offset:24576
	ds_read_b64_tr_b16 v[240:241], v219 offset:28672
	v_add_f32_e32 v254, v235, v254
	v_exp_f32_e32 v237, v237
	v_add_f32_e32 v254, v236, v254
	v_add_f32_e32 v254, v237, v254
	s_cmp_lg_u64 s[8:9], 0
	s_cbranch_scc1 .Latt_nd2_3
	s_lshl_b32 s101, s100, 15
	s_add_i32 m0, s41, s101
	s_add_u32 s100, s34, 0xf00
	s_addc_u32 s101, s35, 0
	global_load_lds_dwordx4 v182, s[100:101]
.Latt_nd2_3:
	s_waitcnt lgkmcnt(8)
	v_mfma_f32_32x32x16_bf16 v[16:31], v[128:131], v[242:245], v[16:31]
	ds_read_b64_tr_b16 v[128:129], v221 offset:24576
	ds_read_b64_tr_b16 v[130:131], v221 offset:28672
	v_cvt_pk_bf16_f32 v250, v230, v231
	v_cvt_pk_bf16_f32 v251, v232, v233
	v_cvt_pk_bf16_f32 v252, v234, v235
	v_cvt_pk_bf16_f32 v253, v236, v237
	v_add_f32_e32 v195, v195, v254
	s_waitcnt lgkmcnt(8)
	v_mfma_f32_32x32x16_bf16 v[0:15], v[206:209], v[242:245], v[0:15]
	ds_read_b64_tr_b16 v[206:207], v205 offset:24832
	ds_read_b64_tr_b16 v[208:209], v205 offset:28928
	s_cmp_lg_u64 s[8:9], 0
	s_cbranch_scc1 .Latt_nd3_3
	s_add_i32 m0, m0, 0x400
	s_nop 0
	global_load_lds_dwordx4 v184, s[100:101]
.Latt_nd3_3:
	s_waitcnt lgkmcnt(8)
	v_mfma_f32_32x32x16_bf16 v[112:127], v[210:213], v[250:253], v[112:127]
	ds_read_b64_tr_b16 v[210:211], v218 offset:24832
	ds_read_b64_tr_b16 v[212:213], v218 offset:28928
	s_waitcnt lgkmcnt(8)
	v_mfma_f32_32x32x16_bf16 v[96:111], v[214:217], v[250:253], v[96:111]
	ds_read_b64_tr_b16 v[214:215], v219 offset:24832
	ds_read_b64_tr_b16 v[216:217], v219 offset:28928
	s_cmp_lg_u64 s[8:9], 0
	s_cbranch_scc1 .Latt_nd4_3
	s_add_i32 m0, m0, 0x400
	s_nop 0
	global_load_lds_dwordx4 v186, s[100:101]
.Latt_nd4_3:
	s_waitcnt lgkmcnt(8)
	v_mfma_f32_32x32x16_bf16 v[80:95], v[238:241], v[250:253], v[80:95]
	ds_read_b64_tr_b16 v[238:239], v221 offset:24832
	ds_read_b64_tr_b16 v[240:241], v221 offset:28928
	s_waitcnt lgkmcnt(8)
	v_mfma_f32_32x32x16_bf16 v[64:79], v[128:131], v[250:253], v[64:79]
	s_cmp_lg_u64 s[8:9], 0
	s_cbranch_scc1 .Latt_nd5_3
	s_add_i32 m0, m0, 0x400
	s_nop 0
	global_load_lds_dwordx4 v188, s[100:101]

.Latt_rs1_3:
	s_waitcnt lgkmcnt(8)
	v_mfma_f32_32x32x16_bf16 v[64:79], v[238:241], v[250:253], v[64:79]
	ds_read_b64_tr_b16 v[238:239], v205 offset:16384
	ds_read_b64_tr_b16 v[240:241], v205 offset:20480
	s_waitcnt lgkmcnt(8)
	v_mfma_f32_32x32x16_bf16 v[48:63], v[128:131], v[250:253], v[48:63]
	ds_read_b64_tr_b16 v[128:129], v218 offset:16384
	ds_read_b64_tr_b16 v[130:131], v218 offset:20480
	s_waitcnt lgkmcnt(8)
	v_mfma_f32_32x32x16_bf16 v[32:47], v[206:209], v[250:253], v[32:47]
	ds_read_b64_tr_b16 v[206:207], v219 offset:16384
	ds_read_b64_tr_b16 v[208:209], v219 offset:20480
	s_waitcnt lgkmcnt(8)
	v_mfma_f32_32x32x16_bf16 v[16:31], v[210:213], v[250:253], v[16:31]
	ds_read_b64_tr_b16 v[210:211], v221 offset:16384
	ds_read_b64_tr_b16 v[212:213], v221 offset:20480
	s_waitcnt lgkmcnt(8)
	v_mfma_f32_32x32x16_bf16 v[0:15], v[214:217], v[250:253], v[0:15]
	ds_read_b64_tr_b16 v[214:215], v205 offset:16640
	ds_read_b64_tr_b16 v[216:217], v205 offset:20736
	s_nop 11
	v_max_f32_e32 v246, v190, v246
	v_sub_f32_e32 v190, v190, v246
	v_exp_f32_e32 v190, v190
	s_nop 0
	v_pk_mul_f32 v[126:127], v[126:127], v[190:191] op_sel_hi:[1,0]
	v_pk_mul_f32 v[124:125], v[124:125], v[190:191] op_sel_hi:[1,0]
	v_pk_mul_f32 v[122:123], v[122:123], v[190:191] op_sel_hi:[1,0]
	v_pk_mul_f32 v[120:121], v[120:121], v[190:191] op_sel_hi:[1,0]
	v_pk_mul_f32 v[118:119], v[118:119], v[190:191] op_sel_hi:[1,0]
	v_pk_mul_f32 v[116:117], v[116:117], v[190:191] op_sel_hi:[1,0]
	v_pk_mul_f32 v[114:115], v[114:115], v[190:191] op_sel_hi:[1,0]
	v_pk_mul_f32 v[112:113], v[112:113], v[190:191] op_sel_hi:[1,0]
	v_pk_mul_f32 v[110:111], v[110:111], v[190:191] op_sel_hi:[1,0]
	v_pk_mul_f32 v[108:109], v[108:109], v[190:191] op_sel_hi:[1,0]
	v_pk_mul_f32 v[106:107], v[106:107], v[190:191] op_sel_hi:[1,0]
	v_pk_mul_f32 v[104:105], v[104:105], v[190:191] op_sel_hi:[1,0]
	v_pk_mul_f32 v[102:103], v[102:103], v[190:191] op_sel_hi:[1,0]
	v_pk_mul_f32 v[100:101], v[100:101], v[190:191] op_sel_hi:[1,0]
	v_pk_mul_f32 v[98:99], v[98:99], v[190:191] op_sel_hi:[1,0]
	v_pk_mul_f32 v[96:97], v[96:97], v[190:191] op_sel_hi:[1,0]
	v_pk_mul_f32 v[94:95], v[94:95], v[190:191] op_sel_hi:[1,0]
	v_pk_mul_f32 v[92:93], v[92:93], v[190:191] op_sel_hi:[1,0]
	v_pk_mul_f32 v[90:91], v[90:91], v[190:191] op_sel_hi:[1,0]
	v_pk_mul_f32 v[88:89], v[88:89], v[190:191] op_sel_hi:[1,0]
	v_pk_mul_f32 v[86:87], v[86:87], v[190:191] op_sel_hi:[1,0]
	v_pk_mul_f32 v[84:85], v[84:85], v[190:191] op_sel_hi:[1,0]
	v_pk_mul_f32 v[82:83], v[82:83], v[190:191] op_sel_hi:[1,0]
	v_pk_mul_f32 v[80:81], v[80:81], v[190:191] op_sel_hi:[1,0]
	v_pk_mul_f32 v[78:79], v[78:79], v[190:191] op_sel_hi:[1,0]
	v_pk_mul_f32 v[76:77], v[76:77], v[190:191] op_sel_hi:[1,0]
	v_pk_mul_f32 v[74:75], v[74:75], v[190:191] op_sel_hi:[1,0]
	v_pk_mul_f32 v[72:73], v[72:73], v[190:191] op_sel_hi:[1,0]
	v_pk_mul_f32 v[70:71], v[70:71], v[190:191] op_sel_hi:[1,0]
	v_pk_mul_f32 v[68:69], v[68:69], v[190:191] op_sel_hi:[1,0]
	v_pk_mul_f32 v[66:67], v[66:67], v[190:191] op_sel_hi:[1,0]
	v_pk_mul_f32 v[64:65], v[64:65], v[190:191] op_sel_hi:[1,0]
	v_pk_mul_f32 v[62:63], v[62:63], v[190:191] op_sel_hi:[1,0]
	v_pk_mul_f32 v[60:61], v[60:61], v[190:191] op_sel_hi:[1,0]
	v_pk_mul_f32 v[58:59], v[58:59], v[190:191] op_sel_hi:[1,0]
	v_pk_mul_f32 v[56:57], v[56:57], v[190:191] op_sel_hi:[1,0]
	v_pk_mul_f32 v[54:55], v[54:55], v[190:191] op_sel_hi:[1,0]
	v_pk_mul_f32 v[52:53], v[52:53], v[190:191] op_sel_hi:[1,0]
	v_pk_mul_f32 v[50:51], v[50:51], v[190:191] op_sel_hi:[1,0]
	v_pk_mul_f32 v[48:49], v[48:49], v[190:191] op_sel_hi:[1,0]
	v_pk_mul_f32 v[46:47], v[46:47], v[190:191] op_sel_hi:[1,0]
	v_pk_mul_f32 v[44:45], v[44:45], v[190:191] op_sel_hi:[1,0]
	v_pk_mul_f32 v[42:43], v[42:43], v[190:191] op_sel_hi:[1,0]
	v_pk_mul_f32 v[40:41], v[40:41], v[190:191] op_sel_hi:[1,0]
	v_pk_mul_f32 v[38:39], v[38:39], v[190:191] op_sel_hi:[1,0]
	v_pk_mul_f32 v[36:37], v[36:37], v[190:191] op_sel_hi:[1,0]
	v_pk_mul_f32 v[34:35], v[34:35], v[190:191] op_sel_hi:[1,0]
	v_pk_mul_f32 v[32:33], v[32:33], v[190:191] op_sel_hi:[1,0]
	v_pk_mul_f32 v[30:31], v[30:31], v[190:191] op_sel_hi:[1,0]
	v_pk_mul_f32 v[28:29], v[28:29], v[190:191] op_sel_hi:[1,0]
	v_pk_mul_f32 v[26:27], v[26:27], v[190:191] op_sel_hi:[1,0]
	v_pk_mul_f32 v[24:25], v[24:25], v[190:191] op_sel_hi:[1,0]
	v_pk_mul_f32 v[22:23], v[22:23], v[190:191] op_sel_hi:[1,0]
	v_pk_mul_f32 v[20:21], v[20:21], v[190:191] op_sel_hi:[1,0]
	v_pk_mul_f32 v[18:19], v[18:19], v[190:191] op_sel_hi:[1,0]
	v_pk_mul_f32 v[16:17], v[16:17], v[190:191] op_sel_hi:[1,0]
	v_pk_mul_f32 v[14:15], v[14:15], v[190:191] op_sel_hi:[1,0]
	v_pk_mul_f32 v[12:13], v[12:13], v[190:191] op_sel_hi:[1,0]
	v_pk_mul_f32 v[10:11], v[10:11], v[190:191] op_sel_hi:[1,0]
	v_pk_mul_f32 v[8:9], v[8:9], v[190:191] op_sel_hi:[1,0]
	v_pk_mul_f32 v[6:7], v[6:7], v[190:191] op_sel_hi:[1,0]
	v_pk_mul_f32 v[4:5], v[4:5], v[190:191] op_sel_hi:[1,0]
	v_pk_mul_f32 v[2:3], v[2:3], v[190:191] op_sel_hi:[1,0]
	v_pk_mul_f32 v[0:1], v[0:1], v[190:191] op_sel_hi:[1,0]
	v_mul_f32_e32 v195, v195, v190
	v_mov_b32_e32 v190, v246
	v_sub_f32_e32 v222, v222, v190
	v_exp_f32_e32 v222, v222
	v_sub_f32_e32 v223, v223, v190
	v_exp_f32_e32 v223, v223
	v_sub_f32_e32 v224, v224, v190
	v_add_f32_e32 v254, 0, v222
	v_exp_f32_e32 v224, v224
	v_sub_f32_e32 v225, v225, v190
	v_add_f32_e32 v254, v223, v254
	v_exp_f32_e32 v225, v225
	v_sub_f32_e32 v226, v226, v190
	v_add_f32_e32 v254, v224, v254
	v_exp_f32_e32 v226, v226
	v_sub_f32_e32 v227, v227, v190
	v_add_f32_e32 v254, v225, v254
	v_exp_f32_e32 v227, v227
	v_sub_f32_e32 v228, v228, v190
	v_add_f32_e32 v254, v226, v254
	v_exp_f32_e32 v228, v228
	v_sub_f32_e32 v229, v229, v190
	v_add_f32_e32 v254, v227, v254
	v_exp_f32_e32 v229, v229
	v_sub_f32_e32 v230, v230, v190
	v_add_f32_e32 v254, v228, v254
	v_exp_f32_e32 v230, v230
	v_sub_f32_e32 v231, v231, v190
	v_add_f32_e32 v254, v229, v254
	v_exp_f32_e32 v231, v231
	v_sub_f32_e32 v232, v232, v190
	v_add_f32_e32 v254, v230, v254
	v_exp_f32_e32 v232, v232
	v_sub_f32_e32 v233, v233, v190
	v_add_f32_e32 v254, v231, v254
	v_exp_f32_e32 v233, v233
	v_sub_f32_e32 v234, v234, v190
	v_add_f32_e32 v254, v232, v254
	v_exp_f32_e32 v234, v234
	v_sub_f32_e32 v235, v235, v190
	v_add_f32_e32 v254, v233, v254
	v_exp_f32_e32 v235, v235
	v_sub_f32_e32 v236, v236, v190
	v_add_f32_e32 v254, v234, v254
	v_exp_f32_e32 v236, v236
	v_sub_f32_e32 v237, v237, v190
	v_add_f32_e32 v254, v235, v254
	v_exp_f32_e32 v237, v237
	v_add_f32_e32 v254, v236, v254
	v_add_f32_e32 v254, v237, v254
	v_cvt_pk_bf16_f32 v242, v222, v223
	v_cvt_pk_bf16_f32 v243, v224, v225
	v_cvt_pk_bf16_f32 v244, v226, v227
	v_cvt_pk_bf16_f32 v245, v228, v229
	v_cvt_pk_bf16_f32 v250, v230, v231
	v_cvt_pk_bf16_f32 v251, v232, v233
	v_cvt_pk_bf16_f32 v252, v234, v235
	v_cvt_pk_bf16_f32 v253, v236, v237
	v_add_f32_e32 v195, v195, v254
	s_nop 1
	s_waitcnt lgkmcnt(8)
	v_mfma_f32_32x32x16_bf16 v[112:127], v[238:241], v[242:245], v[112:127]
	ds_read_b64_tr_b16 v[238:239], v218 offset:16640
	ds_read_b64_tr_b16 v[240:241], v218 offset:20736
	s_waitcnt lgkmcnt(8)
	v_mfma_f32_32x32x16_bf16 v[96:111], v[128:131], v[242:245], v[96:111]
	ds_read_b64_tr_b16 v[222:223], v219 offset:16640
	ds_read_b64_tr_b16 v[224:225], v219 offset:20736
	s_cmp_lg_u64 s[8:9], 0
	s_cbranch_scc1 .Latt_ndr0_3
	s_sub_i32 s100, s11, 1
	s_cmp_eq_u32 s11, 0
	s_cselect_b32 s100, 2, s100
	s_lshl_b32 s101, s100, 14
	s_add_i32 m0, s40, s101
	s_nop 0
	global_load_lds_dwordx4 v178, s[34:35]
.Latt_ndr0_3:
	s_waitcnt lgkmcnt(8)
	v_mfma_f32_32x32x16_bf16 v[80:95], v[206:209], v[242:245], v[80:95]
	ds_read_b64_tr_b16 v[206:207], v221 offset:16640
	ds_read_b64_tr_b16 v[208:209], v221 offset:20736
	s_waitcnt lgkmcnt(8)
	v_mfma_f32_32x32x16_bf16 v[64:79], v[210:213], v[242:245], v[64:79]
	ds_read_b64_tr_b16 v[210:211], v205 offset:24576
	ds_read_b64_tr_b16 v[212:213], v205 offset:28672
	s_cmp_lg_u64 s[8:9], 0
	s_cbranch_scc1 .Latt_ndr1_3
	s_add_i32 m0, m0, 0x400
	s_nop 0
	global_load_lds_dwordx4 v180, s[34:35]

.Latt_ndr2_3:
	s_waitcnt lgkmcnt(8)
	v_mfma_f32_32x32x16_bf16 v[16:31], v[222:225], v[242:245], v[16:31]
	ds_read_b64_tr_b16 v[222:223], v221 offset:24576
	ds_read_b64_tr_b16 v[224:225], v221 offset:28672
	s_waitcnt lgkmcnt(8)
	v_mfma_f32_32x32x16_bf16 v[0:15], v[206:209], v[242:245], v[0:15]
	ds_read_b64_tr_b16 v[206:207], v205 offset:24832
	ds_read_b64_tr_b16 v[208:209], v205 offset:28928
	s_cmp_lg_u64 s[8:9], 0
	s_cbranch_scc1 .Latt_ndr3_3
	s_add_i32 m0, m0, 0x400
	s_nop 0
	global_load_lds_dwordx4 v184, s[100:101]

.Latt_ndr4_3:
	s_waitcnt lgkmcnt(8)
	v_mfma_f32_32x32x16_bf16 v[80:95], v[238:241], v[250:253], v[80:95]
	ds_read_b64_tr_b16 v[238:239], v221 offset:24832
	ds_read_b64_tr_b16 v[240:241], v221 offset:28928
	s_waitcnt lgkmcnt(8)
	v_mfma_f32_32x32x16_bf16 v[64:79], v[222:225], v[250:253], v[64:79]
	s_cmp_lg_u64 s[8:9], 0
	s_cbranch_scc1 .Latt_ndr5_3
	s_add_i32 m0, m0, 0x400
	s_nop 0
	global_load_lds_dwordx4 v188, s[100:101]

.LBB0_1801:
	s_cmp_gt_i32 s39, s72
	s_cbranch_scc1 .LBB0_1812
	s_add_i32 s100, s39, 63
	s_cmp_le_i32 s100, s71
	s_cbranch_scc0 .Latt_slow_4
	s_lshl_b32 s98, s76, 14
	s_lshl_b32 s99, s76, 15
	s_add_i32 s99, s99, 0xc000
	v_add_u32_e32 v206, s98, v194
	ds_read_b128 v[206:209], v206
	v_add_u32_e32 v210, s98, v195
	ds_read_b128 v[210:213], v210
	v_add_u32_e32 v214, s98, v196
	ds_read_b128 v[214:217], v214
	v_add_u32_e32 v238, s98, v197
	ds_read_b128 v[238:241], v238
	v_add_u32_e32 v242, s98, v198
	ds_read_b128 v[242:245], v242
	v_add_u32_e32 v250, s98, v199
	ds_read_b128 v[250:253], v250
	v_add_u32_e32 v222, s98, v200
	ds_read_b128 v[222:225], v222
	v_add_u32_e32 v226, s98, v201
	ds_read_b128 v[226:229], v226
	v_bfe_u32 v246, v203, 2, 2
	v_bfe_u32 v247, v203, 5, 1
	v_lshl_or_b32 v247, v247, 2, v246
	v_and_b32_e32 v249, 3, v203
	v_and_b32_e32 v254, 16, v203
	v_lshl_or_b32 v249, v249, 2, v254
	v_lshlrev_b32_e32 v249, 1, v249
	v_lshl_add_u32 v247, v247, 9, v249
	v_add_u32_e32 v247, s99, v247
	v_lshlrev_b32_e32 v246, 6, v246
	v_add_u32_e32 v205, v247, v246
	v_xor_b32_e32 v249, 64, v246
	v_add_u32_e32 v218, v247, v249
	v_xor_b32_e32 v249, 0x80, v246
	v_add_u32_e32 v219, v247, v249
	v_xor_b32_e32 v249, 0xc0, v246
	v_add_u32_e32 v221, v247, v249
	s_waitcnt lgkmcnt(7)
	v_mfma_f32_32x32x16_bf16 v[128:143], v[206:209], v[144:147], 0
	v_add_u32_e32 v206, s98, v194
	ds_read_b128 v[206:209], v206 offset:8192
	s_waitcnt lgkmcnt(7)
	v_mfma_f32_32x32x16_bf16 v[128:143], v[210:213], v[148:151], v[128:143]
	v_add_u32_e32 v210, s98, v195
	ds_read_b128 v[210:213], v210 offset:8192
	s_waitcnt lgkmcnt(7)
	v_mfma_f32_32x32x16_bf16 v[128:143], v[214:217], v[152:155], v[128:143]
	v_add_u32_e32 v214, s98, v196
	ds_read_b128 v[214:217], v214 offset:8192
	s_waitcnt lgkmcnt(7)
	v_mfma_f32_32x32x16_bf16 v[128:143], v[238:241], v[156:159], v[128:143]
	v_add_u32_e32 v238, s98, v197
	ds_read_b128 v[238:241], v238 offset:8192
	s_waitcnt lgkmcnt(7)
	v_mfma_f32_32x32x16_bf16 v[128:143], v[242:245], v[160:163], v[128:143]
	s_waitcnt lgkmcnt(6)
	v_mfma_f32_32x32x16_bf16 v[128:143], v[250:253], v[164:167], v[128:143]
	s_waitcnt lgkmcnt(5)
	v_mfma_f32_32x32x16_bf16 v[128:143], v[222:225], v[168:171], v[128:143]
	s_waitcnt lgkmcnt(4)
	v_mfma_f32_32x32x16_bf16 v[128:143], v[226:229], v[172:175], v[128:143]
	s_waitcnt lgkmcnt(3)
	v_mfma_f32_32x32x16_bf16 v[222:237], v[206:209], v[144:147], 0
	v_add_u32_e32 v206, s98, v198
	ds_read_b128 v[206:209], v206 offset:8192
	s_nop 7
	v_max3_f32 v246, v128, v129, v130
	v_max3_f32 v247, v131, v132, v133
	v_max3_f32 v246, v246, v134, v135
	v_max3_f32 v247, v247, v136, v137
	v_max3_f32 v246, v246, v138, v139
	v_max3_f32 v247, v247, v140, v141
	v_max3_f32 v246, v246, v142, v143
	s_waitcnt lgkmcnt(3)
	v_mfma_f32_32x32x16_bf16 v[222:237], v[210:213], v[148:151], v[222:237]
	v_add_u32_e32 v210, s98, v199
	ds_read_b128 v[210:213], v210 offset:8192
	v_max_f32_e32 v246, v246, v247
	v_mov_b32_e32 v247, v246
	v_add_f32_e32 v249, 0x41000000, v190
	s_nop 1
	v_permlane32_swap_b32_e32 v246, v247
	v_max_f32_e32 v246, v246, v247
	v_cmp_gt_f32_e32 vcc, v246, v249
	s_cbranch_vccz .Latt_nr0_4
	v_max_f32_e32 v246, v190, v246
	v_sub_f32_e32 v190, v190, v246
	v_exp_f32_e32 v190, v190
	s_nop 0
	v_pk_mul_f32 v[126:127], v[126:127], v[190:191] op_sel_hi:[1,0]
	v_pk_mul_f32 v[124:125], v[124:125], v[190:191] op_sel_hi:[1,0]
	v_pk_mul_f32 v[122:123], v[122:123], v[190:191] op_sel_hi:[1,0]
	v_pk_mul_f32 v[120:121], v[120:121], v[190:191] op_sel_hi:[1,0]
	v_pk_mul_f32 v[118:119], v[118:119], v[190:191] op_sel_hi:[1,0]
	v_pk_mul_f32 v[116:117], v[116:117], v[190:191] op_sel_hi:[1,0]
	v_pk_mul_f32 v[114:115], v[114:115], v[190:191] op_sel_hi:[1,0]
	v_pk_mul_f32 v[112:113], v[112:113], v[190:191] op_sel_hi:[1,0]
	v_pk_mul_f32 v[110:111], v[110:111], v[190:191] op_sel_hi:[1,0]
	v_pk_mul_f32 v[108:109], v[108:109], v[190:191] op_sel_hi:[1,0]
	v_pk_mul_f32 v[106:107], v[106:107], v[190:191] op_sel_hi:[1,0]
	v_pk_mul_f32 v[104:105], v[104:105], v[190:191] op_sel_hi:[1,0]
	v_pk_mul_f32 v[102:103], v[102:103], v[190:191] op_sel_hi:[1,0]
	v_pk_mul_f32 v[100:101], v[100:101], v[190:191] op_sel_hi:[1,0]
	v_pk_mul_f32 v[98:99], v[98:99], v[190:191] op_sel_hi:[1,0]
	v_pk_mul_f32 v[96:97], v[96:97], v[190:191] op_sel_hi:[1,0]
	v_pk_mul_f32 v[94:95], v[94:95], v[190:191] op_sel_hi:[1,0]
	v_pk_mul_f32 v[92:93], v[92:93], v[190:191] op_sel_hi:[1,0]
	v_pk_mul_f32 v[90:91], v[90:91], v[190:191] op_sel_hi:[1,0]
	v_pk_mul_f32 v[88:89], v[88:89], v[190:191] op_sel_hi:[1,0]
	v_pk_mul_f32 v[86:87], v[86:87], v[190:191] op_sel_hi:[1,0]
	v_pk_mul_f32 v[84:85], v[84:85], v[190:191] op_sel_hi:[1,0]
	v_pk_mul_f32 v[82:83], v[82:83], v[190:191] op_sel_hi:[1,0]
	v_pk_mul_f32 v[80:81], v[80:81], v[190:191] op_sel_hi:[1,0]
	v_pk_mul_f32 v[78:79], v[78:79], v[190:191] op_sel_hi:[1,0]
	v_pk_mul_f32 v[76:77], v[76:77], v[190:191] op_sel_hi:[1,0]
	v_pk_mul_f32 v[74:75], v[74:75], v[190:191] op_sel_hi:[1,0]
	v_pk_mul_f32 v[72:73], v[72:73], v[190:191] op_sel_hi:[1,0]
	v_pk_mul_f32 v[70:71], v[70:71], v[190:191] op_sel_hi:[1,0]
	v_pk_mul_f32 v[68:69], v[68:69], v[190:191] op_sel_hi:[1,0]
	v_pk_mul_f32 v[66:67], v[66:67], v[190:191] op_sel_hi:[1,0]
	v_pk_mul_f32 v[64:65], v[64:65], v[190:191] op_sel_hi:[1,0]
	v_pk_mul_f32 v[62:63], v[62:63], v[190:191] op_sel_hi:[1,0]
	v_pk_mul_f32 v[60:61], v[60:61], v[190:191] op_sel_hi:[1,0]
	v_pk_mul_f32 v[58:59], v[58:59], v[190:191] op_sel_hi:[1,0]
	v_pk_mul_f32 v[56:57], v[56:57], v[190:191] op_sel_hi:[1,0]
	v_pk_mul_f32 v[54:55], v[54:55], v[190:191] op_sel_hi:[1,0]
	v_pk_mul_f32 v[52:53], v[52:53], v[190:191] op_sel_hi:[1,0]
	v_pk_mul_f32 v[50:51], v[50:51], v[190:191] op_sel_hi:[1,0]
	v_pk_mul_f32 v[48:49], v[48:49], v[190:191] op_sel_hi:[1,0]
	v_pk_mul_f32 v[46:47], v[46:47], v[190:191] op_sel_hi:[1,0]
	v_pk_mul_f32 v[44:45], v[44:45], v[190:191] op_sel_hi:[1,0]
	v_pk_mul_f32 v[42:43], v[42:43], v[190:191] op_sel_hi:[1,0]
	v_pk_mul_f32 v[40:41], v[40:41], v[190:191] op_sel_hi:[1,0]
	v_pk_mul_f32 v[38:39], v[38:39], v[190:191] op_sel_hi:[1,0]
	v_pk_mul_f32 v[36:37], v[36:37], v[190:191] op_sel_hi:[1,0]
	v_pk_mul_f32 v[34:35], v[34:35], v[190:191] op_sel_hi:[1,0]
	v_pk_mul_f32 v[32:33], v[32:33], v[190:191] op_sel_hi:[1,0]
	v_pk_mul_f32 v[30:31], v[30:31], v[190:191] op_sel_hi:[1,0]
	v_pk_mul_f32 v[28:29], v[28:29], v[190:191] op_sel_hi:[1,0]
	v_pk_mul_f32 v[26:27], v[26:27], v[190:191] op_sel_hi:[1,0]
	v_pk_mul_f32 v[24:25], v[24:25], v[190:191] op_sel_hi:[1,0]
	v_pk_mul_f32 v[22:23], v[22:23], v[190:191] op_sel_hi:[1,0]
	v_pk_mul_f32 v[20:21], v[20:21], v[190:191] op_sel_hi:[1,0]
	v_pk_mul_f32 v[18:19], v[18:19], v[190:191] op_sel_hi:[1,0]
	v_pk_mul_f32 v[16:17], v[16:17], v[190:191] op_sel_hi:[1,0]
	v_pk_mul_f32 v[14:15], v[14:15], v[190:191] op_sel_hi:[1,0]
	v_pk_mul_f32 v[12:13], v[12:13], v[190:191] op_sel_hi:[1,0]
	v_pk_mul_f32 v[10:11], v[10:11], v[190:191] op_sel_hi:[1,0]
	v_pk_mul_f32 v[8:9], v[8:9], v[190:191] op_sel_hi:[1,0]
	v_pk_mul_f32 v[6:7], v[6:7], v[190:191] op_sel_hi:[1,0]
	v_pk_mul_f32 v[4:5], v[4:5], v[190:191] op_sel_hi:[1,0]
	v_pk_mul_f32 v[2:3], v[2:3], v[190:191] op_sel_hi:[1,0]
	v_pk_mul_f32 v[0:1], v[0:1], v[190:191] op_sel_hi:[1,0]
	v_mul_f32_e32 v202, v202, v190
	v_mov_b32_e32 v190, v246
.Latt_nr0_4:
	s_waitcnt lgkmcnt(3)
	v_mfma_f32_32x32x16_bf16 v[222:237], v[214:217], v[152:155], v[222:237]
	v_add_u32_e32 v214, s98, v200
	ds_read_b128 v[214:217], v214 offset:8192
	v_sub_f32_e32 v128, v128, v190
	v_exp_f32_e32 v128, v128
	v_sub_f32_e32 v129, v129, v190
	v_exp_f32_e32 v129, v129
	v_sub_f32_e32 v130, v130, v190
	s_waitcnt lgkmcnt(3)
	v_mfma_f32_32x32x16_bf16 v[222:237], v[238:241], v[156:159], v[222:237]
	v_add_u32_e32 v238, s98, v201
	ds_read_b128 v[238:241], v238 offset:8192
	v_add_f32_e32 v254, 0, v128
	v_exp_f32_e32 v130, v130
	v_sub_f32_e32 v131, v131, v190
	v_add_f32_e32 v254, v129, v254
	v_exp_f32_e32 v131, v131
	s_waitcnt lgkmcnt(3)
	v_mfma_f32_32x32x16_bf16 v[222:237], v[206:209], v[160:163], v[222:237]
	ds_read_b64_tr_b16 v[206:207], v205
	ds_read_b64_tr_b16 v[208:209], v205 offset:4096
	v_sub_f32_e32 v132, v132, v190
	v_add_f32_e32 v254, v130, v254
	v_exp_f32_e32 v132, v132
	v_sub_f32_e32 v133, v133, v190
	v_add_f32_e32 v254, v131, v254
	s_waitcnt lgkmcnt(4)
	v_mfma_f32_32x32x16_bf16 v[222:237], v[210:213], v[164:167], v[222:237]
	ds_read_b64_tr_b16 v[210:211], v218
	ds_read_b64_tr_b16 v[212:213], v218 offset:4096
	v_exp_f32_e32 v133, v133
	v_sub_f32_e32 v134, v134, v190
	v_add_f32_e32 v254, v132, v254
	v_exp_f32_e32 v134, v134
	s_waitcnt lgkmcnt(5)
	v_mfma_f32_32x32x16_bf16 v[222:237], v[214:217], v[168:171], v[222:237]
	ds_read_b64_tr_b16 v[214:215], v219
	ds_read_b64_tr_b16 v[216:217], v219 offset:4096
	v_sub_f32_e32 v135, v135, v190
	v_add_f32_e32 v254, v133, v254
	v_exp_f32_e32 v135, v135
	s_nop 0
	s_waitcnt lgkmcnt(6)
	v_mfma_f32_32x32x16_bf16 v[222:237], v[238:241], v[172:175], v[222:237]
	ds_read_b64_tr_b16 v[238:239], v221
	ds_read_b64_tr_b16 v[240:241], v221 offset:4096
	v_cvt_pk_bf16_f32 v242, v128, v129
	v_cvt_pk_bf16_f32 v243, v130, v131
	v_cvt_pk_bf16_f32 v244, v132, v133
	v_cvt_pk_bf16_f32 v245, v134, v135
	s_nop 1
	s_waitcnt lgkmcnt(6)
	v_mfma_f32_32x32x16_bf16 v[112:127], v[206:209], v[242:245], v[112:127]
	ds_read_b64_tr_b16 v[206:207], v205 offset:256
	ds_read_b64_tr_b16 v[208:209], v205 offset:4352
	v_sub_f32_e32 v136, v136, v190
	v_add_f32_e32 v254, v134, v254
	v_exp_f32_e32 v136, v136
	v_sub_f32_e32 v137, v137, v190
	v_add_f32_e32 v254, v135, v254
	s_waitcnt lgkmcnt(6)
	v_mfma_f32_32x32x16_bf16 v[96:111], v[210:213], v[242:245], v[96:111]
	ds_read_b64_tr_b16 v[210:211], v218 offset:256
	ds_read_b64_tr_b16 v[212:213], v218 offset:4352
	v_exp_f32_e32 v137, v137
	v_sub_f32_e32 v138, v138, v190
	v_add_f32_e32 v254, v136, v254
	v_exp_f32_e32 v138, v138
	v_sub_f32_e32 v139, v139, v190
	s_waitcnt lgkmcnt(6)
	v_mfma_f32_32x32x16_bf16 v[80:95], v[214:217], v[242:245], v[80:95]
	ds_read_b64_tr_b16 v[214:215], v219 offset:256
	ds_read_b64_tr_b16 v[216:217], v219 offset:4352
	v_add_f32_e32 v254, v137, v254
	v_exp_f32_e32 v139, v139
	v_sub_f32_e32 v140, v140, v190
	v_add_f32_e32 v254, v138, v254
	s_waitcnt lgkmcnt(6)
	v_mfma_f32_32x32x16_bf16 v[64:79], v[238:241], v[242:245], v[64:79]
	ds_read_b64_tr_b16 v[238:239], v221 offset:256
	ds_read_b64_tr_b16 v[240:241], v221 offset:4352
	v_exp_f32_e32 v140, v140
	v_sub_f32_e32 v141, v141, v190
	v_add_f32_e32 v254, v139, v254
	v_exp_f32_e32 v141, v141
	s_waitcnt lgkmcnt(6)
	v_mfma_f32_32x32x16_bf16 v[48:63], v[206:209], v[242:245], v[48:63]
	ds_read_b64_tr_b16 v[206:207], v205 offset:8192
	ds_read_b64_tr_b16 v[208:209], v205 offset:12288
	v_sub_f32_e32 v142, v142, v190
	v_add_f32_e32 v254, v140, v254
	v_exp_f32_e32 v142, v142
	v_sub_f32_e32 v143, v143, v190
	s_waitcnt lgkmcnt(6)
	v_mfma_f32_32x32x16_bf16 v[32:47], v[210:213], v[242:245], v[32:47]
	ds_read_b64_tr_b16 v[210:211], v218 offset:8192
	ds_read_b64_tr_b16 v[212:213], v218 offset:12288
	v_add_f32_e32 v254, v141, v254
	v_exp_f32_e32 v143, v143
	v_add_f32_e32 v254, v142, v254
	v_add_f32_e32 v254, v143, v254
	s_waitcnt lgkmcnt(6)
	v_mfma_f32_32x32x16_bf16 v[16:31], v[214:217], v[242:245], v[16:31]
	ds_read_b64_tr_b16 v[214:215], v219 offset:8192
	ds_read_b64_tr_b16 v[216:217], v219 offset:12288
	v_cvt_pk_bf16_f32 v250, v136, v137
	v_cvt_pk_bf16_f32 v251, v138, v139
	v_cvt_pk_bf16_f32 v252, v140, v141
	v_cvt_pk_bf16_f32 v253, v142, v143
	v_add_f32_e32 v202, v202, v254
	s_waitcnt lgkmcnt(6)
	v_mfma_f32_32x32x16_bf16 v[0:15], v[238:241], v[242:245], v[0:15]
	ds_read_b64_tr_b16 v[238:239], v221 offset:8192
	ds_read_b64_tr_b16 v[240:241], v221 offset:12288
	ds_read_b64_tr_b16 v[128:129], v205 offset:8448
	ds_read_b64_tr_b16 v[130:131], v205 offset:12544
	s_waitcnt lgkmcnt(8)
	v_mfma_f32_32x32x16_bf16 v[112:127], v[206:209], v[250:253], v[112:127]
	ds_read_b64_tr_b16 v[206:207], v218 offset:8448
	ds_read_b64_tr_b16 v[208:209], v218 offset:12544
	v_max3_f32 v246, v222, v223, v224
	v_max3_f32 v247, v225, v226, v227
	v_max3_f32 v246, v246, v228, v229
	v_max3_f32 v247, v247, v230, v231
	v_max3_f32 v246, v246, v232, v233
	v_max3_f32 v247, v247, v234, v235
	s_waitcnt lgkmcnt(8)
	v_mfma_f32_32x32x16_bf16 v[96:111], v[210:213], v[250:253], v[96:111]
	ds_read_b64_tr_b16 v[210:211], v219 offset:8448
	ds_read_b64_tr_b16 v[212:213], v219 offset:12544
	v_max3_f32 v246, v246, v236, v237
	v_max_f32_e32 v246, v246, v247
	v_mov_b32_e32 v247, v246
	v_add_f32_e32 v249, 0x41000000, v190
	s_nop 1
	s_waitcnt lgkmcnt(8)
	v_mfma_f32_32x32x16_bf16 v[80:95], v[214:217], v[250:253], v[80:95]
	ds_read_b64_tr_b16 v[214:215], v221 offset:8448
	ds_read_b64_tr_b16 v[216:217], v221 offset:12544
	v_permlane32_swap_b32_e32 v246, v247
	v_max_f32_e32 v246, v246, v247
	v_cmp_gt_f32_e32 vcc, v246, v249
	s_cbranch_vccnz .Latt_rs1_4
	s_waitcnt lgkmcnt(8)
	v_mfma_f32_32x32x16_bf16 v[64:79], v[238:241], v[250:253], v[64:79]
	ds_read_b64_tr_b16 v[238:239], v205 offset:16384
	ds_read_b64_tr_b16 v[240:241], v205 offset:20480
	v_sub_f32_e32 v222, v222, v190
	v_exp_f32_e32 v222, v222
	v_sub_f32_e32 v223, v223, v190
	v_exp_f32_e32 v223, v223
	v_sub_f32_e32 v224, v224, v190
	v_add_f32_e32 v254, 0, v222
	s_waitcnt lgkmcnt(8)
	v_mfma_f32_32x32x16_bf16 v[48:63], v[128:131], v[250:253], v[48:63]
	ds_read_b64_tr_b16 v[128:129], v218 offset:16384
	ds_read_b64_tr_b16 v[130:131], v218 offset:20480
	v_exp_f32_e32 v224, v224
	v_sub_f32_e32 v225, v225, v190
	v_add_f32_e32 v254, v223, v254
	v_exp_f32_e32 v225, v225
	v_sub_f32_e32 v226, v226, v190
	v_add_f32_e32 v254, v224, v254
	s_waitcnt lgkmcnt(8)
	v_mfma_f32_32x32x16_bf16 v[32:47], v[206:209], v[250:253], v[32:47]
	ds_read_b64_tr_b16 v[206:207], v219 offset:16384
	ds_read_b64_tr_b16 v[208:209], v219 offset:20480
	v_exp_f32_e32 v226, v226
	v_sub_f32_e32 v227, v227, v190
	v_add_f32_e32 v254, v225, v254
	v_exp_f32_e32 v227, v227
	v_sub_f32_e32 v228, v228, v190
	s_waitcnt lgkmcnt(8)
	v_mfma_f32_32x32x16_bf16 v[16:31], v[210:213], v[250:253], v[16:31]
	ds_read_b64_tr_b16 v[210:211], v221 offset:16384
	ds_read_b64_tr_b16 v[212:213], v221 offset:20480
	v_add_f32_e32 v254, v226, v254
	v_exp_f32_e32 v228, v228
	v_sub_f32_e32 v229, v229, v190
	v_add_f32_e32 v254, v227, v254
	v_exp_f32_e32 v229, v229
	s_waitcnt lgkmcnt(8)
	v_mfma_f32_32x32x16_bf16 v[0:15], v[214:217], v[250:253], v[0:15]
	ds_read_b64_tr_b16 v[214:215], v205 offset:16640
	ds_read_b64_tr_b16 v[216:217], v205 offset:20736
	s_nop 0
	v_cvt_pk_bf16_f32 v242, v222, v223
	v_cvt_pk_bf16_f32 v243, v224, v225
	v_cvt_pk_bf16_f32 v244, v226, v227
	v_cvt_pk_bf16_f32 v245, v228, v229
	s_nop 1
	s_waitcnt lgkmcnt(8)
	v_mfma_f32_32x32x16_bf16 v[112:127], v[238:241], v[242:245], v[112:127]
	ds_read_b64_tr_b16 v[238:239], v218 offset:16640
	ds_read_b64_tr_b16 v[240:241], v218 offset:20736
	v_sub_f32_e32 v230, v230, v190
	v_add_f32_e32 v254, v228, v254
	v_exp_f32_e32 v230, v230
	v_sub_f32_e32 v231, v231, v190
	v_add_f32_e32 v254, v229, v254
	s_waitcnt lgkmcnt(8)
	v_mfma_f32_32x32x16_bf16 v[96:111], v[128:131], v[242:245], v[96:111]
	ds_read_b64_tr_b16 v[128:129], v219 offset:16640
	ds_read_b64_tr_b16 v[130:131], v219 offset:20736
	v_exp_f32_e32 v231, v231
	v_sub_f32_e32 v232, v232, v190
	v_add_f32_e32 v254, v230, v254
	v_exp_f32_e32 v232, v232
	v_sub_f32_e32 v233, v233, v190
	s_cmp_lg_u64 s[18:19], 0
	s_cbranch_scc1 .Latt_nd0_4
	s_sub_i32 s100, s76, 1
	s_cmp_eq_u32 s76, 0
	s_cselect_b32 s100, 2, s100
	s_lshl_b32 s101, s100, 14
	s_add_i32 m0, s73, s101
	s_nop 0
	global_load_lds_dwordx4 v178, s[14:15]

.Latt_nd1_4:
	s_waitcnt lgkmcnt(8)
	v_mfma_f32_32x32x16_bf16 v[48:63], v[214:217], v[242:245], v[48:63]
	ds_read_b64_tr_b16 v[214:215], v218 offset:24576
	ds_read_b64_tr_b16 v[216:217], v218 offset:28672
	v_sub_f32_e32 v236, v236, v190
	v_add_f32_e32 v254, v234, v254
	v_exp_f32_e32 v236, v236
	v_sub_f32_e32 v237, v237, v190
	s_waitcnt lgkmcnt(8)
	v_mfma_f32_32x32x16_bf16 v[32:47], v[238:241], v[242:245], v[32:47]
	ds_read_b64_tr_b16 v[238:239], v219 offset:24576
	ds_read_b64_tr_b16 v[240:241], v219 offset:28672
	v_add_f32_e32 v254, v235, v254
	v_exp_f32_e32 v237, v237
	v_add_f32_e32 v254, v236, v254
	v_add_f32_e32 v254, v237, v254
	s_cmp_lg_u64 s[18:19], 0
	s_cbranch_scc1 .Latt_nd2_4
	s_lshl_b32 s101, s100, 15
	s_add_i32 m0, s74, s101
	s_add_u32 s100, s14, 0x1000
	s_addc_u32 s101, s15, 0
	global_load_lds_dwordx4 v182, s[100:101]

.Latt_rs1_4:
	s_waitcnt lgkmcnt(8)
	v_mfma_f32_32x32x16_bf16 v[64:79], v[238:241], v[250:253], v[64:79]
	ds_read_b64_tr_b16 v[238:239], v205 offset:16384
	ds_read_b64_tr_b16 v[240:241], v205 offset:20480
	s_waitcnt lgkmcnt(8)
	v_mfma_f32_32x32x16_bf16 v[48:63], v[128:131], v[250:253], v[48:63]
	ds_read_b64_tr_b16 v[128:129], v218 offset:16384
	ds_read_b64_tr_b16 v[130:131], v218 offset:20480
	s_waitcnt lgkmcnt(8)
	v_mfma_f32_32x32x16_bf16 v[32:47], v[206:209], v[250:253], v[32:47]
	ds_read_b64_tr_b16 v[206:207], v219 offset:16384
	ds_read_b64_tr_b16 v[208:209], v219 offset:20480
	s_waitcnt lgkmcnt(8)
	v_mfma_f32_32x32x16_bf16 v[16:31], v[210:213], v[250:253], v[16:31]
	ds_read_b64_tr_b16 v[210:211], v221 offset:16384
	ds_read_b64_tr_b16 v[212:213], v221 offset:20480
	s_waitcnt lgkmcnt(8)
	v_mfma_f32_32x32x16_bf16 v[0:15], v[214:217], v[250:253], v[0:15]
	ds_read_b64_tr_b16 v[214:215], v205 offset:16640
	ds_read_b64_tr_b16 v[216:217], v205 offset:20736
	s_nop 11
	v_max_f32_e32 v246, v190, v246
	v_sub_f32_e32 v190, v190, v246
	v_exp_f32_e32 v190, v190
	s_nop 0
	v_pk_mul_f32 v[126:127], v[126:127], v[190:191] op_sel_hi:[1,0]
	v_pk_mul_f32 v[124:125], v[124:125], v[190:191] op_sel_hi:[1,0]
	v_pk_mul_f32 v[122:123], v[122:123], v[190:191] op_sel_hi:[1,0]
	v_pk_mul_f32 v[120:121], v[120:121], v[190:191] op_sel_hi:[1,0]
	v_pk_mul_f32 v[118:119], v[118:119], v[190:191] op_sel_hi:[1,0]
	v_pk_mul_f32 v[116:117], v[116:117], v[190:191] op_sel_hi:[1,0]
	v_pk_mul_f32 v[114:115], v[114:115], v[190:191] op_sel_hi:[1,0]
	v_pk_mul_f32 v[112:113], v[112:113], v[190:191] op_sel_hi:[1,0]
	v_pk_mul_f32 v[110:111], v[110:111], v[190:191] op_sel_hi:[1,0]
	v_pk_mul_f32 v[108:109], v[108:109], v[190:191] op_sel_hi:[1,0]
	v_pk_mul_f32 v[106:107], v[106:107], v[190:191] op_sel_hi:[1,0]
	v_pk_mul_f32 v[104:105], v[104:105], v[190:191] op_sel_hi:[1,0]
	v_pk_mul_f32 v[102:103], v[102:103], v[190:191] op_sel_hi:[1,0]
	v_pk_mul_f32 v[100:101], v[100:101], v[190:191] op_sel_hi:[1,0]
	v_pk_mul_f32 v[98:99], v[98:99], v[190:191] op_sel_hi:[1,0]
	v_pk_mul_f32 v[96:97], v[96:97], v[190:191] op_sel_hi:[1,0]
	v_pk_mul_f32 v[94:95], v[94:95], v[190:191] op_sel_hi:[1,0]
	v_pk_mul_f32 v[92:93], v[92:93], v[190:191] op_sel_hi:[1,0]
	v_pk_mul_f32 v[90:91], v[90:91], v[190:191] op_sel_hi:[1,0]
	v_pk_mul_f32 v[88:89], v[88:89], v[190:191] op_sel_hi:[1,0]
	v_pk_mul_f32 v[86:87], v[86:87], v[190:191] op_sel_hi:[1,0]
	v_pk_mul_f32 v[84:85], v[84:85], v[190:191] op_sel_hi:[1,0]
	v_pk_mul_f32 v[82:83], v[82:83], v[190:191] op_sel_hi:[1,0]
	v_pk_mul_f32 v[80:81], v[80:81], v[190:191] op_sel_hi:[1,0]
	v_pk_mul_f32 v[78:79], v[78:79], v[190:191] op_sel_hi:[1,0]
	v_pk_mul_f32 v[76:77], v[76:77], v[190:191] op_sel_hi:[1,0]
	v_pk_mul_f32 v[74:75], v[74:75], v[190:191] op_sel_hi:[1,0]
	v_pk_mul_f32 v[72:73], v[72:73], v[190:191] op_sel_hi:[1,0]
	v_pk_mul_f32 v[70:71], v[70:71], v[190:191] op_sel_hi:[1,0]
	v_pk_mul_f32 v[68:69], v[68:69], v[190:191] op_sel_hi:[1,0]
	v_pk_mul_f32 v[66:67], v[66:67], v[190:191] op_sel_hi:[1,0]
	v_pk_mul_f32 v[64:65], v[64:65], v[190:191] op_sel_hi:[1,0]
	v_pk_mul_f32 v[62:63], v[62:63], v[190:191] op_sel_hi:[1,0]
	v_pk_mul_f32 v[60:61], v[60:61], v[190:191] op_sel_hi:[1,0]
	v_pk_mul_f32 v[58:59], v[58:59], v[190:191] op_sel_hi:[1,0]
	v_pk_mul_f32 v[56:57], v[56:57], v[190:191] op_sel_hi:[1,0]
	v_pk_mul_f32 v[54:55], v[54:55], v[190:191] op_sel_hi:[1,0]
	v_pk_mul_f32 v[52:53], v[52:53], v[190:191] op_sel_hi:[1,0]
	v_pk_mul_f32 v[50:51], v[50:51], v[190:191] op_sel_hi:[1,0]
	v_pk_mul_f32 v[48:49], v[48:49], v[190:191] op_sel_hi:[1,0]
	v_pk_mul_f32 v[46:47], v[46:47], v[190:191] op_sel_hi:[1,0]
	v_pk_mul_f32 v[44:45], v[44:45], v[190:191] op_sel_hi:[1,0]
	v_pk_mul_f32 v[42:43], v[42:43], v[190:191] op_sel_hi:[1,0]
	v_pk_mul_f32 v[40:41], v[40:41], v[190:191] op_sel_hi:[1,0]
	v_pk_mul_f32 v[38:39], v[38:39], v[190:191] op_sel_hi:[1,0]
	v_pk_mul_f32 v[36:37], v[36:37], v[190:191] op_sel_hi:[1,0]
	v_pk_mul_f32 v[34:35], v[34:35], v[190:191] op_sel_hi:[1,0]
	v_pk_mul_f32 v[32:33], v[32:33], v[190:191] op_sel_hi:[1,0]
	v_pk_mul_f32 v[30:31], v[30:31], v[190:191] op_sel_hi:[1,0]
	v_pk_mul_f32 v[28:29], v[28:29], v[190:191] op_sel_hi:[1,0]
	v_pk_mul_f32 v[26:27], v[26:27], v[190:191] op_sel_hi:[1,0]
	v_pk_mul_f32 v[24:25], v[24:25], v[190:191] op_sel_hi:[1,0]
	v_pk_mul_f32 v[22:23], v[22:23], v[190:191] op_sel_hi:[1,0]
	v_pk_mul_f32 v[20:21], v[20:21], v[190:191] op_sel_hi:[1,0]
	v_pk_mul_f32 v[18:19], v[18:19], v[190:191] op_sel_hi:[1,0]
	v_pk_mul_f32 v[16:17], v[16:17], v[190:191] op_sel_hi:[1,0]
	v_pk_mul_f32 v[14:15], v[14:15], v[190:191] op_sel_hi:[1,0]
	v_pk_mul_f32 v[12:13], v[12:13], v[190:191] op_sel_hi:[1,0]
	v_pk_mul_f32 v[10:11], v[10:11], v[190:191] op_sel_hi:[1,0]
	v_pk_mul_f32 v[8:9], v[8:9], v[190:191] op_sel_hi:[1,0]
	v_pk_mul_f32 v[6:7], v[6:7], v[190:191] op_sel_hi:[1,0]
	v_pk_mul_f32 v[4:5], v[4:5], v[190:191] op_sel_hi:[1,0]
	v_pk_mul_f32 v[2:3], v[2:3], v[190:191] op_sel_hi:[1,0]
	v_pk_mul_f32 v[0:1], v[0:1], v[190:191] op_sel_hi:[1,0]
	v_mul_f32_e32 v202, v202, v190
	v_mov_b32_e32 v190, v246
	v_sub_f32_e32 v222, v222, v190
	v_exp_f32_e32 v222, v222
	v_sub_f32_e32 v223, v223, v190
	v_exp_f32_e32 v223, v223
	v_sub_f32_e32 v224, v224, v190
	v_add_f32_e32 v254, 0, v222
	v_exp_f32_e32 v224, v224
	v_sub_f32_e32 v225, v225, v190
	v_add_f32_e32 v254, v223, v254
	v_exp_f32_e32 v225, v225
	v_sub_f32_e32 v226, v226, v190
	v_add_f32_e32 v254, v224, v254
	v_exp_f32_e32 v226, v226
	v_sub_f32_e32 v227, v227, v190
	v_add_f32_e32 v254, v225, v254
	v_exp_f32_e32 v227, v227
	v_sub_f32_e32 v228, v228, v190
	v_add_f32_e32 v254, v226, v254
	v_exp_f32_e32 v228, v228
	v_sub_f32_e32 v229, v229, v190
	v_add_f32_e32 v254, v227, v254
	v_exp_f32_e32 v229, v229
	v_sub_f32_e32 v230, v230, v190
	v_add_f32_e32 v254, v228, v254
	v_exp_f32_e32 v230, v230
	v_sub_f32_e32 v231, v231, v190
	v_add_f32_e32 v254, v229, v254
	v_exp_f32_e32 v231, v231
	v_sub_f32_e32 v232, v232, v190
	v_add_f32_e32 v254, v230, v254
	v_exp_f32_e32 v232, v232
	v_sub_f32_e32 v233, v233, v190
	v_add_f32_e32 v254, v231, v254
	v_exp_f32_e32 v233, v233
	v_sub_f32_e32 v234, v234, v190
	v_add_f32_e32 v254, v232, v254
	v_exp_f32_e32 v234, v234
	v_sub_f32_e32 v235, v235, v190
	v_add_f32_e32 v254, v233, v254
	v_exp_f32_e32 v235, v235
	v_sub_f32_e32 v236, v236, v190
	v_add_f32_e32 v254, v234, v254
	v_exp_f32_e32 v236, v236
	v_sub_f32_e32 v237, v237, v190
	v_add_f32_e32 v254, v235, v254
	v_exp_f32_e32 v237, v237
	v_add_f32_e32 v254, v236, v254
	v_add_f32_e32 v254, v237, v254
	v_cvt_pk_bf16_f32 v242, v222, v223
	v_cvt_pk_bf16_f32 v243, v224, v225
	v_cvt_pk_bf16_f32 v244, v226, v227
	v_cvt_pk_bf16_f32 v245, v228, v229
	v_cvt_pk_bf16_f32 v250, v230, v231
	v_cvt_pk_bf16_f32 v251, v232, v233
	v_cvt_pk_bf16_f32 v252, v234, v235
	v_cvt_pk_bf16_f32 v253, v236, v237
	v_add_f32_e32 v202, v202, v254
	s_nop 1
	s_waitcnt lgkmcnt(8)
	v_mfma_f32_32x32x16_bf16 v[112:127], v[238:241], v[242:245], v[112:127]
	ds_read_b64_tr_b16 v[238:239], v218 offset:16640
	ds_read_b64_tr_b16 v[240:241], v218 offset:20736
	s_waitcnt lgkmcnt(8)
	v_mfma_f32_32x32x16_bf16 v[96:111], v[128:131], v[242:245], v[96:111]
	ds_read_b64_tr_b16 v[222:223], v219 offset:16640
	ds_read_b64_tr_b16 v[224:225], v219 offset:20736
	s_cmp_lg_u64 s[18:19], 0
	s_cbranch_scc1 .Latt_ndr0_4
	s_sub_i32 s100, s76, 1
	s_cmp_eq_u32 s76, 0
	s_cselect_b32 s100, 2, s100
	s_lshl_b32 s101, s100, 14
	s_add_i32 m0, s73, s101
	s_nop 0
	global_load_lds_dwordx4 v178, s[14:15]

.LBB0_1820:
	s_cmp_gt_i32 s4, s72
	s_cbranch_scc1 .LBB0_1831
	s_add_i32 s100, s4, 63
	s_cmp_le_i32 s100, s71
	s_cbranch_scc0 .Latt_slow_5
	s_lshl_b32 s98, s33, 14
	s_lshl_b32 s99, s33, 15
	s_add_i32 s99, s99, 0xc000
	v_add_u32_e32 v206, s98, v196
	ds_read_b128 v[206:209], v206
	v_add_u32_e32 v210, s98, v197
	ds_read_b128 v[210:213], v210
	v_add_u32_e32 v214, s98, v198
	ds_read_b128 v[214:217], v214
	v_add_u32_e32 v238, s98, v199
	ds_read_b128 v[238:241], v238
	v_add_u32_e32 v242, s98, v200
	ds_read_b128 v[242:245], v242
	v_add_u32_e32 v250, s98, v201
	ds_read_b128 v[250:253], v250
	v_add_u32_e32 v222, s98, v202
	ds_read_b128 v[222:225], v222
	v_add_u32_e32 v226, s98, v203
	ds_read_b128 v[226:229], v226
	v_bfe_u32 v246, v204, 2, 2
	v_bfe_u32 v247, v204, 5, 1
	v_lshl_or_b32 v247, v247, 2, v246
	v_and_b32_e32 v249, 3, v204
	v_and_b32_e32 v254, 16, v204
	v_lshl_or_b32 v249, v249, 2, v254
	v_lshlrev_b32_e32 v249, 1, v249
	v_lshl_add_u32 v247, v247, 9, v249
	v_add_u32_e32 v247, s99, v247
	v_lshlrev_b32_e32 v246, 6, v246
	v_add_u32_e32 v205, v247, v246
	v_xor_b32_e32 v249, 64, v246
	v_add_u32_e32 v218, v247, v249
	v_xor_b32_e32 v249, 0x80, v246
	v_add_u32_e32 v219, v247, v249
	v_xor_b32_e32 v249, 0xc0, v246
	v_add_u32_e32 v221, v247, v249
	s_waitcnt lgkmcnt(7)
	v_mfma_f32_32x32x16_bf16 v[128:143], v[206:209], v[144:147], 0
	v_add_u32_e32 v206, s98, v196
	ds_read_b128 v[206:209], v206 offset:8192
	s_waitcnt lgkmcnt(7)
	v_mfma_f32_32x32x16_bf16 v[128:143], v[210:213], v[148:151], v[128:143]
	v_add_u32_e32 v210, s98, v197
	ds_read_b128 v[210:213], v210 offset:8192
	s_waitcnt lgkmcnt(7)
	v_mfma_f32_32x32x16_bf16 v[128:143], v[214:217], v[152:155], v[128:143]
	v_add_u32_e32 v214, s98, v198
	ds_read_b128 v[214:217], v214 offset:8192
	s_waitcnt lgkmcnt(7)
	v_mfma_f32_32x32x16_bf16 v[128:143], v[238:241], v[156:159], v[128:143]
	v_add_u32_e32 v238, s98, v199
	ds_read_b128 v[238:241], v238 offset:8192
	s_waitcnt lgkmcnt(7)
	v_mfma_f32_32x32x16_bf16 v[128:143], v[242:245], v[160:163], v[128:143]
	s_waitcnt lgkmcnt(6)
	v_mfma_f32_32x32x16_bf16 v[128:143], v[250:253], v[164:167], v[128:143]
	s_waitcnt lgkmcnt(5)
	v_mfma_f32_32x32x16_bf16 v[128:143], v[222:225], v[168:171], v[128:143]
	s_waitcnt lgkmcnt(4)
	v_mfma_f32_32x32x16_bf16 v[128:143], v[226:229], v[172:175], v[128:143]
	s_waitcnt lgkmcnt(3)
	v_mfma_f32_32x32x16_bf16 v[222:237], v[206:209], v[144:147], 0
	v_add_u32_e32 v206, s98, v200
	ds_read_b128 v[206:209], v206 offset:8192
	s_nop 7
	v_max3_f32 v246, v128, v129, v130
	v_max3_f32 v247, v131, v132, v133
	v_max3_f32 v246, v246, v134, v135
	v_max3_f32 v247, v247, v136, v137
	v_max3_f32 v246, v246, v138, v139
	v_max3_f32 v247, v247, v140, v141
	v_max3_f32 v246, v246, v142, v143
	s_waitcnt lgkmcnt(3)
	v_mfma_f32_32x32x16_bf16 v[222:237], v[210:213], v[148:151], v[222:237]
	v_add_u32_e32 v210, s98, v201
	ds_read_b128 v[210:213], v210 offset:8192
	v_max_f32_e32 v246, v246, v247
	v_mov_b32_e32 v247, v246
	v_add_f32_e32 v249, 0x41000000, v190
	s_nop 1
	v_permlane32_swap_b32_e32 v246, v247
	v_max_f32_e32 v246, v246, v247
	v_cmp_gt_f32_e32 vcc, v246, v249
	s_cbranch_vccz .Latt_nr0_5
	v_max_f32_e32 v246, v190, v246
	v_sub_f32_e32 v190, v190, v246
	v_exp_f32_e32 v190, v190
	s_nop 0
	v_pk_mul_f32 v[126:127], v[126:127], v[190:191] op_sel_hi:[1,0]
	v_pk_mul_f32 v[124:125], v[124:125], v[190:191] op_sel_hi:[1,0]
	v_pk_mul_f32 v[122:123], v[122:123], v[190:191] op_sel_hi:[1,0]
	v_pk_mul_f32 v[120:121], v[120:121], v[190:191] op_sel_hi:[1,0]
	v_pk_mul_f32 v[118:119], v[118:119], v[190:191] op_sel_hi:[1,0]
	v_pk_mul_f32 v[116:117], v[116:117], v[190:191] op_sel_hi:[1,0]
	v_pk_mul_f32 v[114:115], v[114:115], v[190:191] op_sel_hi:[1,0]
	v_pk_mul_f32 v[112:113], v[112:113], v[190:191] op_sel_hi:[1,0]
	v_pk_mul_f32 v[110:111], v[110:111], v[190:191] op_sel_hi:[1,0]
	v_pk_mul_f32 v[108:109], v[108:109], v[190:191] op_sel_hi:[1,0]
	v_pk_mul_f32 v[106:107], v[106:107], v[190:191] op_sel_hi:[1,0]
	v_pk_mul_f32 v[104:105], v[104:105], v[190:191] op_sel_hi:[1,0]
	v_pk_mul_f32 v[102:103], v[102:103], v[190:191] op_sel_hi:[1,0]
	v_pk_mul_f32 v[100:101], v[100:101], v[190:191] op_sel_hi:[1,0]
	v_pk_mul_f32 v[98:99], v[98:99], v[190:191] op_sel_hi:[1,0]
	v_pk_mul_f32 v[96:97], v[96:97], v[190:191] op_sel_hi:[1,0]
	v_pk_mul_f32 v[94:95], v[94:95], v[190:191] op_sel_hi:[1,0]
	v_pk_mul_f32 v[92:93], v[92:93], v[190:191] op_sel_hi:[1,0]
	v_pk_mul_f32 v[90:91], v[90:91], v[190:191] op_sel_hi:[1,0]
	v_pk_mul_f32 v[88:89], v[88:89], v[190:191] op_sel_hi:[1,0]
	v_pk_mul_f32 v[86:87], v[86:87], v[190:191] op_sel_hi:[1,0]
	v_pk_mul_f32 v[84:85], v[84:85], v[190:191] op_sel_hi:[1,0]
	v_pk_mul_f32 v[82:83], v[82:83], v[190:191] op_sel_hi:[1,0]
	v_pk_mul_f32 v[80:81], v[80:81], v[190:191] op_sel_hi:[1,0]
	v_pk_mul_f32 v[78:79], v[78:79], v[190:191] op_sel_hi:[1,0]
	v_pk_mul_f32 v[76:77], v[76:77], v[190:191] op_sel_hi:[1,0]
	v_pk_mul_f32 v[74:75], v[74:75], v[190:191] op_sel_hi:[1,0]
	v_pk_mul_f32 v[72:73], v[72:73], v[190:191] op_sel_hi:[1,0]
	v_pk_mul_f32 v[70:71], v[70:71], v[190:191] op_sel_hi:[1,0]
	v_pk_mul_f32 v[68:69], v[68:69], v[190:191] op_sel_hi:[1,0]
	v_pk_mul_f32 v[66:67], v[66:67], v[190:191] op_sel_hi:[1,0]
	v_pk_mul_f32 v[64:65], v[64:65], v[190:191] op_sel_hi:[1,0]
	v_pk_mul_f32 v[62:63], v[62:63], v[190:191] op_sel_hi:[1,0]
	v_pk_mul_f32 v[60:61], v[60:61], v[190:191] op_sel_hi:[1,0]
	v_pk_mul_f32 v[58:59], v[58:59], v[190:191] op_sel_hi:[1,0]
	v_pk_mul_f32 v[56:57], v[56:57], v[190:191] op_sel_hi:[1,0]
	v_pk_mul_f32 v[54:55], v[54:55], v[190:191] op_sel_hi:[1,0]
	v_pk_mul_f32 v[52:53], v[52:53], v[190:191] op_sel_hi:[1,0]
	v_pk_mul_f32 v[50:51], v[50:51], v[190:191] op_sel_hi:[1,0]
	v_pk_mul_f32 v[48:49], v[48:49], v[190:191] op_sel_hi:[1,0]
	v_pk_mul_f32 v[46:47], v[46:47], v[190:191] op_sel_hi:[1,0]
	v_pk_mul_f32 v[44:45], v[44:45], v[190:191] op_sel_hi:[1,0]
	v_pk_mul_f32 v[42:43], v[42:43], v[190:191] op_sel_hi:[1,0]
	v_pk_mul_f32 v[40:41], v[40:41], v[190:191] op_sel_hi:[1,0]
	v_pk_mul_f32 v[38:39], v[38:39], v[190:191] op_sel_hi:[1,0]
	v_pk_mul_f32 v[36:37], v[36:37], v[190:191] op_sel_hi:[1,0]
	v_pk_mul_f32 v[34:35], v[34:35], v[190:191] op_sel_hi:[1,0]
	v_pk_mul_f32 v[32:33], v[32:33], v[190:191] op_sel_hi:[1,0]
	v_pk_mul_f32 v[30:31], v[30:31], v[190:191] op_sel_hi:[1,0]
	v_pk_mul_f32 v[28:29], v[28:29], v[190:191] op_sel_hi:[1,0]
	v_pk_mul_f32 v[26:27], v[26:27], v[190:191] op_sel_hi:[1,0]
	v_pk_mul_f32 v[24:25], v[24:25], v[190:191] op_sel_hi:[1,0]
	v_pk_mul_f32 v[22:23], v[22:23], v[190:191] op_sel_hi:[1,0]
	v_pk_mul_f32 v[20:21], v[20:21], v[190:191] op_sel_hi:[1,0]
	v_pk_mul_f32 v[18:19], v[18:19], v[190:191] op_sel_hi:[1,0]
	v_pk_mul_f32 v[16:17], v[16:17], v[190:191] op_sel_hi:[1,0]
	v_pk_mul_f32 v[14:15], v[14:15], v[190:191] op_sel_hi:[1,0]
	v_pk_mul_f32 v[12:13], v[12:13], v[190:191] op_sel_hi:[1,0]
	v_pk_mul_f32 v[10:11], v[10:11], v[190:191] op_sel_hi:[1,0]
	v_pk_mul_f32 v[8:9], v[8:9], v[190:191] op_sel_hi:[1,0]
	v_pk_mul_f32 v[6:7], v[6:7], v[190:191] op_sel_hi:[1,0]
	v_pk_mul_f32 v[4:5], v[4:5], v[190:191] op_sel_hi:[1,0]
	v_pk_mul_f32 v[2:3], v[2:3], v[190:191] op_sel_hi:[1,0]
	v_pk_mul_f32 v[0:1], v[0:1], v[190:191] op_sel_hi:[1,0]
	v_mul_f32_e32 v195, v195, v190
	v_mov_b32_e32 v190, v246
.Latt_nr0_5:
	s_waitcnt lgkmcnt(3)
	v_mfma_f32_32x32x16_bf16 v[222:237], v[214:217], v[152:155], v[222:237]
	v_add_u32_e32 v214, s98, v202
	ds_read_b128 v[214:217], v214 offset:8192
	v_sub_f32_e32 v128, v128, v190
	v_exp_f32_e32 v128, v128
	v_sub_f32_e32 v129, v129, v190
	v_exp_f32_e32 v129, v129
	v_sub_f32_e32 v130, v130, v190
	s_waitcnt lgkmcnt(3)
	v_mfma_f32_32x32x16_bf16 v[222:237], v[238:241], v[156:159], v[222:237]
	v_add_u32_e32 v238, s98, v203
	ds_read_b128 v[238:241], v238 offset:8192
	v_add_f32_e32 v254, 0, v128
	v_exp_f32_e32 v130, v130
	v_sub_f32_e32 v131, v131, v190
	v_add_f32_e32 v254, v129, v254
	v_exp_f32_e32 v131, v131
	s_waitcnt lgkmcnt(3)
	v_mfma_f32_32x32x16_bf16 v[222:237], v[206:209], v[160:163], v[222:237]
	ds_read_b64_tr_b16 v[206:207], v205
	ds_read_b64_tr_b16 v[208:209], v205 offset:4096
	v_sub_f32_e32 v132, v132, v190
	v_add_f32_e32 v254, v130, v254
	v_exp_f32_e32 v132, v132
	v_sub_f32_e32 v133, v133, v190
	v_add_f32_e32 v254, v131, v254
	s_waitcnt lgkmcnt(4)
	v_mfma_f32_32x32x16_bf16 v[222:237], v[210:213], v[164:167], v[222:237]
	ds_read_b64_tr_b16 v[210:211], v218
	ds_read_b64_tr_b16 v[212:213], v218 offset:4096
	v_exp_f32_e32 v133, v133
	v_sub_f32_e32 v134, v134, v190
	v_add_f32_e32 v254, v132, v254
	v_exp_f32_e32 v134, v134
	s_waitcnt lgkmcnt(5)
	v_mfma_f32_32x32x16_bf16 v[222:237], v[214:217], v[168:171], v[222:237]
	ds_read_b64_tr_b16 v[214:215], v219
	ds_read_b64_tr_b16 v[216:217], v219 offset:4096
	v_sub_f32_e32 v135, v135, v190
	v_add_f32_e32 v254, v133, v254
	v_exp_f32_e32 v135, v135
	s_nop 0
	s_waitcnt lgkmcnt(6)
	v_mfma_f32_32x32x16_bf16 v[222:237], v[238:241], v[172:175], v[222:237]
	ds_read_b64_tr_b16 v[238:239], v221
	ds_read_b64_tr_b16 v[240:241], v221 offset:4096
	v_cvt_pk_bf16_f32 v242, v128, v129
	v_cvt_pk_bf16_f32 v243, v130, v131
	v_cvt_pk_bf16_f32 v244, v132, v133
	v_cvt_pk_bf16_f32 v245, v134, v135
	s_nop 1
	s_waitcnt lgkmcnt(6)
	v_mfma_f32_32x32x16_bf16 v[112:127], v[206:209], v[242:245], v[112:127]
	ds_read_b64_tr_b16 v[206:207], v205 offset:256
	ds_read_b64_tr_b16 v[208:209], v205 offset:4352
	v_sub_f32_e32 v136, v136, v190
	v_add_f32_e32 v254, v134, v254
	v_exp_f32_e32 v136, v136
	v_sub_f32_e32 v137, v137, v190
	v_add_f32_e32 v254, v135, v254
	s_waitcnt lgkmcnt(6)
	v_mfma_f32_32x32x16_bf16 v[96:111], v[210:213], v[242:245], v[96:111]
	ds_read_b64_tr_b16 v[210:211], v218 offset:256
	ds_read_b64_tr_b16 v[212:213], v218 offset:4352
	v_exp_f32_e32 v137, v137
	v_sub_f32_e32 v138, v138, v190
	v_add_f32_e32 v254, v136, v254
	v_exp_f32_e32 v138, v138
	v_sub_f32_e32 v139, v139, v190
	s_waitcnt lgkmcnt(6)
	v_mfma_f32_32x32x16_bf16 v[80:95], v[214:217], v[242:245], v[80:95]
	ds_read_b64_tr_b16 v[214:215], v219 offset:256
	ds_read_b64_tr_b16 v[216:217], v219 offset:4352
	v_add_f32_e32 v254, v137, v254
	v_exp_f32_e32 v139, v139
	v_sub_f32_e32 v140, v140, v190
	v_add_f32_e32 v254, v138, v254
	s_waitcnt lgkmcnt(6)
	v_mfma_f32_32x32x16_bf16 v[64:79], v[238:241], v[242:245], v[64:79]
	ds_read_b64_tr_b16 v[238:239], v221 offset:256
	ds_read_b64_tr_b16 v[240:241], v221 offset:4352
	v_exp_f32_e32 v140, v140
	v_sub_f32_e32 v141, v141, v190
	v_add_f32_e32 v254, v139, v254
	v_exp_f32_e32 v141, v141
	s_waitcnt lgkmcnt(6)
	v_mfma_f32_32x32x16_bf16 v[48:63], v[206:209], v[242:245], v[48:63]
	ds_read_b64_tr_b16 v[206:207], v205 offset:8192
	ds_read_b64_tr_b16 v[208:209], v205 offset:12288
	v_sub_f32_e32 v142, v142, v190
	v_add_f32_e32 v254, v140, v254
	v_exp_f32_e32 v142, v142
	v_sub_f32_e32 v143, v143, v190
	s_waitcnt lgkmcnt(6)
	v_mfma_f32_32x32x16_bf16 v[32:47], v[210:213], v[242:245], v[32:47]
	ds_read_b64_tr_b16 v[210:211], v218 offset:8192
	ds_read_b64_tr_b16 v[212:213], v218 offset:12288
	v_add_f32_e32 v254, v141, v254
	v_exp_f32_e32 v143, v143
	v_add_f32_e32 v254, v142, v254
	v_add_f32_e32 v254, v143, v254
	s_waitcnt lgkmcnt(6)
	v_mfma_f32_32x32x16_bf16 v[16:31], v[214:217], v[242:245], v[16:31]
	ds_read_b64_tr_b16 v[214:215], v219 offset:8192
	ds_read_b64_tr_b16 v[216:217], v219 offset:12288
	v_cvt_pk_bf16_f32 v250, v136, v137
	v_cvt_pk_bf16_f32 v251, v138, v139
	v_cvt_pk_bf16_f32 v252, v140, v141
	v_cvt_pk_bf16_f32 v253, v142, v143
	v_add_f32_e32 v195, v195, v254
	s_waitcnt lgkmcnt(6)
	v_mfma_f32_32x32x16_bf16 v[0:15], v[238:241], v[242:245], v[0:15]
	ds_read_b64_tr_b16 v[238:239], v221 offset:8192
	ds_read_b64_tr_b16 v[240:241], v221 offset:12288
	ds_read_b64_tr_b16 v[128:129], v205 offset:8448
	ds_read_b64_tr_b16 v[130:131], v205 offset:12544
	s_waitcnt lgkmcnt(8)
	v_mfma_f32_32x32x16_bf16 v[112:127], v[206:209], v[250:253], v[112:127]
	ds_read_b64_tr_b16 v[206:207], v218 offset:8448
	ds_read_b64_tr_b16 v[208:209], v218 offset:12544
	v_max3_f32 v246, v222, v223, v224
	v_max3_f32 v247, v225, v226, v227
	v_max3_f32 v246, v246, v228, v229
	v_max3_f32 v247, v247, v230, v231
	v_max3_f32 v246, v246, v232, v233
	v_max3_f32 v247, v247, v234, v235
	s_waitcnt lgkmcnt(8)
	v_mfma_f32_32x32x16_bf16 v[96:111], v[210:213], v[250:253], v[96:111]
	ds_read_b64_tr_b16 v[210:211], v219 offset:8448
	ds_read_b64_tr_b16 v[212:213], v219 offset:12544
	v_max3_f32 v246, v246, v236, v237
	v_max_f32_e32 v246, v246, v247
	v_mov_b32_e32 v247, v246
	v_add_f32_e32 v249, 0x41000000, v190
	s_nop 1
	s_waitcnt lgkmcnt(8)
	v_mfma_f32_32x32x16_bf16 v[80:95], v[214:217], v[250:253], v[80:95]
	ds_read_b64_tr_b16 v[214:215], v221 offset:8448
	ds_read_b64_tr_b16 v[216:217], v221 offset:12544
	v_permlane32_swap_b32_e32 v246, v247
	v_max_f32_e32 v246, v246, v247
	v_cmp_gt_f32_e32 vcc, v246, v249
	s_cbranch_vccnz .Latt_rs1_5
	s_waitcnt lgkmcnt(8)
	v_mfma_f32_32x32x16_bf16 v[64:79], v[238:241], v[250:253], v[64:79]
	ds_read_b64_tr_b16 v[238:239], v205 offset:16384
	ds_read_b64_tr_b16 v[240:241], v205 offset:20480
	v_sub_f32_e32 v222, v222, v190
	v_exp_f32_e32 v222, v222
	v_sub_f32_e32 v223, v223, v190
	v_exp_f32_e32 v223, v223
	v_sub_f32_e32 v224, v224, v190
	v_add_f32_e32 v254, 0, v222
	s_waitcnt lgkmcnt(8)
	v_mfma_f32_32x32x16_bf16 v[48:63], v[128:131], v[250:253], v[48:63]
	ds_read_b64_tr_b16 v[128:129], v218 offset:16384
	ds_read_b64_tr_b16 v[130:131], v218 offset:20480
	v_exp_f32_e32 v224, v224
	v_sub_f32_e32 v225, v225, v190
	v_add_f32_e32 v254, v223, v254
	v_exp_f32_e32 v225, v225
	v_sub_f32_e32 v226, v226, v190
	v_add_f32_e32 v254, v224, v254
	s_waitcnt lgkmcnt(8)
	v_mfma_f32_32x32x16_bf16 v[32:47], v[206:209], v[250:253], v[32:47]
	ds_read_b64_tr_b16 v[206:207], v219 offset:16384
	ds_read_b64_tr_b16 v[208:209], v219 offset:20480
	v_exp_f32_e32 v226, v226
	v_sub_f32_e32 v227, v227, v190
	v_add_f32_e32 v254, v225, v254
	v_exp_f32_e32 v227, v227
	v_sub_f32_e32 v228, v228, v190
	s_waitcnt lgkmcnt(8)
	v_mfma_f32_32x32x16_bf16 v[16:31], v[210:213], v[250:253], v[16:31]
	ds_read_b64_tr_b16 v[210:211], v221 offset:16384
	ds_read_b64_tr_b16 v[212:213], v221 offset:20480
	v_add_f32_e32 v254, v226, v254
	v_exp_f32_e32 v228, v228
	v_sub_f32_e32 v229, v229, v190
	v_add_f32_e32 v254, v227, v254
	v_exp_f32_e32 v229, v229
	s_waitcnt lgkmcnt(8)
	v_mfma_f32_32x32x16_bf16 v[0:15], v[214:217], v[250:253], v[0:15]
	ds_read_b64_tr_b16 v[214:215], v205 offset:16640
	ds_read_b64_tr_b16 v[216:217], v205 offset:20736
	s_nop 0
	v_cvt_pk_bf16_f32 v242, v222, v223
	v_cvt_pk_bf16_f32 v243, v224, v225
	v_cvt_pk_bf16_f32 v244, v226, v227
	v_cvt_pk_bf16_f32 v245, v228, v229
	s_nop 1
	s_waitcnt lgkmcnt(8)
	v_mfma_f32_32x32x16_bf16 v[112:127], v[238:241], v[242:245], v[112:127]
	ds_read_b64_tr_b16 v[238:239], v218 offset:16640
	ds_read_b64_tr_b16 v[240:241], v218 offset:20736
	v_sub_f32_e32 v230, v230, v190
	v_add_f32_e32 v254, v228, v254
	v_exp_f32_e32 v230, v230
	v_sub_f32_e32 v231, v231, v190
	v_add_f32_e32 v254, v229, v254
	s_waitcnt lgkmcnt(8)
	v_mfma_f32_32x32x16_bf16 v[96:111], v[128:131], v[242:245], v[96:111]
	ds_read_b64_tr_b16 v[128:129], v219 offset:16640
	ds_read_b64_tr_b16 v[130:131], v219 offset:20736
	v_exp_f32_e32 v231, v231
	v_sub_f32_e32 v232, v232, v190
	v_add_f32_e32 v254, v230, v254
	v_exp_f32_e32 v232, v232
	v_sub_f32_e32 v233, v233, v190
	s_cmp_lg_u64 s[18:19], 0
	s_cbranch_scc1 .Latt_nd0_5
	s_sub_i32 s100, s33, 1
	s_cmp_eq_u32 s33, 0
	s_cselect_b32 s100, 2, s100
	s_lshl_b32 s101, s100, 14
	s_add_i32 m0, s73, s101
	s_nop 0
	global_load_lds_dwordx4 v178, s[12:13]

.Latt_nd1_5:
	s_waitcnt lgkmcnt(8)
	v_mfma_f32_32x32x16_bf16 v[48:63], v[214:217], v[242:245], v[48:63]
	ds_read_b64_tr_b16 v[214:215], v218 offset:24576
	ds_read_b64_tr_b16 v[216:217], v218 offset:28672
	v_sub_f32_e32 v236, v236, v190
	v_add_f32_e32 v254, v234, v254
	v_exp_f32_e32 v236, v236
	v_sub_f32_e32 v237, v237, v190
	s_waitcnt lgkmcnt(8)
	v_mfma_f32_32x32x16_bf16 v[32:47], v[238:241], v[242:245], v[32:47]
	ds_read_b64_tr_b16 v[238:239], v219 offset:24576
	ds_read_b64_tr_b16 v[240:241], v219 offset:28672
	v_add_f32_e32 v254, v235, v254
	v_exp_f32_e32 v237, v237
	v_add_f32_e32 v254, v236, v254
	v_add_f32_e32 v254, v237, v254
	s_cmp_lg_u64 s[18:19], 0
	s_cbranch_scc1 .Latt_nd2_5
	s_lshl_b32 s101, s100, 15
	s_add_i32 m0, s74, s101
	s_add_u32 s100, s12, 0xf00
	s_addc_u32 s101, s13, 0
	global_load_lds_dwordx4 v182, s[100:101]

.Latt_rs1_5:
	s_waitcnt lgkmcnt(8)
	v_mfma_f32_32x32x16_bf16 v[64:79], v[238:241], v[250:253], v[64:79]
	ds_read_b64_tr_b16 v[238:239], v205 offset:16384
	ds_read_b64_tr_b16 v[240:241], v205 offset:20480
	s_waitcnt lgkmcnt(8)
	v_mfma_f32_32x32x16_bf16 v[48:63], v[128:131], v[250:253], v[48:63]
	ds_read_b64_tr_b16 v[128:129], v218 offset:16384
	ds_read_b64_tr_b16 v[130:131], v218 offset:20480
	s_waitcnt lgkmcnt(8)
	v_mfma_f32_32x32x16_bf16 v[32:47], v[206:209], v[250:253], v[32:47]
	ds_read_b64_tr_b16 v[206:207], v219 offset:16384
	ds_read_b64_tr_b16 v[208:209], v219 offset:20480
	s_waitcnt lgkmcnt(8)
	v_mfma_f32_32x32x16_bf16 v[16:31], v[210:213], v[250:253], v[16:31]
	ds_read_b64_tr_b16 v[210:211], v221 offset:16384
	ds_read_b64_tr_b16 v[212:213], v221 offset:20480
	s_waitcnt lgkmcnt(8)
	v_mfma_f32_32x32x16_bf16 v[0:15], v[214:217], v[250:253], v[0:15]
	ds_read_b64_tr_b16 v[214:215], v205 offset:16640
	ds_read_b64_tr_b16 v[216:217], v205 offset:20736
	s_nop 11
	v_max_f32_e32 v246, v190, v246
	v_sub_f32_e32 v190, v190, v246
	v_exp_f32_e32 v190, v190
	s_nop 0
	v_pk_mul_f32 v[126:127], v[126:127], v[190:191] op_sel_hi:[1,0]
	v_pk_mul_f32 v[124:125], v[124:125], v[190:191] op_sel_hi:[1,0]
	v_pk_mul_f32 v[122:123], v[122:123], v[190:191] op_sel_hi:[1,0]
	v_pk_mul_f32 v[120:121], v[120:121], v[190:191] op_sel_hi:[1,0]
	v_pk_mul_f32 v[118:119], v[118:119], v[190:191] op_sel_hi:[1,0]
	v_pk_mul_f32 v[116:117], v[116:117], v[190:191] op_sel_hi:[1,0]
	v_pk_mul_f32 v[114:115], v[114:115], v[190:191] op_sel_hi:[1,0]
	v_pk_mul_f32 v[112:113], v[112:113], v[190:191] op_sel_hi:[1,0]
	v_pk_mul_f32 v[110:111], v[110:111], v[190:191] op_sel_hi:[1,0]
	v_pk_mul_f32 v[108:109], v[108:109], v[190:191] op_sel_hi:[1,0]
	v_pk_mul_f32 v[106:107], v[106:107], v[190:191] op_sel_hi:[1,0]
	v_pk_mul_f32 v[104:105], v[104:105], v[190:191] op_sel_hi:[1,0]
	v_pk_mul_f32 v[102:103], v[102:103], v[190:191] op_sel_hi:[1,0]
	v_pk_mul_f32 v[100:101], v[100:101], v[190:191] op_sel_hi:[1,0]
	v_pk_mul_f32 v[98:99], v[98:99], v[190:191] op_sel_hi:[1,0]
	v_pk_mul_f32 v[96:97], v[96:97], v[190:191] op_sel_hi:[1,0]
	v_pk_mul_f32 v[94:95], v[94:95], v[190:191] op_sel_hi:[1,0]
	v_pk_mul_f32 v[92:93], v[92:93], v[190:191] op_sel_hi:[1,0]
	v_pk_mul_f32 v[90:91], v[90:91], v[190:191] op_sel_hi:[1,0]
	v_pk_mul_f32 v[88:89], v[88:89], v[190:191] op_sel_hi:[1,0]
	v_pk_mul_f32 v[86:87], v[86:87], v[190:191] op_sel_hi:[1,0]
	v_pk_mul_f32 v[84:85], v[84:85], v[190:191] op_sel_hi:[1,0]
	v_pk_mul_f32 v[82:83], v[82:83], v[190:191] op_sel_hi:[1,0]
	v_pk_mul_f32 v[80:81], v[80:81], v[190:191] op_sel_hi:[1,0]
	v_pk_mul_f32 v[78:79], v[78:79], v[190:191] op_sel_hi:[1,0]
	v_pk_mul_f32 v[76:77], v[76:77], v[190:191] op_sel_hi:[1,0]
	v_pk_mul_f32 v[74:75], v[74:75], v[190:191] op_sel_hi:[1,0]
	v_pk_mul_f32 v[72:73], v[72:73], v[190:191] op_sel_hi:[1,0]
	v_pk_mul_f32 v[70:71], v[70:71], v[190:191] op_sel_hi:[1,0]
	v_pk_mul_f32 v[68:69], v[68:69], v[190:191] op_sel_hi:[1,0]
	v_pk_mul_f32 v[66:67], v[66:67], v[190:191] op_sel_hi:[1,0]
	v_pk_mul_f32 v[64:65], v[64:65], v[190:191] op_sel_hi:[1,0]
	v_pk_mul_f32 v[62:63], v[62:63], v[190:191] op_sel_hi:[1,0]
	v_pk_mul_f32 v[60:61], v[60:61], v[190:191] op_sel_hi:[1,0]
	v_pk_mul_f32 v[58:59], v[58:59], v[190:191] op_sel_hi:[1,0]
	v_pk_mul_f32 v[56:57], v[56:57], v[190:191] op_sel_hi:[1,0]
	v_pk_mul_f32 v[54:55], v[54:55], v[190:191] op_sel_hi:[1,0]
	v_pk_mul_f32 v[52:53], v[52:53], v[190:191] op_sel_hi:[1,0]
	v_pk_mul_f32 v[50:51], v[50:51], v[190:191] op_sel_hi:[1,0]
	v_pk_mul_f32 v[48:49], v[48:49], v[190:191] op_sel_hi:[1,0]
	v_pk_mul_f32 v[46:47], v[46:47], v[190:191] op_sel_hi:[1,0]
	v_pk_mul_f32 v[44:45], v[44:45], v[190:191] op_sel_hi:[1,0]
	v_pk_mul_f32 v[42:43], v[42:43], v[190:191] op_sel_hi:[1,0]
	v_pk_mul_f32 v[40:41], v[40:41], v[190:191] op_sel_hi:[1,0]
	v_pk_mul_f32 v[38:39], v[38:39], v[190:191] op_sel_hi:[1,0]
	v_pk_mul_f32 v[36:37], v[36:37], v[190:191] op_sel_hi:[1,0]
	v_pk_mul_f32 v[34:35], v[34:35], v[190:191] op_sel_hi:[1,0]
	v_pk_mul_f32 v[32:33], v[32:33], v[190:191] op_sel_hi:[1,0]
	v_pk_mul_f32 v[30:31], v[30:31], v[190:191] op_sel_hi:[1,0]
	v_pk_mul_f32 v[28:29], v[28:29], v[190:191] op_sel_hi:[1,0]
	v_pk_mul_f32 v[26:27], v[26:27], v[190:191] op_sel_hi:[1,0]
	v_pk_mul_f32 v[24:25], v[24:25], v[190:191] op_sel_hi:[1,0]
	v_pk_mul_f32 v[22:23], v[22:23], v[190:191] op_sel_hi:[1,0]
	v_pk_mul_f32 v[20:21], v[20:21], v[190:191] op_sel_hi:[1,0]
	v_pk_mul_f32 v[18:19], v[18:19], v[190:191] op_sel_hi:[1,0]
	v_pk_mul_f32 v[16:17], v[16:17], v[190:191] op_sel_hi:[1,0]
	v_pk_mul_f32 v[14:15], v[14:15], v[190:191] op_sel_hi:[1,0]
	v_pk_mul_f32 v[12:13], v[12:13], v[190:191] op_sel_hi:[1,0]
	v_pk_mul_f32 v[10:11], v[10:11], v[190:191] op_sel_hi:[1,0]
	v_pk_mul_f32 v[8:9], v[8:9], v[190:191] op_sel_hi:[1,0]
	v_pk_mul_f32 v[6:7], v[6:7], v[190:191] op_sel_hi:[1,0]
	v_pk_mul_f32 v[4:5], v[4:5], v[190:191] op_sel_hi:[1,0]
	v_pk_mul_f32 v[2:3], v[2:3], v[190:191] op_sel_hi:[1,0]
	v_pk_mul_f32 v[0:1], v[0:1], v[190:191] op_sel_hi:[1,0]
	v_mul_f32_e32 v195, v195, v190
	v_mov_b32_e32 v190, v246
	v_sub_f32_e32 v222, v222, v190
	v_exp_f32_e32 v222, v222
	v_sub_f32_e32 v223, v223, v190
	v_exp_f32_e32 v223, v223
	v_sub_f32_e32 v224, v224, v190
	v_add_f32_e32 v254, 0, v222
	v_exp_f32_e32 v224, v224
	v_sub_f32_e32 v225, v225, v190
	v_add_f32_e32 v254, v223, v254
	v_exp_f32_e32 v225, v225
	v_sub_f32_e32 v226, v226, v190
	v_add_f32_e32 v254, v224, v254
	v_exp_f32_e32 v226, v226
	v_sub_f32_e32 v227, v227, v190
	v_add_f32_e32 v254, v225, v254
	v_exp_f32_e32 v227, v227
	v_sub_f32_e32 v228, v228, v190
	v_add_f32_e32 v254, v226, v254
	v_exp_f32_e32 v228, v228
	v_sub_f32_e32 v229, v229, v190
	v_add_f32_e32 v254, v227, v254
	v_exp_f32_e32 v229, v229
	v_sub_f32_e32 v230, v230, v190
	v_add_f32_e32 v254, v228, v254
	v_exp_f32_e32 v230, v230
	v_sub_f32_e32 v231, v231, v190
	v_add_f32_e32 v254, v229, v254
	v_exp_f32_e32 v231, v231
	v_sub_f32_e32 v232, v232, v190
	v_add_f32_e32 v254, v230, v254
	v_exp_f32_e32 v232, v232
	v_sub_f32_e32 v233, v233, v190
	v_add_f32_e32 v254, v231, v254
	v_exp_f32_e32 v233, v233
	v_sub_f32_e32 v234, v234, v190
	v_add_f32_e32 v254, v232, v254
	v_exp_f32_e32 v234, v234
	v_sub_f32_e32 v235, v235, v190
	v_add_f32_e32 v254, v233, v254
	v_exp_f32_e32 v235, v235
	v_sub_f32_e32 v236, v236, v190
	v_add_f32_e32 v254, v234, v254
	v_exp_f32_e32 v236, v236
	v_sub_f32_e32 v237, v237, v190
	v_add_f32_e32 v254, v235, v254
	v_exp_f32_e32 v237, v237
	v_add_f32_e32 v254, v236, v254
	v_add_f32_e32 v254, v237, v254
	v_cvt_pk_bf16_f32 v242, v222, v223
	v_cvt_pk_bf16_f32 v243, v224, v225
	v_cvt_pk_bf16_f32 v244, v226, v227
	v_cvt_pk_bf16_f32 v245, v228, v229
	v_cvt_pk_bf16_f32 v250, v230, v231
	v_cvt_pk_bf16_f32 v251, v232, v233
	v_cvt_pk_bf16_f32 v252, v234, v235
	v_cvt_pk_bf16_f32 v253, v236, v237
	v_add_f32_e32 v195, v195, v254
	s_nop 1
	s_waitcnt lgkmcnt(8)
	v_mfma_f32_32x32x16_bf16 v[112:127], v[238:241], v[242:245], v[112:127]
	ds_read_b64_tr_b16 v[238:239], v218 offset:16640
	ds_read_b64_tr_b16 v[240:241], v218 offset:20736
	s_waitcnt lgkmcnt(8)
	v_mfma_f32_32x32x16_bf16 v[96:111], v[128:131], v[242:245], v[96:111]
	ds_read_b64_tr_b16 v[222:223], v219 offset:16640
	ds_read_b64_tr_b16 v[224:225], v219 offset:20736
	s_cmp_lg_u64 s[18:19], 0
	s_cbranch_scc1 .Latt_ndr0_5
	s_sub_i32 s100, s33, 1
	s_cmp_eq_u32 s33, 0
	s_cselect_b32 s100, 2, s100
	s_lshl_b32 s101, s100, 14
	s_add_i32 m0, s73, s101
	s_nop 0
	global_load_lds_dwordx4 v178, s[12:13]

.LBB0_1839:
	s_cmp_gt_i32 s72, s69
	s_cbranch_scc1 .LBB0_1850
	s_add_i32 s100, s72, 63
	s_cmp_le_i32 s100, s68
	s_cbranch_scc0 .Latt_slow_6
	s_lshl_b32 s98, s34, 14
	s_lshl_b32 s99, s34, 15
	s_add_i32 s99, s99, 0xc000
	v_add_u32_e32 v206, s98, v195
	ds_read_b128 v[206:209], v206
	v_add_u32_e32 v210, s98, v196
	ds_read_b128 v[210:213], v210
	v_add_u32_e32 v214, s98, v197
	ds_read_b128 v[214:217], v214
	v_add_u32_e32 v238, s98, v198
	ds_read_b128 v[238:241], v238
	v_add_u32_e32 v242, s98, v199
	ds_read_b128 v[242:245], v242
	v_add_u32_e32 v250, s98, v200
	ds_read_b128 v[250:253], v250
	v_add_u32_e32 v222, s98, v201
	ds_read_b128 v[222:225], v222
	v_add_u32_e32 v226, s98, v202
	ds_read_b128 v[226:229], v226
	v_bfe_u32 v246, v204, 2, 2
	v_bfe_u32 v247, v204, 5, 1
	v_lshl_or_b32 v247, v247, 2, v246
	v_and_b32_e32 v249, 3, v204
	v_and_b32_e32 v254, 16, v204
	v_lshl_or_b32 v249, v249, 2, v254
	v_lshlrev_b32_e32 v249, 1, v249
	v_lshl_add_u32 v247, v247, 9, v249
	v_add_u32_e32 v247, s99, v247
	v_lshlrev_b32_e32 v246, 6, v246
	v_add_u32_e32 v205, v247, v246
	v_xor_b32_e32 v249, 64, v246
	v_add_u32_e32 v218, v247, v249
	v_xor_b32_e32 v249, 0x80, v246
	v_add_u32_e32 v219, v247, v249
	v_xor_b32_e32 v249, 0xc0, v246
	v_add_u32_e32 v221, v247, v249
	s_waitcnt lgkmcnt(7)
	v_mfma_f32_32x32x16_bf16 v[128:143], v[206:209], v[144:147], 0
	v_add_u32_e32 v206, s98, v195
	ds_read_b128 v[206:209], v206 offset:8192
	s_waitcnt lgkmcnt(7)
	v_mfma_f32_32x32x16_bf16 v[128:143], v[210:213], v[148:151], v[128:143]
	v_add_u32_e32 v210, s98, v196
	ds_read_b128 v[210:213], v210 offset:8192
	s_waitcnt lgkmcnt(7)
	v_mfma_f32_32x32x16_bf16 v[128:143], v[214:217], v[152:155], v[128:143]
	v_add_u32_e32 v214, s98, v197
	ds_read_b128 v[214:217], v214 offset:8192
	s_waitcnt lgkmcnt(7)
	v_mfma_f32_32x32x16_bf16 v[128:143], v[238:241], v[156:159], v[128:143]
	v_add_u32_e32 v238, s98, v198
	ds_read_b128 v[238:241], v238 offset:8192
	s_waitcnt lgkmcnt(7)
	v_mfma_f32_32x32x16_bf16 v[128:143], v[242:245], v[160:163], v[128:143]
	s_waitcnt lgkmcnt(6)
	v_mfma_f32_32x32x16_bf16 v[128:143], v[250:253], v[164:167], v[128:143]
	s_waitcnt lgkmcnt(5)
	v_mfma_f32_32x32x16_bf16 v[128:143], v[222:225], v[168:171], v[128:143]
	s_waitcnt lgkmcnt(4)
	v_mfma_f32_32x32x16_bf16 v[128:143], v[226:229], v[172:175], v[128:143]
	s_waitcnt lgkmcnt(3)
	v_mfma_f32_32x32x16_bf16 v[222:237], v[206:209], v[144:147], 0
	v_add_u32_e32 v206, s98, v199
	ds_read_b128 v[206:209], v206 offset:8192
	s_nop 7
	v_max3_f32 v246, v128, v129, v130
	v_max3_f32 v247, v131, v132, v133
	v_max3_f32 v246, v246, v134, v135
	v_max3_f32 v247, v247, v136, v137
	v_max3_f32 v246, v246, v138, v139
	v_max3_f32 v247, v247, v140, v141
	v_max3_f32 v246, v246, v142, v143
	s_waitcnt lgkmcnt(3)
	v_mfma_f32_32x32x16_bf16 v[222:237], v[210:213], v[148:151], v[222:237]
	v_add_u32_e32 v210, s98, v200
	ds_read_b128 v[210:213], v210 offset:8192
	v_max_f32_e32 v246, v246, v247
	v_mov_b32_e32 v247, v246
	v_add_f32_e32 v249, 0x41000000, v190
	s_nop 1
	v_permlane32_swap_b32_e32 v246, v247
	v_max_f32_e32 v246, v246, v247
	v_cmp_gt_f32_e32 vcc, v246, v249
	s_cbranch_vccz .Latt_nr0_6
	v_max_f32_e32 v246, v190, v246
	v_sub_f32_e32 v190, v190, v246
	v_exp_f32_e32 v190, v190
	s_nop 0
	v_pk_mul_f32 v[126:127], v[126:127], v[190:191] op_sel_hi:[1,0]
	v_pk_mul_f32 v[124:125], v[124:125], v[190:191] op_sel_hi:[1,0]
	v_pk_mul_f32 v[122:123], v[122:123], v[190:191] op_sel_hi:[1,0]
	v_pk_mul_f32 v[120:121], v[120:121], v[190:191] op_sel_hi:[1,0]
	v_pk_mul_f32 v[118:119], v[118:119], v[190:191] op_sel_hi:[1,0]
	v_pk_mul_f32 v[116:117], v[116:117], v[190:191] op_sel_hi:[1,0]
	v_pk_mul_f32 v[114:115], v[114:115], v[190:191] op_sel_hi:[1,0]
	v_pk_mul_f32 v[112:113], v[112:113], v[190:191] op_sel_hi:[1,0]
	v_pk_mul_f32 v[110:111], v[110:111], v[190:191] op_sel_hi:[1,0]
	v_pk_mul_f32 v[108:109], v[108:109], v[190:191] op_sel_hi:[1,0]
	v_pk_mul_f32 v[106:107], v[106:107], v[190:191] op_sel_hi:[1,0]
	v_pk_mul_f32 v[104:105], v[104:105], v[190:191] op_sel_hi:[1,0]
	v_pk_mul_f32 v[102:103], v[102:103], v[190:191] op_sel_hi:[1,0]
	v_pk_mul_f32 v[100:101], v[100:101], v[190:191] op_sel_hi:[1,0]
	v_pk_mul_f32 v[98:99], v[98:99], v[190:191] op_sel_hi:[1,0]
	v_pk_mul_f32 v[96:97], v[96:97], v[190:191] op_sel_hi:[1,0]
	v_pk_mul_f32 v[94:95], v[94:95], v[190:191] op_sel_hi:[1,0]
	v_pk_mul_f32 v[92:93], v[92:93], v[190:191] op_sel_hi:[1,0]
	v_pk_mul_f32 v[90:91], v[90:91], v[190:191] op_sel_hi:[1,0]
	v_pk_mul_f32 v[88:89], v[88:89], v[190:191] op_sel_hi:[1,0]
	v_pk_mul_f32 v[86:87], v[86:87], v[190:191] op_sel_hi:[1,0]
	v_pk_mul_f32 v[84:85], v[84:85], v[190:191] op_sel_hi:[1,0]
	v_pk_mul_f32 v[82:83], v[82:83], v[190:191] op_sel_hi:[1,0]
	v_pk_mul_f32 v[80:81], v[80:81], v[190:191] op_sel_hi:[1,0]
	v_pk_mul_f32 v[78:79], v[78:79], v[190:191] op_sel_hi:[1,0]
	v_pk_mul_f32 v[76:77], v[76:77], v[190:191] op_sel_hi:[1,0]
	v_pk_mul_f32 v[74:75], v[74:75], v[190:191] op_sel_hi:[1,0]
	v_pk_mul_f32 v[72:73], v[72:73], v[190:191] op_sel_hi:[1,0]
	v_pk_mul_f32 v[70:71], v[70:71], v[190:191] op_sel_hi:[1,0]
	v_pk_mul_f32 v[68:69], v[68:69], v[190:191] op_sel_hi:[1,0]
	v_pk_mul_f32 v[66:67], v[66:67], v[190:191] op_sel_hi:[1,0]
	v_pk_mul_f32 v[64:65], v[64:65], v[190:191] op_sel_hi:[1,0]
	v_pk_mul_f32 v[62:63], v[62:63], v[190:191] op_sel_hi:[1,0]
	v_pk_mul_f32 v[60:61], v[60:61], v[190:191] op_sel_hi:[1,0]
	v_pk_mul_f32 v[58:59], v[58:59], v[190:191] op_sel_hi:[1,0]
	v_pk_mul_f32 v[56:57], v[56:57], v[190:191] op_sel_hi:[1,0]
	v_pk_mul_f32 v[54:55], v[54:55], v[190:191] op_sel_hi:[1,0]
	v_pk_mul_f32 v[52:53], v[52:53], v[190:191] op_sel_hi:[1,0]
	v_pk_mul_f32 v[50:51], v[50:51], v[190:191] op_sel_hi:[1,0]
	v_pk_mul_f32 v[48:49], v[48:49], v[190:191] op_sel_hi:[1,0]
	v_pk_mul_f32 v[46:47], v[46:47], v[190:191] op_sel_hi:[1,0]
	v_pk_mul_f32 v[44:45], v[44:45], v[190:191] op_sel_hi:[1,0]
	v_pk_mul_f32 v[42:43], v[42:43], v[190:191] op_sel_hi:[1,0]
	v_pk_mul_f32 v[40:41], v[40:41], v[190:191] op_sel_hi:[1,0]
	v_pk_mul_f32 v[38:39], v[38:39], v[190:191] op_sel_hi:[1,0]
	v_pk_mul_f32 v[36:37], v[36:37], v[190:191] op_sel_hi:[1,0]
	v_pk_mul_f32 v[34:35], v[34:35], v[190:191] op_sel_hi:[1,0]
	v_pk_mul_f32 v[32:33], v[32:33], v[190:191] op_sel_hi:[1,0]
	v_pk_mul_f32 v[30:31], v[30:31], v[190:191] op_sel_hi:[1,0]
	v_pk_mul_f32 v[28:29], v[28:29], v[190:191] op_sel_hi:[1,0]
	v_pk_mul_f32 v[26:27], v[26:27], v[190:191] op_sel_hi:[1,0]
	v_pk_mul_f32 v[24:25], v[24:25], v[190:191] op_sel_hi:[1,0]
	v_pk_mul_f32 v[22:23], v[22:23], v[190:191] op_sel_hi:[1,0]
	v_pk_mul_f32 v[20:21], v[20:21], v[190:191] op_sel_hi:[1,0]
	v_pk_mul_f32 v[18:19], v[18:19], v[190:191] op_sel_hi:[1,0]
	v_pk_mul_f32 v[16:17], v[16:17], v[190:191] op_sel_hi:[1,0]
	v_pk_mul_f32 v[14:15], v[14:15], v[190:191] op_sel_hi:[1,0]
	v_pk_mul_f32 v[12:13], v[12:13], v[190:191] op_sel_hi:[1,0]
	v_pk_mul_f32 v[10:11], v[10:11], v[190:191] op_sel_hi:[1,0]
	v_pk_mul_f32 v[8:9], v[8:9], v[190:191] op_sel_hi:[1,0]
	v_pk_mul_f32 v[6:7], v[6:7], v[190:191] op_sel_hi:[1,0]
	v_pk_mul_f32 v[4:5], v[4:5], v[190:191] op_sel_hi:[1,0]
	v_pk_mul_f32 v[2:3], v[2:3], v[190:191] op_sel_hi:[1,0]
	v_pk_mul_f32 v[0:1], v[0:1], v[190:191] op_sel_hi:[1,0]
	v_mul_f32_e32 v203, v203, v190
	v_mov_b32_e32 v190, v246
.Latt_nr0_6:
	s_waitcnt lgkmcnt(3)
	v_mfma_f32_32x32x16_bf16 v[222:237], v[214:217], v[152:155], v[222:237]
	v_add_u32_e32 v214, s98, v201
	ds_read_b128 v[214:217], v214 offset:8192
	v_sub_f32_e32 v128, v128, v190
	v_exp_f32_e32 v128, v128
	v_sub_f32_e32 v129, v129, v190
	v_exp_f32_e32 v129, v129
	v_sub_f32_e32 v130, v130, v190
	s_waitcnt lgkmcnt(3)
	v_mfma_f32_32x32x16_bf16 v[222:237], v[238:241], v[156:159], v[222:237]
	v_add_u32_e32 v238, s98, v202
	ds_read_b128 v[238:241], v238 offset:8192
	v_add_f32_e32 v254, 0, v128
	v_exp_f32_e32 v130, v130
	v_sub_f32_e32 v131, v131, v190
	v_add_f32_e32 v254, v129, v254
	v_exp_f32_e32 v131, v131
	s_waitcnt lgkmcnt(3)
	v_mfma_f32_32x32x16_bf16 v[222:237], v[206:209], v[160:163], v[222:237]
	ds_read_b64_tr_b16 v[206:207], v205
	ds_read_b64_tr_b16 v[208:209], v205 offset:4096
	v_sub_f32_e32 v132, v132, v190
	v_add_f32_e32 v254, v130, v254
	v_exp_f32_e32 v132, v132
	v_sub_f32_e32 v133, v133, v190
	v_add_f32_e32 v254, v131, v254
	s_waitcnt lgkmcnt(4)
	v_mfma_f32_32x32x16_bf16 v[222:237], v[210:213], v[164:167], v[222:237]
	ds_read_b64_tr_b16 v[210:211], v218
	ds_read_b64_tr_b16 v[212:213], v218 offset:4096
	v_exp_f32_e32 v133, v133
	v_sub_f32_e32 v134, v134, v190
	v_add_f32_e32 v254, v132, v254
	v_exp_f32_e32 v134, v134
	s_waitcnt lgkmcnt(5)
	v_mfma_f32_32x32x16_bf16 v[222:237], v[214:217], v[168:171], v[222:237]
	ds_read_b64_tr_b16 v[214:215], v219
	ds_read_b64_tr_b16 v[216:217], v219 offset:4096
	v_sub_f32_e32 v135, v135, v190
	v_add_f32_e32 v254, v133, v254
	v_exp_f32_e32 v135, v135
	s_nop 0
	s_waitcnt lgkmcnt(6)
	v_mfma_f32_32x32x16_bf16 v[222:237], v[238:241], v[172:175], v[222:237]
	ds_read_b64_tr_b16 v[238:239], v221
	ds_read_b64_tr_b16 v[240:241], v221 offset:4096
	v_cvt_pk_bf16_f32 v242, v128, v129
	v_cvt_pk_bf16_f32 v243, v130, v131
	v_cvt_pk_bf16_f32 v244, v132, v133
	v_cvt_pk_bf16_f32 v245, v134, v135
	s_nop 1
	s_waitcnt lgkmcnt(6)
	v_mfma_f32_32x32x16_bf16 v[112:127], v[206:209], v[242:245], v[112:127]
	ds_read_b64_tr_b16 v[206:207], v205 offset:256
	ds_read_b64_tr_b16 v[208:209], v205 offset:4352
	v_sub_f32_e32 v136, v136, v190
	v_add_f32_e32 v254, v134, v254
	v_exp_f32_e32 v136, v136
	v_sub_f32_e32 v137, v137, v190
	v_add_f32_e32 v254, v135, v254
	s_waitcnt lgkmcnt(6)
	v_mfma_f32_32x32x16_bf16 v[96:111], v[210:213], v[242:245], v[96:111]
	ds_read_b64_tr_b16 v[210:211], v218 offset:256
	ds_read_b64_tr_b16 v[212:213], v218 offset:4352
	v_exp_f32_e32 v137, v137
	v_sub_f32_e32 v138, v138, v190
	v_add_f32_e32 v254, v136, v254
	v_exp_f32_e32 v138, v138
	v_sub_f32_e32 v139, v139, v190
	s_waitcnt lgkmcnt(6)
	v_mfma_f32_32x32x16_bf16 v[80:95], v[214:217], v[242:245], v[80:95]
	ds_read_b64_tr_b16 v[214:215], v219 offset:256
	ds_read_b64_tr_b16 v[216:217], v219 offset:4352
	v_add_f32_e32 v254, v137, v254
	v_exp_f32_e32 v139, v139
	v_sub_f32_e32 v140, v140, v190
	v_add_f32_e32 v254, v138, v254
	s_waitcnt lgkmcnt(6)
	v_mfma_f32_32x32x16_bf16 v[64:79], v[238:241], v[242:245], v[64:79]
	ds_read_b64_tr_b16 v[238:239], v221 offset:256
	ds_read_b64_tr_b16 v[240:241], v221 offset:4352
	v_exp_f32_e32 v140, v140
	v_sub_f32_e32 v141, v141, v190
	v_add_f32_e32 v254, v139, v254
	v_exp_f32_e32 v141, v141
	s_waitcnt lgkmcnt(6)
	v_mfma_f32_32x32x16_bf16 v[48:63], v[206:209], v[242:245], v[48:63]
	ds_read_b64_tr_b16 v[206:207], v205 offset:8192
	ds_read_b64_tr_b16 v[208:209], v205 offset:12288
	v_sub_f32_e32 v142, v142, v190
	v_add_f32_e32 v254, v140, v254
	v_exp_f32_e32 v142, v142
	v_sub_f32_e32 v143, v143, v190
	s_waitcnt lgkmcnt(6)
	v_mfma_f32_32x32x16_bf16 v[32:47], v[210:213], v[242:245], v[32:47]
	ds_read_b64_tr_b16 v[210:211], v218 offset:8192
	ds_read_b64_tr_b16 v[212:213], v218 offset:12288
	v_add_f32_e32 v254, v141, v254
	v_exp_f32_e32 v143, v143
	v_add_f32_e32 v254, v142, v254
	v_add_f32_e32 v254, v143, v254
	s_waitcnt lgkmcnt(6)
	v_mfma_f32_32x32x16_bf16 v[16:31], v[214:217], v[242:245], v[16:31]
	ds_read_b64_tr_b16 v[214:215], v219 offset:8192
	ds_read_b64_tr_b16 v[216:217], v219 offset:12288
	v_cvt_pk_bf16_f32 v250, v136, v137
	v_cvt_pk_bf16_f32 v251, v138, v139
	v_cvt_pk_bf16_f32 v252, v140, v141
	v_cvt_pk_bf16_f32 v253, v142, v143
	v_add_f32_e32 v203, v203, v254
	s_waitcnt lgkmcnt(6)
	v_mfma_f32_32x32x16_bf16 v[0:15], v[238:241], v[242:245], v[0:15]
	ds_read_b64_tr_b16 v[238:239], v221 offset:8192
	ds_read_b64_tr_b16 v[240:241], v221 offset:12288
	ds_read_b64_tr_b16 v[128:129], v205 offset:8448
	ds_read_b64_tr_b16 v[130:131], v205 offset:12544
	s_waitcnt lgkmcnt(8)
	v_mfma_f32_32x32x16_bf16 v[112:127], v[206:209], v[250:253], v[112:127]
	ds_read_b64_tr_b16 v[206:207], v218 offset:8448
	ds_read_b64_tr_b16 v[208:209], v218 offset:12544
	v_max3_f32 v246, v222, v223, v224
	v_max3_f32 v247, v225, v226, v227
	v_max3_f32 v246, v246, v228, v229
	v_max3_f32 v247, v247, v230, v231
	v_max3_f32 v246, v246, v232, v233
	v_max3_f32 v247, v247, v234, v235
	s_waitcnt lgkmcnt(8)
	v_mfma_f32_32x32x16_bf16 v[96:111], v[210:213], v[250:253], v[96:111]
	ds_read_b64_tr_b16 v[210:211], v219 offset:8448
	ds_read_b64_tr_b16 v[212:213], v219 offset:12544
	v_max3_f32 v246, v246, v236, v237
	v_max_f32_e32 v246, v246, v247
	v_mov_b32_e32 v247, v246
	v_add_f32_e32 v249, 0x41000000, v190
	s_nop 1
	s_waitcnt lgkmcnt(8)
	v_mfma_f32_32x32x16_bf16 v[80:95], v[214:217], v[250:253], v[80:95]
	ds_read_b64_tr_b16 v[214:215], v221 offset:8448
	ds_read_b64_tr_b16 v[216:217], v221 offset:12544
	v_permlane32_swap_b32_e32 v246, v247
	v_max_f32_e32 v246, v246, v247
	v_cmp_gt_f32_e32 vcc, v246, v249
	s_cbranch_vccnz .Latt_rs1_6
	s_waitcnt lgkmcnt(8)
	v_mfma_f32_32x32x16_bf16 v[64:79], v[238:241], v[250:253], v[64:79]
	ds_read_b64_tr_b16 v[238:239], v205 offset:16384
	ds_read_b64_tr_b16 v[240:241], v205 offset:20480
	v_sub_f32_e32 v222, v222, v190
	v_exp_f32_e32 v222, v222
	v_sub_f32_e32 v223, v223, v190
	v_exp_f32_e32 v223, v223
	v_sub_f32_e32 v224, v224, v190
	v_add_f32_e32 v254, 0, v222
	s_waitcnt lgkmcnt(8)
	v_mfma_f32_32x32x16_bf16 v[48:63], v[128:131], v[250:253], v[48:63]
	ds_read_b64_tr_b16 v[128:129], v218 offset:16384
	ds_read_b64_tr_b16 v[130:131], v218 offset:20480
	v_exp_f32_e32 v224, v224
	v_sub_f32_e32 v225, v225, v190
	v_add_f32_e32 v254, v223, v254
	v_exp_f32_e32 v225, v225
	v_sub_f32_e32 v226, v226, v190
	v_add_f32_e32 v254, v224, v254
	s_waitcnt lgkmcnt(8)
	v_mfma_f32_32x32x16_bf16 v[32:47], v[206:209], v[250:253], v[32:47]
	ds_read_b64_tr_b16 v[206:207], v219 offset:16384
	ds_read_b64_tr_b16 v[208:209], v219 offset:20480
	v_exp_f32_e32 v226, v226
	v_sub_f32_e32 v227, v227, v190
	v_add_f32_e32 v254, v225, v254
	v_exp_f32_e32 v227, v227
	v_sub_f32_e32 v228, v228, v190
	s_waitcnt lgkmcnt(8)
	v_mfma_f32_32x32x16_bf16 v[16:31], v[210:213], v[250:253], v[16:31]
	ds_read_b64_tr_b16 v[210:211], v221 offset:16384
	ds_read_b64_tr_b16 v[212:213], v221 offset:20480
	v_add_f32_e32 v254, v226, v254
	v_exp_f32_e32 v228, v228
	v_sub_f32_e32 v229, v229, v190
	v_add_f32_e32 v254, v227, v254
	v_exp_f32_e32 v229, v229
	s_waitcnt lgkmcnt(8)
	v_mfma_f32_32x32x16_bf16 v[0:15], v[214:217], v[250:253], v[0:15]
	ds_read_b64_tr_b16 v[214:215], v205 offset:16640
	ds_read_b64_tr_b16 v[216:217], v205 offset:20736
	s_nop 0
	v_cvt_pk_bf16_f32 v242, v222, v223
	v_cvt_pk_bf16_f32 v243, v224, v225
	v_cvt_pk_bf16_f32 v244, v226, v227
	v_cvt_pk_bf16_f32 v245, v228, v229
	s_nop 1
	s_waitcnt lgkmcnt(8)
	v_mfma_f32_32x32x16_bf16 v[112:127], v[238:241], v[242:245], v[112:127]
	ds_read_b64_tr_b16 v[238:239], v218 offset:16640
	ds_read_b64_tr_b16 v[240:241], v218 offset:20736
	v_sub_f32_e32 v230, v230, v190
	v_add_f32_e32 v254, v228, v254
	v_exp_f32_e32 v230, v230
	v_sub_f32_e32 v231, v231, v190
	v_add_f32_e32 v254, v229, v254
	s_waitcnt lgkmcnt(8)
	v_mfma_f32_32x32x16_bf16 v[96:111], v[128:131], v[242:245], v[96:111]
	ds_read_b64_tr_b16 v[128:129], v219 offset:16640
	ds_read_b64_tr_b16 v[130:131], v219 offset:20736
	v_exp_f32_e32 v231, v231
	v_sub_f32_e32 v232, v232, v190
	v_add_f32_e32 v254, v230, v254
	v_exp_f32_e32 v232, v232
	v_sub_f32_e32 v233, v233, v190
	s_cmp_lg_u64 s[12:13], 0
	s_cbranch_scc1 .Latt_nd0_6
	s_sub_i32 s100, s34, 1
	s_cmp_eq_u32 s34, 0
	s_cselect_b32 s100, 2, s100
	s_lshl_b32 s101, s100, 14
	s_add_i32 m0, s36, s101
	s_nop 0
	global_load_lds_dwordx4 v178, s[20:21]
.Latt_nd0_6:
	s_waitcnt lgkmcnt(8)
	v_mfma_f32_32x32x16_bf16 v[80:95], v[206:209], v[242:245], v[80:95]
	ds_read_b64_tr_b16 v[206:207], v221 offset:16640
	ds_read_b64_tr_b16 v[208:209], v221 offset:20736
	v_add_f32_e32 v254, v231, v254
	v_exp_f32_e32 v233, v233
	v_sub_f32_e32 v234, v234, v190
	v_add_f32_e32 v254, v232, v254
	s_waitcnt lgkmcnt(8)
	v_mfma_f32_32x32x16_bf16 v[64:79], v[210:213], v[242:245], v[64:79]
	ds_read_b64_tr_b16 v[210:211], v205 offset:24576
	ds_read_b64_tr_b16 v[212:213], v205 offset:28672
	v_exp_f32_e32 v234, v234
	v_sub_f32_e32 v235, v235, v190
	v_add_f32_e32 v254, v233, v254
	v_exp_f32_e32 v235, v235
	s_cmp_lg_u64 s[12:13], 0
	s_cbranch_scc1 .Latt_nd1_6
	s_add_i32 m0, m0, 0x400
	s_nop 0
	global_load_lds_dwordx4 v180, s[20:21]
.Latt_nd1_6:
	s_waitcnt lgkmcnt(8)
	v_mfma_f32_32x32x16_bf16 v[48:63], v[214:217], v[242:245], v[48:63]
	ds_read_b64_tr_b16 v[214:215], v218 offset:24576
	ds_read_b64_tr_b16 v[216:217], v218 offset:28672
	v_sub_f32_e32 v236, v236, v190
	v_add_f32_e32 v254, v234, v254
	v_exp_f32_e32 v236, v236
	v_sub_f32_e32 v237, v237, v190
	s_waitcnt lgkmcnt(8)
	v_mfma_f32_32x32x16_bf16 v[32:47], v[238:241], v[242:245], v[32:47]
	ds_read_b64_tr_b16 v[238:239], v219 offset:24576
	ds_read_b64_tr_b16 v[240:241], v219 offset:28672
	v_add_f32_e32 v254, v235, v254
	v_exp_f32_e32 v237, v237
	v_add_f32_e32 v254, v236, v254
	v_add_f32_e32 v254, v237, v254
	s_cmp_lg_u64 s[12:13], 0
	s_cbranch_scc1 .Latt_nd2_6
	s_lshl_b32 s101, s100, 15
	s_add_i32 m0, s37, s101
	s_add_u32 s100, s20, 0x1000
	s_addc_u32 s101, s21, 0
	global_load_lds_dwordx4 v182, s[100:101]

.Latt_rs1_6:
	s_waitcnt lgkmcnt(8)
	v_mfma_f32_32x32x16_bf16 v[64:79], v[238:241], v[250:253], v[64:79]
	ds_read_b64_tr_b16 v[238:239], v205 offset:16384
	ds_read_b64_tr_b16 v[240:241], v205 offset:20480
	s_waitcnt lgkmcnt(8)
	v_mfma_f32_32x32x16_bf16 v[48:63], v[128:131], v[250:253], v[48:63]
	ds_read_b64_tr_b16 v[128:129], v218 offset:16384
	ds_read_b64_tr_b16 v[130:131], v218 offset:20480
	s_waitcnt lgkmcnt(8)
	v_mfma_f32_32x32x16_bf16 v[32:47], v[206:209], v[250:253], v[32:47]
	ds_read_b64_tr_b16 v[206:207], v219 offset:16384
	ds_read_b64_tr_b16 v[208:209], v219 offset:20480
	s_waitcnt lgkmcnt(8)
	v_mfma_f32_32x32x16_bf16 v[16:31], v[210:213], v[250:253], v[16:31]
	ds_read_b64_tr_b16 v[210:211], v221 offset:16384
	ds_read_b64_tr_b16 v[212:213], v221 offset:20480
	s_waitcnt lgkmcnt(8)
	v_mfma_f32_32x32x16_bf16 v[0:15], v[214:217], v[250:253], v[0:15]
	ds_read_b64_tr_b16 v[214:215], v205 offset:16640
	ds_read_b64_tr_b16 v[216:217], v205 offset:20736
	s_nop 11
	v_max_f32_e32 v246, v190, v246
	v_sub_f32_e32 v190, v190, v246
	v_exp_f32_e32 v190, v190
	s_nop 0
	v_pk_mul_f32 v[126:127], v[126:127], v[190:191] op_sel_hi:[1,0]
	v_pk_mul_f32 v[124:125], v[124:125], v[190:191] op_sel_hi:[1,0]
	v_pk_mul_f32 v[122:123], v[122:123], v[190:191] op_sel_hi:[1,0]
	v_pk_mul_f32 v[120:121], v[120:121], v[190:191] op_sel_hi:[1,0]
	v_pk_mul_f32 v[118:119], v[118:119], v[190:191] op_sel_hi:[1,0]
	v_pk_mul_f32 v[116:117], v[116:117], v[190:191] op_sel_hi:[1,0]
	v_pk_mul_f32 v[114:115], v[114:115], v[190:191] op_sel_hi:[1,0]
	v_pk_mul_f32 v[112:113], v[112:113], v[190:191] op_sel_hi:[1,0]
	v_pk_mul_f32 v[110:111], v[110:111], v[190:191] op_sel_hi:[1,0]
	v_pk_mul_f32 v[108:109], v[108:109], v[190:191] op_sel_hi:[1,0]
	v_pk_mul_f32 v[106:107], v[106:107], v[190:191] op_sel_hi:[1,0]
	v_pk_mul_f32 v[104:105], v[104:105], v[190:191] op_sel_hi:[1,0]
	v_pk_mul_f32 v[102:103], v[102:103], v[190:191] op_sel_hi:[1,0]
	v_pk_mul_f32 v[100:101], v[100:101], v[190:191] op_sel_hi:[1,0]
	v_pk_mul_f32 v[98:99], v[98:99], v[190:191] op_sel_hi:[1,0]
	v_pk_mul_f32 v[96:97], v[96:97], v[190:191] op_sel_hi:[1,0]
	v_pk_mul_f32 v[94:95], v[94:95], v[190:191] op_sel_hi:[1,0]
	v_pk_mul_f32 v[92:93], v[92:93], v[190:191] op_sel_hi:[1,0]
	v_pk_mul_f32 v[90:91], v[90:91], v[190:191] op_sel_hi:[1,0]
	v_pk_mul_f32 v[88:89], v[88:89], v[190:191] op_sel_hi:[1,0]
	v_pk_mul_f32 v[86:87], v[86:87], v[190:191] op_sel_hi:[1,0]
	v_pk_mul_f32 v[84:85], v[84:85], v[190:191] op_sel_hi:[1,0]
	v_pk_mul_f32 v[82:83], v[82:83], v[190:191] op_sel_hi:[1,0]
	v_pk_mul_f32 v[80:81], v[80:81], v[190:191] op_sel_hi:[1,0]
	v_pk_mul_f32 v[78:79], v[78:79], v[190:191] op_sel_hi:[1,0]
	v_pk_mul_f32 v[76:77], v[76:77], v[190:191] op_sel_hi:[1,0]
	v_pk_mul_f32 v[74:75], v[74:75], v[190:191] op_sel_hi:[1,0]
	v_pk_mul_f32 v[72:73], v[72:73], v[190:191] op_sel_hi:[1,0]
	v_pk_mul_f32 v[70:71], v[70:71], v[190:191] op_sel_hi:[1,0]
	v_pk_mul_f32 v[68:69], v[68:69], v[190:191] op_sel_hi:[1,0]
	v_pk_mul_f32 v[66:67], v[66:67], v[190:191] op_sel_hi:[1,0]
	v_pk_mul_f32 v[64:65], v[64:65], v[190:191] op_sel_hi:[1,0]
	v_pk_mul_f32 v[62:63], v[62:63], v[190:191] op_sel_hi:[1,0]
	v_pk_mul_f32 v[60:61], v[60:61], v[190:191] op_sel_hi:[1,0]
	v_pk_mul_f32 v[58:59], v[58:59], v[190:191] op_sel_hi:[1,0]
	v_pk_mul_f32 v[56:57], v[56:57], v[190:191] op_sel_hi:[1,0]
	v_pk_mul_f32 v[54:55], v[54:55], v[190:191] op_sel_hi:[1,0]
	v_pk_mul_f32 v[52:53], v[52:53], v[190:191] op_sel_hi:[1,0]
	v_pk_mul_f32 v[50:51], v[50:51], v[190:191] op_sel_hi:[1,0]
	v_pk_mul_f32 v[48:49], v[48:49], v[190:191] op_sel_hi:[1,0]
	v_pk_mul_f32 v[46:47], v[46:47], v[190:191] op_sel_hi:[1,0]
	v_pk_mul_f32 v[44:45], v[44:45], v[190:191] op_sel_hi:[1,0]
	v_pk_mul_f32 v[42:43], v[42:43], v[190:191] op_sel_hi:[1,0]
	v_pk_mul_f32 v[40:41], v[40:41], v[190:191] op_sel_hi:[1,0]
	v_pk_mul_f32 v[38:39], v[38:39], v[190:191] op_sel_hi:[1,0]
	v_pk_mul_f32 v[36:37], v[36:37], v[190:191] op_sel_hi:[1,0]
	v_pk_mul_f32 v[34:35], v[34:35], v[190:191] op_sel_hi:[1,0]
	v_pk_mul_f32 v[32:33], v[32:33], v[190:191] op_sel_hi:[1,0]
	v_pk_mul_f32 v[30:31], v[30:31], v[190:191] op_sel_hi:[1,0]
	v_pk_mul_f32 v[28:29], v[28:29], v[190:191] op_sel_hi:[1,0]
	v_pk_mul_f32 v[26:27], v[26:27], v[190:191] op_sel_hi:[1,0]
	v_pk_mul_f32 v[24:25], v[24:25], v[190:191] op_sel_hi:[1,0]
	v_pk_mul_f32 v[22:23], v[22:23], v[190:191] op_sel_hi:[1,0]
	v_pk_mul_f32 v[20:21], v[20:21], v[190:191] op_sel_hi:[1,0]
	v_pk_mul_f32 v[18:19], v[18:19], v[190:191] op_sel_hi:[1,0]
	v_pk_mul_f32 v[16:17], v[16:17], v[190:191] op_sel_hi:[1,0]
	v_pk_mul_f32 v[14:15], v[14:15], v[190:191] op_sel_hi:[1,0]
	v_pk_mul_f32 v[12:13], v[12:13], v[190:191] op_sel_hi:[1,0]
	v_pk_mul_f32 v[10:11], v[10:11], v[190:191] op_sel_hi:[1,0]
	v_pk_mul_f32 v[8:9], v[8:9], v[190:191] op_sel_hi:[1,0]
	v_pk_mul_f32 v[6:7], v[6:7], v[190:191] op_sel_hi:[1,0]
	v_pk_mul_f32 v[4:5], v[4:5], v[190:191] op_sel_hi:[1,0]
	v_pk_mul_f32 v[2:3], v[2:3], v[190:191] op_sel_hi:[1,0]
	v_pk_mul_f32 v[0:1], v[0:1], v[190:191] op_sel_hi:[1,0]
	v_mul_f32_e32 v203, v203, v190
	v_mov_b32_e32 v190, v246
	v_sub_f32_e32 v222, v222, v190
	v_exp_f32_e32 v222, v222
	v_sub_f32_e32 v223, v223, v190
	v_exp_f32_e32 v223, v223
	v_sub_f32_e32 v224, v224, v190
	v_add_f32_e32 v254, 0, v222
	v_exp_f32_e32 v224, v224
	v_sub_f32_e32 v225, v225, v190
	v_add_f32_e32 v254, v223, v254
	v_exp_f32_e32 v225, v225
	v_sub_f32_e32 v226, v226, v190
	v_add_f32_e32 v254, v224, v254
	v_exp_f32_e32 v226, v226
	v_sub_f32_e32 v227, v227, v190
	v_add_f32_e32 v254, v225, v254
	v_exp_f32_e32 v227, v227
	v_sub_f32_e32 v228, v228, v190
	v_add_f32_e32 v254, v226, v254
	v_exp_f32_e32 v228, v228
	v_sub_f32_e32 v229, v229, v190
	v_add_f32_e32 v254, v227, v254
	v_exp_f32_e32 v229, v229
	v_sub_f32_e32 v230, v230, v190
	v_add_f32_e32 v254, v228, v254
	v_exp_f32_e32 v230, v230
	v_sub_f32_e32 v231, v231, v190
	v_add_f32_e32 v254, v229, v254
	v_exp_f32_e32 v231, v231
	v_sub_f32_e32 v232, v232, v190
	v_add_f32_e32 v254, v230, v254
	v_exp_f32_e32 v232, v232
	v_sub_f32_e32 v233, v233, v190
	v_add_f32_e32 v254, v231, v254
	v_exp_f32_e32 v233, v233
	v_sub_f32_e32 v234, v234, v190
	v_add_f32_e32 v254, v232, v254
	v_exp_f32_e32 v234, v234
	v_sub_f32_e32 v235, v235, v190
	v_add_f32_e32 v254, v233, v254
	v_exp_f32_e32 v235, v235
	v_sub_f32_e32 v236, v236, v190
	v_add_f32_e32 v254, v234, v254
	v_exp_f32_e32 v236, v236
	v_sub_f32_e32 v237, v237, v190
	v_add_f32_e32 v254, v235, v254
	v_exp_f32_e32 v237, v237
	v_add_f32_e32 v254, v236, v254
	v_add_f32_e32 v254, v237, v254
	v_cvt_pk_bf16_f32 v242, v222, v223
	v_cvt_pk_bf16_f32 v243, v224, v225
	v_cvt_pk_bf16_f32 v244, v226, v227
	v_cvt_pk_bf16_f32 v245, v228, v229
	v_cvt_pk_bf16_f32 v250, v230, v231
	v_cvt_pk_bf16_f32 v251, v232, v233
	v_cvt_pk_bf16_f32 v252, v234, v235
	v_cvt_pk_bf16_f32 v253, v236, v237
	v_add_f32_e32 v203, v203, v254
	s_nop 1
	s_waitcnt lgkmcnt(8)
	v_mfma_f32_32x32x16_bf16 v[112:127], v[238:241], v[242:245], v[112:127]
	ds_read_b64_tr_b16 v[238:239], v218 offset:16640
	ds_read_b64_tr_b16 v[240:241], v218 offset:20736
	s_waitcnt lgkmcnt(8)
	v_mfma_f32_32x32x16_bf16 v[96:111], v[128:131], v[242:245], v[96:111]
	ds_read_b64_tr_b16 v[222:223], v219 offset:16640
	ds_read_b64_tr_b16 v[224:225], v219 offset:20736
	s_cmp_lg_u64 s[12:13], 0
	s_cbranch_scc1 .Latt_ndr0_6
	s_sub_i32 s100, s34, 1
	s_cmp_eq_u32 s34, 0
	s_cselect_b32 s100, 2, s100
	s_lshl_b32 s101, s100, 14
	s_add_i32 m0, s36, s101
	s_nop 0
	global_load_lds_dwordx4 v178, s[20:21]
.Latt_ndr0_6:
	s_waitcnt lgkmcnt(8)
	v_mfma_f32_32x32x16_bf16 v[80:95], v[206:209], v[242:245], v[80:95]
	ds_read_b64_tr_b16 v[206:207], v221 offset:16640
	ds_read_b64_tr_b16 v[208:209], v221 offset:20736
	s_waitcnt lgkmcnt(8)
	v_mfma_f32_32x32x16_bf16 v[64:79], v[210:213], v[242:245], v[64:79]
	ds_read_b64_tr_b16 v[210:211], v205 offset:24576
	ds_read_b64_tr_b16 v[212:213], v205 offset:28672
	s_cmp_lg_u64 s[12:13], 0
	s_cbranch_scc1 .Latt_ndr1_6
	s_add_i32 m0, m0, 0x400
	s_nop 0
	global_load_lds_dwordx4 v180, s[20:21]

.LBB0_1858:
	s_cmp_gt_i32 s14, s69
	s_cbranch_scc1 .LBB0_1869
	s_add_i32 s100, s14, 63
	s_cmp_le_i32 s100, s68
	s_cbranch_scc0 .Latt_slow_7
	s_lshl_b32 s98, s11, 14
	s_lshl_b32 s99, s11, 15
	s_add_i32 s99, s99, 0xc000
	v_add_u32_e32 v206, s98, v196
	ds_read_b128 v[206:209], v206
	v_add_u32_e32 v210, s98, v197
	ds_read_b128 v[210:213], v210
	v_add_u32_e32 v214, s98, v198
	ds_read_b128 v[214:217], v214
	v_add_u32_e32 v238, s98, v199
	ds_read_b128 v[238:241], v238
	v_add_u32_e32 v242, s98, v200
	ds_read_b128 v[242:245], v242
	v_add_u32_e32 v250, s98, v201
	ds_read_b128 v[250:253], v250
	v_add_u32_e32 v222, s98, v202
	ds_read_b128 v[222:225], v222
	v_add_u32_e32 v226, s98, v203
	ds_read_b128 v[226:229], v226
	v_bfe_u32 v246, v204, 2, 2
	v_bfe_u32 v247, v204, 5, 1
	v_lshl_or_b32 v247, v247, 2, v246
	v_and_b32_e32 v249, 3, v204
	v_and_b32_e32 v254, 16, v204
	v_lshl_or_b32 v249, v249, 2, v254
	v_lshlrev_b32_e32 v249, 1, v249
	v_lshl_add_u32 v247, v247, 9, v249
	v_add_u32_e32 v247, s99, v247
	v_lshlrev_b32_e32 v246, 6, v246
	v_add_u32_e32 v205, v247, v246
	v_xor_b32_e32 v249, 64, v246
	v_add_u32_e32 v218, v247, v249
	v_xor_b32_e32 v249, 0x80, v246
	v_add_u32_e32 v219, v247, v249
	v_xor_b32_e32 v249, 0xc0, v246
	v_add_u32_e32 v221, v247, v249
	s_waitcnt lgkmcnt(7)
	v_mfma_f32_32x32x16_bf16 v[128:143], v[206:209], v[144:147], 0
	v_add_u32_e32 v206, s98, v196
	ds_read_b128 v[206:209], v206 offset:8192
	s_waitcnt lgkmcnt(7)
	v_mfma_f32_32x32x16_bf16 v[128:143], v[210:213], v[148:151], v[128:143]
	v_add_u32_e32 v210, s98, v197
	ds_read_b128 v[210:213], v210 offset:8192
	s_waitcnt lgkmcnt(7)
	v_mfma_f32_32x32x16_bf16 v[128:143], v[214:217], v[152:155], v[128:143]
	v_add_u32_e32 v214, s98, v198
	ds_read_b128 v[214:217], v214 offset:8192
	s_waitcnt lgkmcnt(7)
	v_mfma_f32_32x32x16_bf16 v[128:143], v[238:241], v[156:159], v[128:143]
	v_add_u32_e32 v238, s98, v199
	ds_read_b128 v[238:241], v238 offset:8192
	s_waitcnt lgkmcnt(7)
	v_mfma_f32_32x32x16_bf16 v[128:143], v[242:245], v[160:163], v[128:143]
	s_waitcnt lgkmcnt(6)
	v_mfma_f32_32x32x16_bf16 v[128:143], v[250:253], v[164:167], v[128:143]
	s_waitcnt lgkmcnt(5)
	v_mfma_f32_32x32x16_bf16 v[128:143], v[222:225], v[168:171], v[128:143]
	s_waitcnt lgkmcnt(4)
	v_mfma_f32_32x32x16_bf16 v[128:143], v[226:229], v[172:175], v[128:143]
	s_waitcnt lgkmcnt(3)
	v_mfma_f32_32x32x16_bf16 v[222:237], v[206:209], v[144:147], 0
	v_add_u32_e32 v206, s98, v200
	ds_read_b128 v[206:209], v206 offset:8192
	s_nop 7
	v_max3_f32 v246, v128, v129, v130
	v_max3_f32 v247, v131, v132, v133
	v_max3_f32 v246, v246, v134, v135
	v_max3_f32 v247, v247, v136, v137
	v_max3_f32 v246, v246, v138, v139
	v_max3_f32 v247, v247, v140, v141
	v_max3_f32 v246, v246, v142, v143
	s_waitcnt lgkmcnt(3)
	v_mfma_f32_32x32x16_bf16 v[222:237], v[210:213], v[148:151], v[222:237]
	v_add_u32_e32 v210, s98, v201
	ds_read_b128 v[210:213], v210 offset:8192
	v_max_f32_e32 v246, v246, v247
	v_mov_b32_e32 v247, v246
	v_add_f32_e32 v249, 0x41000000, v190
	s_nop 1
	v_permlane32_swap_b32_e32 v246, v247
	v_max_f32_e32 v246, v246, v247
	v_cmp_gt_f32_e32 vcc, v246, v249
	s_cbranch_vccz .Latt_nr0_7
	v_max_f32_e32 v246, v190, v246
	v_sub_f32_e32 v190, v190, v246
	v_exp_f32_e32 v190, v190
	s_nop 0
	v_pk_mul_f32 v[126:127], v[126:127], v[190:191] op_sel_hi:[1,0]
	v_pk_mul_f32 v[124:125], v[124:125], v[190:191] op_sel_hi:[1,0]
	v_pk_mul_f32 v[122:123], v[122:123], v[190:191] op_sel_hi:[1,0]
	v_pk_mul_f32 v[120:121], v[120:121], v[190:191] op_sel_hi:[1,0]
	v_pk_mul_f32 v[118:119], v[118:119], v[190:191] op_sel_hi:[1,0]
	v_pk_mul_f32 v[116:117], v[116:117], v[190:191] op_sel_hi:[1,0]
	v_pk_mul_f32 v[114:115], v[114:115], v[190:191] op_sel_hi:[1,0]
	v_pk_mul_f32 v[112:113], v[112:113], v[190:191] op_sel_hi:[1,0]
	v_pk_mul_f32 v[110:111], v[110:111], v[190:191] op_sel_hi:[1,0]
	v_pk_mul_f32 v[108:109], v[108:109], v[190:191] op_sel_hi:[1,0]
	v_pk_mul_f32 v[106:107], v[106:107], v[190:191] op_sel_hi:[1,0]
	v_pk_mul_f32 v[104:105], v[104:105], v[190:191] op_sel_hi:[1,0]
	v_pk_mul_f32 v[102:103], v[102:103], v[190:191] op_sel_hi:[1,0]
	v_pk_mul_f32 v[100:101], v[100:101], v[190:191] op_sel_hi:[1,0]
	v_pk_mul_f32 v[98:99], v[98:99], v[190:191] op_sel_hi:[1,0]
	v_pk_mul_f32 v[96:97], v[96:97], v[190:191] op_sel_hi:[1,0]
	v_pk_mul_f32 v[94:95], v[94:95], v[190:191] op_sel_hi:[1,0]
	v_pk_mul_f32 v[92:93], v[92:93], v[190:191] op_sel_hi:[1,0]
	v_pk_mul_f32 v[90:91], v[90:91], v[190:191] op_sel_hi:[1,0]
	v_pk_mul_f32 v[88:89], v[88:89], v[190:191] op_sel_hi:[1,0]
	v_pk_mul_f32 v[86:87], v[86:87], v[190:191] op_sel_hi:[1,0]
	v_pk_mul_f32 v[84:85], v[84:85], v[190:191] op_sel_hi:[1,0]
	v_pk_mul_f32 v[82:83], v[82:83], v[190:191] op_sel_hi:[1,0]
	v_pk_mul_f32 v[80:81], v[80:81], v[190:191] op_sel_hi:[1,0]
	v_pk_mul_f32 v[78:79], v[78:79], v[190:191] op_sel_hi:[1,0]
	v_pk_mul_f32 v[76:77], v[76:77], v[190:191] op_sel_hi:[1,0]
	v_pk_mul_f32 v[74:75], v[74:75], v[190:191] op_sel_hi:[1,0]
	v_pk_mul_f32 v[72:73], v[72:73], v[190:191] op_sel_hi:[1,0]
	v_pk_mul_f32 v[70:71], v[70:71], v[190:191] op_sel_hi:[1,0]
	v_pk_mul_f32 v[68:69], v[68:69], v[190:191] op_sel_hi:[1,0]
	v_pk_mul_f32 v[66:67], v[66:67], v[190:191] op_sel_hi:[1,0]
	v_pk_mul_f32 v[64:65], v[64:65], v[190:191] op_sel_hi:[1,0]
	v_pk_mul_f32 v[62:63], v[62:63], v[190:191] op_sel_hi:[1,0]
	v_pk_mul_f32 v[60:61], v[60:61], v[190:191] op_sel_hi:[1,0]
	v_pk_mul_f32 v[58:59], v[58:59], v[190:191] op_sel_hi:[1,0]
	v_pk_mul_f32 v[56:57], v[56:57], v[190:191] op_sel_hi:[1,0]
	v_pk_mul_f32 v[54:55], v[54:55], v[190:191] op_sel_hi:[1,0]
	v_pk_mul_f32 v[52:53], v[52:53], v[190:191] op_sel_hi:[1,0]
	v_pk_mul_f32 v[50:51], v[50:51], v[190:191] op_sel_hi:[1,0]
	v_pk_mul_f32 v[48:49], v[48:49], v[190:191] op_sel_hi:[1,0]
	v_pk_mul_f32 v[46:47], v[46:47], v[190:191] op_sel_hi:[1,0]
	v_pk_mul_f32 v[44:45], v[44:45], v[190:191] op_sel_hi:[1,0]
	v_pk_mul_f32 v[42:43], v[42:43], v[190:191] op_sel_hi:[1,0]
	v_pk_mul_f32 v[40:41], v[40:41], v[190:191] op_sel_hi:[1,0]
	v_pk_mul_f32 v[38:39], v[38:39], v[190:191] op_sel_hi:[1,0]
	v_pk_mul_f32 v[36:37], v[36:37], v[190:191] op_sel_hi:[1,0]
	v_pk_mul_f32 v[34:35], v[34:35], v[190:191] op_sel_hi:[1,0]
	v_pk_mul_f32 v[32:33], v[32:33], v[190:191] op_sel_hi:[1,0]
	v_pk_mul_f32 v[30:31], v[30:31], v[190:191] op_sel_hi:[1,0]
	v_pk_mul_f32 v[28:29], v[28:29], v[190:191] op_sel_hi:[1,0]
	v_pk_mul_f32 v[26:27], v[26:27], v[190:191] op_sel_hi:[1,0]
	v_pk_mul_f32 v[24:25], v[24:25], v[190:191] op_sel_hi:[1,0]
	v_pk_mul_f32 v[22:23], v[22:23], v[190:191] op_sel_hi:[1,0]
	v_pk_mul_f32 v[20:21], v[20:21], v[190:191] op_sel_hi:[1,0]
	v_pk_mul_f32 v[18:19], v[18:19], v[190:191] op_sel_hi:[1,0]
	v_pk_mul_f32 v[16:17], v[16:17], v[190:191] op_sel_hi:[1,0]
	v_pk_mul_f32 v[14:15], v[14:15], v[190:191] op_sel_hi:[1,0]
	v_pk_mul_f32 v[12:13], v[12:13], v[190:191] op_sel_hi:[1,0]
	v_pk_mul_f32 v[10:11], v[10:11], v[190:191] op_sel_hi:[1,0]
	v_pk_mul_f32 v[8:9], v[8:9], v[190:191] op_sel_hi:[1,0]
	v_pk_mul_f32 v[6:7], v[6:7], v[190:191] op_sel_hi:[1,0]
	v_pk_mul_f32 v[4:5], v[4:5], v[190:191] op_sel_hi:[1,0]
	v_pk_mul_f32 v[2:3], v[2:3], v[190:191] op_sel_hi:[1,0]
	v_pk_mul_f32 v[0:1], v[0:1], v[190:191] op_sel_hi:[1,0]
	v_mul_f32_e32 v195, v195, v190
	v_mov_b32_e32 v190, v246
.Latt_nr0_7:
	s_waitcnt lgkmcnt(3)
	v_mfma_f32_32x32x16_bf16 v[222:237], v[214:217], v[152:155], v[222:237]
	v_add_u32_e32 v214, s98, v202
	ds_read_b128 v[214:217], v214 offset:8192
	v_sub_f32_e32 v128, v128, v190
	v_exp_f32_e32 v128, v128
	v_sub_f32_e32 v129, v129, v190
	v_exp_f32_e32 v129, v129
	v_sub_f32_e32 v130, v130, v190
	s_waitcnt lgkmcnt(3)
	v_mfma_f32_32x32x16_bf16 v[222:237], v[238:241], v[156:159], v[222:237]
	v_add_u32_e32 v238, s98, v203
	ds_read_b128 v[238:241], v238 offset:8192
	v_add_f32_e32 v254, 0, v128
	v_exp_f32_e32 v130, v130
	v_sub_f32_e32 v131, v131, v190
	v_add_f32_e32 v254, v129, v254
	v_exp_f32_e32 v131, v131
	s_waitcnt lgkmcnt(3)
	v_mfma_f32_32x32x16_bf16 v[222:237], v[206:209], v[160:163], v[222:237]
	ds_read_b64_tr_b16 v[206:207], v205
	ds_read_b64_tr_b16 v[208:209], v205 offset:4096
	v_sub_f32_e32 v132, v132, v190
	v_add_f32_e32 v254, v130, v254
	v_exp_f32_e32 v132, v132
	v_sub_f32_e32 v133, v133, v190
	v_add_f32_e32 v254, v131, v254
	s_waitcnt lgkmcnt(4)
	v_mfma_f32_32x32x16_bf16 v[222:237], v[210:213], v[164:167], v[222:237]
	ds_read_b64_tr_b16 v[210:211], v218
	ds_read_b64_tr_b16 v[212:213], v218 offset:4096
	v_exp_f32_e32 v133, v133
	v_sub_f32_e32 v134, v134, v190
	v_add_f32_e32 v254, v132, v254
	v_exp_f32_e32 v134, v134
	s_waitcnt lgkmcnt(5)
	v_mfma_f32_32x32x16_bf16 v[222:237], v[214:217], v[168:171], v[222:237]
	ds_read_b64_tr_b16 v[214:215], v219
	ds_read_b64_tr_b16 v[216:217], v219 offset:4096
	v_sub_f32_e32 v135, v135, v190
	v_add_f32_e32 v254, v133, v254
	v_exp_f32_e32 v135, v135
	s_nop 0
	s_waitcnt lgkmcnt(6)
	v_mfma_f32_32x32x16_bf16 v[222:237], v[238:241], v[172:175], v[222:237]
	ds_read_b64_tr_b16 v[238:239], v221
	ds_read_b64_tr_b16 v[240:241], v221 offset:4096
	v_cvt_pk_bf16_f32 v242, v128, v129
	v_cvt_pk_bf16_f32 v243, v130, v131
	v_cvt_pk_bf16_f32 v244, v132, v133
	v_cvt_pk_bf16_f32 v245, v134, v135
	s_nop 1
	s_waitcnt lgkmcnt(6)
	v_mfma_f32_32x32x16_bf16 v[112:127], v[206:209], v[242:245], v[112:127]
	ds_read_b64_tr_b16 v[206:207], v205 offset:256
	ds_read_b64_tr_b16 v[208:209], v205 offset:4352
	v_sub_f32_e32 v136, v136, v190
	v_add_f32_e32 v254, v134, v254
	v_exp_f32_e32 v136, v136
	v_sub_f32_e32 v137, v137, v190
	v_add_f32_e32 v254, v135, v254
	s_waitcnt lgkmcnt(6)
	v_mfma_f32_32x32x16_bf16 v[96:111], v[210:213], v[242:245], v[96:111]
	ds_read_b64_tr_b16 v[210:211], v218 offset:256
	ds_read_b64_tr_b16 v[212:213], v218 offset:4352
	v_exp_f32_e32 v137, v137
	v_sub_f32_e32 v138, v138, v190
	v_add_f32_e32 v254, v136, v254
	v_exp_f32_e32 v138, v138
	v_sub_f32_e32 v139, v139, v190
	s_waitcnt lgkmcnt(6)
	v_mfma_f32_32x32x16_bf16 v[80:95], v[214:217], v[242:245], v[80:95]
	ds_read_b64_tr_b16 v[214:215], v219 offset:256
	ds_read_b64_tr_b16 v[216:217], v219 offset:4352
	v_add_f32_e32 v254, v137, v254
	v_exp_f32_e32 v139, v139
	v_sub_f32_e32 v140, v140, v190
	v_add_f32_e32 v254, v138, v254
	s_waitcnt lgkmcnt(6)
	v_mfma_f32_32x32x16_bf16 v[64:79], v[238:241], v[242:245], v[64:79]
	ds_read_b64_tr_b16 v[238:239], v221 offset:256
	ds_read_b64_tr_b16 v[240:241], v221 offset:4352
	v_exp_f32_e32 v140, v140
	v_sub_f32_e32 v141, v141, v190
	v_add_f32_e32 v254, v139, v254
	v_exp_f32_e32 v141, v141
	s_waitcnt lgkmcnt(6)
	v_mfma_f32_32x32x16_bf16 v[48:63], v[206:209], v[242:245], v[48:63]
	ds_read_b64_tr_b16 v[206:207], v205 offset:8192
	ds_read_b64_tr_b16 v[208:209], v205 offset:12288
	v_sub_f32_e32 v142, v142, v190
	v_add_f32_e32 v254, v140, v254
	v_exp_f32_e32 v142, v142
	v_sub_f32_e32 v143, v143, v190
	s_waitcnt lgkmcnt(6)
	v_mfma_f32_32x32x16_bf16 v[32:47], v[210:213], v[242:245], v[32:47]
	ds_read_b64_tr_b16 v[210:211], v218 offset:8192
	ds_read_b64_tr_b16 v[212:213], v218 offset:12288
	v_add_f32_e32 v254, v141, v254
	v_exp_f32_e32 v143, v143
	v_add_f32_e32 v254, v142, v254
	v_add_f32_e32 v254, v143, v254
	s_waitcnt lgkmcnt(6)
	v_mfma_f32_32x32x16_bf16 v[16:31], v[214:217], v[242:245], v[16:31]
	ds_read_b64_tr_b16 v[214:215], v219 offset:8192
	ds_read_b64_tr_b16 v[216:217], v219 offset:12288
	v_cvt_pk_bf16_f32 v250, v136, v137
	v_cvt_pk_bf16_f32 v251, v138, v139
	v_cvt_pk_bf16_f32 v252, v140, v141
	v_cvt_pk_bf16_f32 v253, v142, v143
	v_add_f32_e32 v195, v195, v254
	s_waitcnt lgkmcnt(6)
	v_mfma_f32_32x32x16_bf16 v[0:15], v[238:241], v[242:245], v[0:15]
	ds_read_b64_tr_b16 v[238:239], v221 offset:8192
	ds_read_b64_tr_b16 v[240:241], v221 offset:12288
	ds_read_b64_tr_b16 v[128:129], v205 offset:8448
	ds_read_b64_tr_b16 v[130:131], v205 offset:12544
	s_waitcnt lgkmcnt(8)
	v_mfma_f32_32x32x16_bf16 v[112:127], v[206:209], v[250:253], v[112:127]
	ds_read_b64_tr_b16 v[206:207], v218 offset:8448
	ds_read_b64_tr_b16 v[208:209], v218 offset:12544
	v_max3_f32 v246, v222, v223, v224
	v_max3_f32 v247, v225, v226, v227
	v_max3_f32 v246, v246, v228, v229
	v_max3_f32 v247, v247, v230, v231
	v_max3_f32 v246, v246, v232, v233
	v_max3_f32 v247, v247, v234, v235
	s_waitcnt lgkmcnt(8)
	v_mfma_f32_32x32x16_bf16 v[96:111], v[210:213], v[250:253], v[96:111]
	ds_read_b64_tr_b16 v[210:211], v219 offset:8448
	ds_read_b64_tr_b16 v[212:213], v219 offset:12544
	v_max3_f32 v246, v246, v236, v237
	v_max_f32_e32 v246, v246, v247
	v_mov_b32_e32 v247, v246
	v_add_f32_e32 v249, 0x41000000, v190
	s_nop 1
	s_waitcnt lgkmcnt(8)
	v_mfma_f32_32x32x16_bf16 v[80:95], v[214:217], v[250:253], v[80:95]
	ds_read_b64_tr_b16 v[214:215], v221 offset:8448
	ds_read_b64_tr_b16 v[216:217], v221 offset:12544
	v_permlane32_swap_b32_e32 v246, v247
	v_max_f32_e32 v246, v246, v247
	v_cmp_gt_f32_e32 vcc, v246, v249
	s_cbranch_vccnz .Latt_rs1_7
	s_waitcnt lgkmcnt(8)
	v_mfma_f32_32x32x16_bf16 v[64:79], v[238:241], v[250:253], v[64:79]
	ds_read_b64_tr_b16 v[238:239], v205 offset:16384
	ds_read_b64_tr_b16 v[240:241], v205 offset:20480
	v_sub_f32_e32 v222, v222, v190
	v_exp_f32_e32 v222, v222
	v_sub_f32_e32 v223, v223, v190
	v_exp_f32_e32 v223, v223
	v_sub_f32_e32 v224, v224, v190
	v_add_f32_e32 v254, 0, v222
	s_waitcnt lgkmcnt(8)
	v_mfma_f32_32x32x16_bf16 v[48:63], v[128:131], v[250:253], v[48:63]
	ds_read_b64_tr_b16 v[128:129], v218 offset:16384
	ds_read_b64_tr_b16 v[130:131], v218 offset:20480
	v_exp_f32_e32 v224, v224
	v_sub_f32_e32 v225, v225, v190
	v_add_f32_e32 v254, v223, v254
	v_exp_f32_e32 v225, v225
	v_sub_f32_e32 v226, v226, v190
	v_add_f32_e32 v254, v224, v254
	s_waitcnt lgkmcnt(8)
	v_mfma_f32_32x32x16_bf16 v[32:47], v[206:209], v[250:253], v[32:47]
	ds_read_b64_tr_b16 v[206:207], v219 offset:16384
	ds_read_b64_tr_b16 v[208:209], v219 offset:20480
	v_exp_f32_e32 v226, v226
	v_sub_f32_e32 v227, v227, v190
	v_add_f32_e32 v254, v225, v254
	v_exp_f32_e32 v227, v227
	v_sub_f32_e32 v228, v228, v190
	s_waitcnt lgkmcnt(8)
	v_mfma_f32_32x32x16_bf16 v[16:31], v[210:213], v[250:253], v[16:31]
	ds_read_b64_tr_b16 v[210:211], v221 offset:16384
	ds_read_b64_tr_b16 v[212:213], v221 offset:20480
	v_add_f32_e32 v254, v226, v254
	v_exp_f32_e32 v228, v228
	v_sub_f32_e32 v229, v229, v190
	v_add_f32_e32 v254, v227, v254
	v_exp_f32_e32 v229, v229
	s_waitcnt lgkmcnt(8)
	v_mfma_f32_32x32x16_bf16 v[0:15], v[214:217], v[250:253], v[0:15]
	ds_read_b64_tr_b16 v[214:215], v205 offset:16640
	ds_read_b64_tr_b16 v[216:217], v205 offset:20736
	s_nop 0
	v_cvt_pk_bf16_f32 v242, v222, v223
	v_cvt_pk_bf16_f32 v243, v224, v225
	v_cvt_pk_bf16_f32 v244, v226, v227
	v_cvt_pk_bf16_f32 v245, v228, v229
	s_nop 1
	s_waitcnt lgkmcnt(8)
	v_mfma_f32_32x32x16_bf16 v[112:127], v[238:241], v[242:245], v[112:127]
	ds_read_b64_tr_b16 v[238:239], v218 offset:16640
	ds_read_b64_tr_b16 v[240:241], v218 offset:20736
	v_sub_f32_e32 v230, v230, v190
	v_add_f32_e32 v254, v228, v254
	v_exp_f32_e32 v230, v230
	v_sub_f32_e32 v231, v231, v190
	v_add_f32_e32 v254, v229, v254
	s_waitcnt lgkmcnt(8)
	v_mfma_f32_32x32x16_bf16 v[96:111], v[128:131], v[242:245], v[96:111]
	ds_read_b64_tr_b16 v[128:129], v219 offset:16640
	ds_read_b64_tr_b16 v[130:131], v219 offset:20736
	v_exp_f32_e32 v231, v231
	v_sub_f32_e32 v232, v232, v190
	v_add_f32_e32 v254, v230, v254
	v_exp_f32_e32 v232, v232
	v_sub_f32_e32 v233, v233, v190
	s_cmp_lg_u64 s[8:9], 0
	s_cbranch_scc1 .Latt_nd0_7
	s_sub_i32 s100, s11, 1
	s_cmp_eq_u32 s11, 0
	s_cselect_b32 s100, 2, s100
	s_lshl_b32 s101, s100, 14
	s_add_i32 m0, s36, s101
	s_nop 0
	global_load_lds_dwordx4 v178, s[22:23]
.Latt_nd0_7:
	s_waitcnt lgkmcnt(8)
	v_mfma_f32_32x32x16_bf16 v[80:95], v[206:209], v[242:245], v[80:95]
	ds_read_b64_tr_b16 v[206:207], v221 offset:16640
	ds_read_b64_tr_b16 v[208:209], v221 offset:20736
	v_add_f32_e32 v254, v231, v254
	v_exp_f32_e32 v233, v233
	v_sub_f32_e32 v234, v234, v190
	v_add_f32_e32 v254, v232, v254
	s_waitcnt lgkmcnt(8)
	v_mfma_f32_32x32x16_bf16 v[64:79], v[210:213], v[242:245], v[64:79]
	ds_read_b64_tr_b16 v[210:211], v205 offset:24576
	ds_read_b64_tr_b16 v[212:213], v205 offset:28672
	v_exp_f32_e32 v234, v234
	v_sub_f32_e32 v235, v235, v190
	v_add_f32_e32 v254, v233, v254
	v_exp_f32_e32 v235, v235
	s_cmp_lg_u64 s[8:9], 0
	s_cbranch_scc1 .Latt_nd1_7
	s_add_i32 m0, m0, 0x400
	s_nop 0
	global_load_lds_dwordx4 v180, s[22:23]
.Latt_nd1_7:
	s_waitcnt lgkmcnt(8)
	v_mfma_f32_32x32x16_bf16 v[48:63], v[214:217], v[242:245], v[48:63]
	ds_read_b64_tr_b16 v[214:215], v218 offset:24576
	ds_read_b64_tr_b16 v[216:217], v218 offset:28672
	v_sub_f32_e32 v236, v236, v190
	v_add_f32_e32 v254, v234, v254
	v_exp_f32_e32 v236, v236
	v_sub_f32_e32 v237, v237, v190
	s_waitcnt lgkmcnt(8)
	v_mfma_f32_32x32x16_bf16 v[32:47], v[238:241], v[242:245], v[32:47]
	ds_read_b64_tr_b16 v[238:239], v219 offset:24576
	ds_read_b64_tr_b16 v[240:241], v219 offset:28672
	v_add_f32_e32 v254, v235, v254
	v_exp_f32_e32 v237, v237
	v_add_f32_e32 v254, v236, v254
	v_add_f32_e32 v254, v237, v254
	s_cmp_lg_u64 s[8:9], 0
	s_cbranch_scc1 .Latt_nd2_7
	s_lshl_b32 s101, s100, 15
	s_add_i32 m0, s37, s101
	s_add_u32 s100, s22, 0xf00
	s_addc_u32 s101, s23, 0
	global_load_lds_dwordx4 v182, s[100:101]

.Latt_rs1_7:
	s_waitcnt lgkmcnt(8)
	v_mfma_f32_32x32x16_bf16 v[64:79], v[238:241], v[250:253], v[64:79]
	ds_read_b64_tr_b16 v[238:239], v205 offset:16384
	ds_read_b64_tr_b16 v[240:241], v205 offset:20480
	s_waitcnt lgkmcnt(8)
	v_mfma_f32_32x32x16_bf16 v[48:63], v[128:131], v[250:253], v[48:63]
	ds_read_b64_tr_b16 v[128:129], v218 offset:16384
	ds_read_b64_tr_b16 v[130:131], v218 offset:20480
	s_waitcnt lgkmcnt(8)
	v_mfma_f32_32x32x16_bf16 v[32:47], v[206:209], v[250:253], v[32:47]
	ds_read_b64_tr_b16 v[206:207], v219 offset:16384
	ds_read_b64_tr_b16 v[208:209], v219 offset:20480
	s_waitcnt lgkmcnt(8)
	v_mfma_f32_32x32x16_bf16 v[16:31], v[210:213], v[250:253], v[16:31]
	ds_read_b64_tr_b16 v[210:211], v221 offset:16384
	ds_read_b64_tr_b16 v[212:213], v221 offset:20480
	s_waitcnt lgkmcnt(8)
	v_mfma_f32_32x32x16_bf16 v[0:15], v[214:217], v[250:253], v[0:15]
	ds_read_b64_tr_b16 v[214:215], v205 offset:16640
	ds_read_b64_tr_b16 v[216:217], v205 offset:20736
	s_nop 11
	v_max_f32_e32 v246, v190, v246
	v_sub_f32_e32 v190, v190, v246
	v_exp_f32_e32 v190, v190
	s_nop 0
	v_pk_mul_f32 v[126:127], v[126:127], v[190:191] op_sel_hi:[1,0]
	v_pk_mul_f32 v[124:125], v[124:125], v[190:191] op_sel_hi:[1,0]
	v_pk_mul_f32 v[122:123], v[122:123], v[190:191] op_sel_hi:[1,0]
	v_pk_mul_f32 v[120:121], v[120:121], v[190:191] op_sel_hi:[1,0]
	v_pk_mul_f32 v[118:119], v[118:119], v[190:191] op_sel_hi:[1,0]
	v_pk_mul_f32 v[116:117], v[116:117], v[190:191] op_sel_hi:[1,0]
	v_pk_mul_f32 v[114:115], v[114:115], v[190:191] op_sel_hi:[1,0]
	v_pk_mul_f32 v[112:113], v[112:113], v[190:191] op_sel_hi:[1,0]
	v_pk_mul_f32 v[110:111], v[110:111], v[190:191] op_sel_hi:[1,0]
	v_pk_mul_f32 v[108:109], v[108:109], v[190:191] op_sel_hi:[1,0]
	v_pk_mul_f32 v[106:107], v[106:107], v[190:191] op_sel_hi:[1,0]
	v_pk_mul_f32 v[104:105], v[104:105], v[190:191] op_sel_hi:[1,0]
	v_pk_mul_f32 v[102:103], v[102:103], v[190:191] op_sel_hi:[1,0]
	v_pk_mul_f32 v[100:101], v[100:101], v[190:191] op_sel_hi:[1,0]
	v_pk_mul_f32 v[98:99], v[98:99], v[190:191] op_sel_hi:[1,0]
	v_pk_mul_f32 v[96:97], v[96:97], v[190:191] op_sel_hi:[1,0]
	v_pk_mul_f32 v[94:95], v[94:95], v[190:191] op_sel_hi:[1,0]
	v_pk_mul_f32 v[92:93], v[92:93], v[190:191] op_sel_hi:[1,0]
	v_pk_mul_f32 v[90:91], v[90:91], v[190:191] op_sel_hi:[1,0]
	v_pk_mul_f32 v[88:89], v[88:89], v[190:191] op_sel_hi:[1,0]
	v_pk_mul_f32 v[86:87], v[86:87], v[190:191] op_sel_hi:[1,0]
	v_pk_mul_f32 v[84:85], v[84:85], v[190:191] op_sel_hi:[1,0]
	v_pk_mul_f32 v[82:83], v[82:83], v[190:191] op_sel_hi:[1,0]
	v_pk_mul_f32 v[80:81], v[80:81], v[190:191] op_sel_hi:[1,0]
	v_pk_mul_f32 v[78:79], v[78:79], v[190:191] op_sel_hi:[1,0]
	v_pk_mul_f32 v[76:77], v[76:77], v[190:191] op_sel_hi:[1,0]
	v_pk_mul_f32 v[74:75], v[74:75], v[190:191] op_sel_hi:[1,0]
	v_pk_mul_f32 v[72:73], v[72:73], v[190:191] op_sel_hi:[1,0]
	v_pk_mul_f32 v[70:71], v[70:71], v[190:191] op_sel_hi:[1,0]
	v_pk_mul_f32 v[68:69], v[68:69], v[190:191] op_sel_hi:[1,0]
	v_pk_mul_f32 v[66:67], v[66:67], v[190:191] op_sel_hi:[1,0]
	v_pk_mul_f32 v[64:65], v[64:65], v[190:191] op_sel_hi:[1,0]
	v_pk_mul_f32 v[62:63], v[62:63], v[190:191] op_sel_hi:[1,0]
	v_pk_mul_f32 v[60:61], v[60:61], v[190:191] op_sel_hi:[1,0]
	v_pk_mul_f32 v[58:59], v[58:59], v[190:191] op_sel_hi:[1,0]
	v_pk_mul_f32 v[56:57], v[56:57], v[190:191] op_sel_hi:[1,0]
	v_pk_mul_f32 v[54:55], v[54:55], v[190:191] op_sel_hi:[1,0]
	v_pk_mul_f32 v[52:53], v[52:53], v[190:191] op_sel_hi:[1,0]
	v_pk_mul_f32 v[50:51], v[50:51], v[190:191] op_sel_hi:[1,0]
	v_pk_mul_f32 v[48:49], v[48:49], v[190:191] op_sel_hi:[1,0]
	v_pk_mul_f32 v[46:47], v[46:47], v[190:191] op_sel_hi:[1,0]
	v_pk_mul_f32 v[44:45], v[44:45], v[190:191] op_sel_hi:[1,0]
	v_pk_mul_f32 v[42:43], v[42:43], v[190:191] op_sel_hi:[1,0]
	v_pk_mul_f32 v[40:41], v[40:41], v[190:191] op_sel_hi:[1,0]
	v_pk_mul_f32 v[38:39], v[38:39], v[190:191] op_sel_hi:[1,0]
	v_pk_mul_f32 v[36:37], v[36:37], v[190:191] op_sel_hi:[1,0]
	v_pk_mul_f32 v[34:35], v[34:35], v[190:191] op_sel_hi:[1,0]
	v_pk_mul_f32 v[32:33], v[32:33], v[190:191] op_sel_hi:[1,0]
	v_pk_mul_f32 v[30:31], v[30:31], v[190:191] op_sel_hi:[1,0]
	v_pk_mul_f32 v[28:29], v[28:29], v[190:191] op_sel_hi:[1,0]
	v_pk_mul_f32 v[26:27], v[26:27], v[190:191] op_sel_hi:[1,0]
	v_pk_mul_f32 v[24:25], v[24:25], v[190:191] op_sel_hi:[1,0]
	v_pk_mul_f32 v[22:23], v[22:23], v[190:191] op_sel_hi:[1,0]
	v_pk_mul_f32 v[20:21], v[20:21], v[190:191] op_sel_hi:[1,0]
	v_pk_mul_f32 v[18:19], v[18:19], v[190:191] op_sel_hi:[1,0]
	v_pk_mul_f32 v[16:17], v[16:17], v[190:191] op_sel_hi:[1,0]
	v_pk_mul_f32 v[14:15], v[14:15], v[190:191] op_sel_hi:[1,0]
	v_pk_mul_f32 v[12:13], v[12:13], v[190:191] op_sel_hi:[1,0]
	v_pk_mul_f32 v[10:11], v[10:11], v[190:191] op_sel_hi:[1,0]
	v_pk_mul_f32 v[8:9], v[8:9], v[190:191] op_sel_hi:[1,0]
	v_pk_mul_f32 v[6:7], v[6:7], v[190:191] op_sel_hi:[1,0]
	v_pk_mul_f32 v[4:5], v[4:5], v[190:191] op_sel_hi:[1,0]
	v_pk_mul_f32 v[2:3], v[2:3], v[190:191] op_sel_hi:[1,0]
	v_pk_mul_f32 v[0:1], v[0:1], v[190:191] op_sel_hi:[1,0]
	v_mul_f32_e32 v195, v195, v190
	v_mov_b32_e32 v190, v246
	v_sub_f32_e32 v222, v222, v190
	v_exp_f32_e32 v222, v222
	v_sub_f32_e32 v223, v223, v190
	v_exp_f32_e32 v223, v223
	v_sub_f32_e32 v224, v224, v190
	v_add_f32_e32 v254, 0, v222
	v_exp_f32_e32 v224, v224
	v_sub_f32_e32 v225, v225, v190
	v_add_f32_e32 v254, v223, v254
	v_exp_f32_e32 v225, v225
	v_sub_f32_e32 v226, v226, v190
	v_add_f32_e32 v254, v224, v254
	v_exp_f32_e32 v226, v226
	v_sub_f32_e32 v227, v227, v190
	v_add_f32_e32 v254, v225, v254
	v_exp_f32_e32 v227, v227
	v_sub_f32_e32 v228, v228, v190
	v_add_f32_e32 v254, v226, v254
	v_exp_f32_e32 v228, v228
	v_sub_f32_e32 v229, v229, v190
	v_add_f32_e32 v254, v227, v254
	v_exp_f32_e32 v229, v229
	v_sub_f32_e32 v230, v230, v190
	v_add_f32_e32 v254, v228, v254
	v_exp_f32_e32 v230, v230
	v_sub_f32_e32 v231, v231, v190
	v_add_f32_e32 v254, v229, v254
	v_exp_f32_e32 v231, v231
	v_sub_f32_e32 v232, v232, v190
	v_add_f32_e32 v254, v230, v254
	v_exp_f32_e32 v232, v232
	v_sub_f32_e32 v233, v233, v190
	v_add_f32_e32 v254, v231, v254
	v_exp_f32_e32 v233, v233
	v_sub_f32_e32 v234, v234, v190
	v_add_f32_e32 v254, v232, v254
	v_exp_f32_e32 v234, v234
	v_sub_f32_e32 v235, v235, v190
	v_add_f32_e32 v254, v233, v254
	v_exp_f32_e32 v235, v235
	v_sub_f32_e32 v236, v236, v190
	v_add_f32_e32 v254, v234, v254
	v_exp_f32_e32 v236, v236
	v_sub_f32_e32 v237, v237, v190
	v_add_f32_e32 v254, v235, v254
	v_exp_f32_e32 v237, v237
	v_add_f32_e32 v254, v236, v254
	v_add_f32_e32 v254, v237, v254
	v_cvt_pk_bf16_f32 v242, v222, v223
	v_cvt_pk_bf16_f32 v243, v224, v225
	v_cvt_pk_bf16_f32 v244, v226, v227
	v_cvt_pk_bf16_f32 v245, v228, v229
	v_cvt_pk_bf16_f32 v250, v230, v231
	v_cvt_pk_bf16_f32 v251, v232, v233
	v_cvt_pk_bf16_f32 v252, v234, v235
	v_cvt_pk_bf16_f32 v253, v236, v237
	v_add_f32_e32 v195, v195, v254
	s_nop 1
	s_waitcnt lgkmcnt(8)
	v_mfma_f32_32x32x16_bf16 v[112:127], v[238:241], v[242:245], v[112:127]
	ds_read_b64_tr_b16 v[238:239], v218 offset:16640
	ds_read_b64_tr_b16 v[240:241], v218 offset:20736
	s_waitcnt lgkmcnt(8)
	v_mfma_f32_32x32x16_bf16 v[96:111], v[128:131], v[242:245], v[96:111]
	ds_read_b64_tr_b16 v[222:223], v219 offset:16640
	ds_read_b64_tr_b16 v[224:225], v219 offset:20736
	s_cmp_lg_u64 s[8:9], 0
	s_cbranch_scc1 .Latt_ndr0_7
	s_sub_i32 s100, s11, 1
	s_cmp_eq_u32 s11, 0
	s_cselect_b32 s100, 2, s100
	s_lshl_b32 s101, s100, 14
	s_add_i32 m0, s36, s101
	s_nop 0
	global_load_lds_dwordx4 v178, s[22:23]
.Latt_ndr0_7:
	s_waitcnt lgkmcnt(8)
	v_mfma_f32_32x32x16_bf16 v[80:95], v[206:209], v[242:245], v[80:95]
	ds_read_b64_tr_b16 v[206:207], v221 offset:16640
	ds_read_b64_tr_b16 v[208:209], v221 offset:20736
	s_waitcnt lgkmcnt(8)
	v_mfma_f32_32x32x16_bf16 v[64:79], v[210:213], v[242:245], v[64:79]
	ds_read_b64_tr_b16 v[210:211], v205 offset:24576
	ds_read_b64_tr_b16 v[212:213], v205 offset:28672
	s_cmp_lg_u64 s[8:9], 0
	s_cbranch_scc1 .Latt_ndr1_7
	s_add_i32 m0, m0, 0x400
	s_nop 0
	global_load_lds_dwordx4 v180, s[22:23]
